# accumulator zeroing of every GEMM unit moved from before the K-loop into the first iteration's LDS-read segment
# speedup vs baseline: 1.0213x; 1.0213x over previous
; template <class Epi, class Sched, bool ALIGN_EPI = false, bool SP2 = false>
; __device__ __forceinline__ void gemm_phase(PG8_LAS unsigned char* lds, const Gemm g, const Sched& S, const Epi& E) {
;     ...
;         const bool has_next = S.next(ui + 1, nxt);
;         const char* nA = has_next ? (const char*)g.A + (size_t)nxt.pm * tstep : cA; const char* nB = has_next ? (const char*)g.Bt + (size_t)nxt.pn * tstep : cB;
;         for (int t = 0; t < nt; t += 2) {
;             const bool last = (t == nt - 2);
;             const char* a1 = cA + (size_t)(t + 1) * kstep;
;             const char* a2 = last ? nA : cA + (size_t)(t + 2) * kstep; const char* b2 = last ? nB : cB + (size_t)(t + 2) * kstep;
;             const char* a3 = a2 + kstep; const char* b3 = b2 + kstep;
.LBB0_184:
	s_ashr_i32 s23, s22, 31
	s_lshl_b64 s[24:25], s[22:23], 19
	s_add_u32 s24, s2, s24
	s_addc_u32 s25, s36, s25
	s_and_b64 s[26:27], s[8:9], exec
	s_cselect_b32 s23, s25, s29
	s_cselect_b32 s33, s24, s28
	s_ashr_i32 s21, s20, 31
	s_lshl_b64 s[26:27], s[20:21], 19
	s_add_u32 s26, s37, s26
	s_addc_u32 s27, s38, s27
	s_and_b64 s[34:35], s[8:9], exec
	s_cselect_b32 s21, s27, s31
	s_cselect_b32 s51, s26, s30
	s_add_u32 s28, s28, 0x40080
	s_addc_u32 s29, s29, 0
	s_add_u32 s52, s30, 0x100
	s_addc_u32 s53, s31, 0
	s_mov_b32 s54, -2

; #define PG8_STAGE(bufoff, gbase, voff) do { _Pragma("unroll") for (int _i = 0; _i < 2; ++_i) \
;         __builtin_amdgcn_global_load_lds((const unsigned*)((const char*)(gbase) + (voff)[_i]), (PG8_LAS unsigned*)(lds + (bufoff) + ldsw + _i * 8192), 16, 0, 0); } while (0)
; #define PG8_LDA(dst, b, h) do { _Pragma("unroll") for (int m = 0; m < 4; ++m) _Pragma("unroll") for (int k = 0; k < 2; ++k) dst[m][k] = *(const PG8_LAS bf16x8*)(lds + PG8_SA(b, h) + aoff + m * 2048 + k * 1024); } while (0)
; #define PG8_LDB(dst, b, h) do { _Pragma("unroll") for (int n = 0; n < 2; ++n) _Pragma("unroll") for (int k = 0; k < 2; ++k) dst[n][k] = *(const PG8_LAS bf16x8*)(lds + PG8_SB(b, h) + boff + n * 2048 + k * 1024); } while (0)
; #define PG8_MMA(ai, bj, At, Bt) do { __builtin_amdgcn_s_setprio(1); _Pragma("unroll") for (int m = 0; m < 4; ++m) _Pragma("unroll") for (int n = 0; n < 2; ++n) _Pragma("unroll") for (int k = 0; k < 2; ++k) \
;         acc[ai][bj][m][n] = __builtin_amdgcn_mfma_f32_16x16x32_bf16(Bt[n][k], At[m][k], acc[ai][bj][m][n], 0, 0, 0); __builtin_amdgcn_s_setprio(0); } while (0)
; #define PG8_WAIT_V(n) asm volatile("s_waitcnt vmcnt(" #n ")" ::: "memory")
; #define PG8_WAIT_L(n) asm volatile("s_waitcnt lgkmcnt(" #n ")" ::: "memory")
; #define PG8_BAR __builtin_amdgcn_s_barrier()
; #define PG8_SCHED __builtin_amdgcn_sched_barrier(0)
; template <class Epi, class Sched, bool ALIGN_EPI = false, bool SP2 = false>
; __device__ __forceinline__ void gemm_phase(PG8_LAS unsigned char* lds, const Gemm g, const Sched& S, const Epi& E) {
;     ...
; #pragma unroll
;     for (int a = 0; a < 2; ++a)
; #pragma unroll
;         for (int b = 0; b < 2; ++b)
; #pragma unroll
;             for (int m = 0; m < 4; ++m)
; #pragma unroll
;                 for (int n = 0; n < 2; ++n) acc[a][b][m][n] = (f32x4){0.f, 0.f, 0.f, 0.f};
;     ...
;             PG8_LDB(B0, 0, 0); PG8_LDB(B1, 0, 1); PG8_SCHED; PG8_LDA(At, 0, 0); PG8_STAGE(PG8_SA(1, 1), a1 + hstep, voffA);
;             PG8_WAIT_V(8); PG8_WAIT_L(0); PG8_BAR; PG8_MMA(0, 0, At, B0); PG8_MMA(0, 1, At, B1); PG8_BAR; PG8_SCHED;
.Lodin_nopf:
	ds_read_b128 v[130:133], v146
	ds_read_b128 v[154:157], v146 offset:1024
	ds_read_b128 v[158:161], v146 offset:2048
	ds_read_b128 v[162:165], v146 offset:3072
	v_add_u32_e32 v146, s58, v151
	ds_read_b128 v[166:169], v146
	ds_read_b128 v[170:173], v146 offset:1024
	ds_read_b128 v[180:183], v146 offset:2048
	ds_read_b128 v[184:187], v146 offset:3072
	v_lshl_add_u64 v[146:147], s[28:29], 0, v[142:143]
	s_add_i32 m0, s40, 0xc000
	ds_read_b128 v[188:191], v153
	ds_read_b128 v[192:195], v153 offset:1024
	ds_read_b128 v[196:199], v153 offset:2048
	ds_read_b128 v[200:203], v153 offset:3072
	ds_read_b128 v[204:207], v153 offset:4096
	ds_read_b128 v[208:211], v153 offset:5120
	ds_read_b128 v[212:215], v153 offset:6144
	ds_read_b128 v[216:219], v153 offset:7168
	global_load_lds_dwordx4 v[146:147], off
	v_lshl_add_u64 v[146:147], s[28:29], 0, v[144:145]
	s_add_i32 m0, s40, 0xe000
	s_nop 0
	global_load_lds_dwordx4 v[146:147], off
	s_cmp_lg_u32 s54, -2
	s_cbranch_scc1 .Lodin_noz
	v_mov_b32_e32 v34, 0
	v_mov_b32_e32 v35, v34
	v_mov_b32_e32 v36, v34
	v_mov_b32_e32 v37, v34
	v_mov_b32_e32 v38, v34
	v_mov_b32_e32 v39, v34
	v_mov_b32_e32 v40, v34
	v_mov_b32_e32 v41, v34
	v_mov_b32_e32 v74, v34
	v_mov_b32_e32 v75, v34
	v_mov_b32_e32 v76, v34
	v_mov_b32_e32 v77, v34
	v_mov_b32_e32 v78, v34
	v_mov_b32_e32 v79, v34
	v_mov_b32_e32 v80, v34
	v_mov_b32_e32 v81, v34
	v_mov_b32_e32 v82, v34
	v_mov_b32_e32 v83, v34
	v_mov_b32_e32 v84, v34
	v_mov_b32_e32 v85, v34
	v_mov_b32_e32 v86, v34
	v_mov_b32_e32 v87, v34
	v_mov_b32_e32 v88, v34
	v_mov_b32_e32 v89, v34
	v_mov_b32_e32 v90, v34
	v_mov_b32_e32 v91, v34
	v_mov_b32_e32 v92, v34
	v_mov_b32_e32 v93, v34
	v_mov_b32_e32 v94, v34
	v_mov_b32_e32 v95, v34
	v_mov_b32_e32 v96, v34
	v_mov_b32_e32 v97, v34
	v_mov_b32_e32 v2, v34
	v_mov_b32_e32 v3, v34
	v_mov_b32_e32 v4, v34
	v_mov_b32_e32 v5, v34
	v_mov_b32_e32 v6, v34
	v_mov_b32_e32 v7, v34
	v_mov_b32_e32 v8, v34
	v_mov_b32_e32 v9, v34
	v_mov_b32_e32 v10, v34
	v_mov_b32_e32 v11, v34
	v_mov_b32_e32 v12, v34
	v_mov_b32_e32 v13, v34
	v_mov_b32_e32 v14, v34
	v_mov_b32_e32 v15, v34
	v_mov_b32_e32 v16, v34
	v_mov_b32_e32 v17, v34
	v_mov_b32_e32 v18, v34
	v_mov_b32_e32 v19, v34
	v_mov_b32_e32 v20, v34
	v_mov_b32_e32 v21, v34
	v_mov_b32_e32 v22, v34
	v_mov_b32_e32 v23, v34
	v_mov_b32_e32 v24, v34
	v_mov_b32_e32 v25, v34
	v_mov_b32_e32 v26, v34
	v_mov_b32_e32 v27, v34
	v_mov_b32_e32 v28, v34
	v_mov_b32_e32 v29, v34
	v_mov_b32_e32 v30, v34
	v_mov_b32_e32 v31, v34
	v_mov_b32_e32 v32, v34
	v_mov_b32_e32 v33, v34
	v_mov_b32_e32 v98, v34
	v_mov_b32_e32 v99, v34
	v_mov_b32_e32 v100, v34
	v_mov_b32_e32 v101, v34
	v_mov_b32_e32 v102, v34
	v_mov_b32_e32 v103, v34
	v_mov_b32_e32 v104, v34
	v_mov_b32_e32 v105, v34
	v_mov_b32_e32 v106, v34
	v_mov_b32_e32 v107, v34
	v_mov_b32_e32 v108, v34
	v_mov_b32_e32 v109, v34
	v_mov_b32_e32 v110, v34
	v_mov_b32_e32 v111, v34
	v_mov_b32_e32 v112, v34
	v_mov_b32_e32 v113, v34
	v_mov_b32_e32 v114, v34
	v_mov_b32_e32 v115, v34
	v_mov_b32_e32 v116, v34
	v_mov_b32_e32 v117, v34
	v_mov_b32_e32 v118, v34
	v_mov_b32_e32 v119, v34
	v_mov_b32_e32 v120, v34
	v_mov_b32_e32 v121, v34
	v_mov_b32_e32 v122, v34
	v_mov_b32_e32 v123, v34
	v_mov_b32_e32 v124, v34
	v_mov_b32_e32 v125, v34
	v_mov_b32_e32 v126, v34
	v_mov_b32_e32 v127, v34
	v_mov_b32_e32 v128, v34
	v_mov_b32_e32 v129, v34
	v_mov_b32_e32 v42, v34
	v_mov_b32_e32 v43, v34
	v_mov_b32_e32 v44, v34
	v_mov_b32_e32 v45, v34
	v_mov_b32_e32 v46, v34
	v_mov_b32_e32 v47, v34
	v_mov_b32_e32 v48, v34
	v_mov_b32_e32 v49, v34
	v_mov_b32_e32 v50, v34
	v_mov_b32_e32 v51, v34
	v_mov_b32_e32 v52, v34
	v_mov_b32_e32 v53, v34
	v_mov_b32_e32 v54, v34
	v_mov_b32_e32 v55, v34
	v_mov_b32_e32 v56, v34
	v_mov_b32_e32 v57, v34
	v_mov_b32_e32 v58, v34
	v_mov_b32_e32 v59, v34
	v_mov_b32_e32 v60, v34
	v_mov_b32_e32 v61, v34
	v_mov_b32_e32 v62, v34
	v_mov_b32_e32 v63, v34
	v_mov_b32_e32 v64, v34
	v_mov_b32_e32 v65, v34
	v_mov_b32_e32 v66, v34
	v_mov_b32_e32 v67, v34
	v_mov_b32_e32 v68, v34
	v_mov_b32_e32 v69, v34
	v_mov_b32_e32 v70, v34
	v_mov_b32_e32 v71, v34
	v_mov_b32_e32 v72, v34
	v_mov_b32_e32 v73, v34
.Lodin_noz:
	s_waitcnt vmcnt(8)
	s_waitcnt lgkmcnt(0)
	s_barrier
	s_setprio 1
	s_waitcnt lgkmcnt(0)
	v_mfma_f32_16x16x32_bf16 v[70:73], v[130:133], v[188:191], v[70:73]
	v_mfma_f32_16x16x32_bf16 v[66:69], v[158:161], v[188:191], v[66:69]
	v_mfma_f32_16x16x32_bf16 v[62:65], v[130:133], v[196:199], v[62:65]
	v_mfma_f32_16x16x32_bf16 v[58:61], v[158:161], v[196:199], v[58:61]
	v_mfma_f32_16x16x32_bf16 v[54:57], v[130:133], v[204:207], v[54:57]
	v_mfma_f32_16x16x32_bf16 v[50:53], v[158:161], v[204:207], v[50:53]
	v_mfma_f32_16x16x32_bf16 v[46:49], v[130:133], v[212:215], v[46:49]
	v_mfma_f32_16x16x32_bf16 v[42:45], v[158:161], v[212:215], v[42:45]
	v_mfma_f32_16x16x32_bf16 v[70:73], v[154:157], v[192:195], v[70:73]
	v_mfma_f32_16x16x32_bf16 v[66:69], v[162:165], v[192:195], v[66:69]
	v_mfma_f32_16x16x32_bf16 v[62:65], v[154:157], v[200:203], v[62:65]
	v_mfma_f32_16x16x32_bf16 v[58:61], v[162:165], v[200:203], v[58:61]
	v_mfma_f32_16x16x32_bf16 v[54:57], v[154:157], v[208:211], v[54:57]
	v_mfma_f32_16x16x32_bf16 v[50:53], v[162:165], v[208:211], v[50:53]
	v_mfma_f32_16x16x32_bf16 v[46:49], v[154:157], v[216:219], v[46:49]
	v_mfma_f32_16x16x32_bf16 v[42:45], v[162:165], v[216:219], v[42:45]
	s_setprio 0
	s_setprio 1
	v_mfma_f32_16x16x32_bf16 v[126:129], v[166:169], v[188:191], v[126:129]
	v_mfma_f32_16x16x32_bf16 v[122:125], v[180:183], v[188:191], v[122:125]
	v_mfma_f32_16x16x32_bf16 v[118:121], v[166:169], v[196:199], v[118:121]
	v_mfma_f32_16x16x32_bf16 v[114:117], v[180:183], v[196:199], v[114:117]
	v_mfma_f32_16x16x32_bf16 v[110:113], v[166:169], v[204:207], v[110:113]
	v_mfma_f32_16x16x32_bf16 v[106:109], v[180:183], v[204:207], v[106:109]
	v_mfma_f32_16x16x32_bf16 v[102:105], v[166:169], v[212:215], v[102:105]
	v_mfma_f32_16x16x32_bf16 v[98:101], v[180:183], v[212:215], v[98:101]
	v_mfma_f32_16x16x32_bf16 v[126:129], v[170:173], v[192:195], v[126:129]
	v_mfma_f32_16x16x32_bf16 v[122:125], v[184:187], v[192:195], v[122:125]
	v_mfma_f32_16x16x32_bf16 v[118:121], v[170:173], v[200:203], v[118:121]
	v_mfma_f32_16x16x32_bf16 v[114:117], v[184:187], v[200:203], v[114:117]
	v_mfma_f32_16x16x32_bf16 v[110:113], v[170:173], v[208:211], v[110:113]
	v_mfma_f32_16x16x32_bf16 v[106:109], v[184:187], v[208:211], v[106:109]
	v_mfma_f32_16x16x32_bf16 v[102:105], v[170:173], v[216:219], v[102:105]
	v_mfma_f32_16x16x32_bf16 v[98:101], v[184:187], v[216:219], v[98:101]
	s_setprio 0
	s_barrier
; #define PG8_STAGE(bufoff, gbase, voff) do { _Pragma("unroll") for (int _i = 0; _i < 2; ++_i) \
;         __builtin_amdgcn_global_load_lds((const unsigned*)((const char*)(gbase) + (voff)[_i]), (PG8_LAS unsigned*)(lds + (bufoff) + ldsw + _i * 8192), 16, 0, 0); } while (0)
; #define PG8_LDA(dst, b, h) do { _Pragma("unroll") for (int m = 0; m < 4; ++m) _Pragma("unroll") for (int k = 0; k < 2; ++k) dst[m][k] = *(const PG8_LAS bf16x8*)(lds + PG8_SA(b, h) + aoff + m * 2048 + k * 1024); } while (0)
; #define PG8_LDB(dst, b, h) do { _Pragma("unroll") for (int n = 0; n < 2; ++n) _Pragma("unroll") for (int k = 0; k < 2; ++k) dst[n][k] = *(const PG8_LAS bf16x8*)(lds + PG8_SB(b, h) + boff + n * 2048 + k * 1024); } while (0)
; #define PG8_MMA(ai, bj, At, Bt) do { __builtin_amdgcn_s_setprio(1); _Pragma("unroll") for (int m = 0; m < 4; ++m) _Pragma("unroll") for (int n = 0; n < 2; ++n) _Pragma("unroll") for (int k = 0; k < 2; ++k) \
;         acc[ai][bj][m][n] = __builtin_amdgcn_mfma_f32_16x16x32_bf16(Bt[n][k], At[m][k], acc[ai][bj][m][n], 0, 0, 0); __builtin_amdgcn_s_setprio(0); } while (0)
; #define PG8_WAIT_V(n) asm volatile("s_waitcnt vmcnt(" #n ")" ::: "memory")
; #define PG8_WAIT_L(n) asm volatile("s_waitcnt lgkmcnt(" #n ")" ::: "memory")
; #define PG8_BAR __builtin_amdgcn_s_barrier()
; #define PG8_SCHED __builtin_amdgcn_sched_barrier(0)
; template <class Epi, class Sched, bool ALIGN_EPI = false, bool SP2 = false>
; __device__ __forceinline__ void gemm_phase(PG8_LAS unsigned char* lds, const Gemm g, const Sched& S, const Epi& E) {
;     ...
;             PG8_LDA(At, 0, 1); PG8_STAGE(PG8_SB(0, 0), b2, voffB); PG8_STAGE(PG8_SB(0, 1), b2 + hstep, voffB); PG8_STAGE(PG8_SA(0, 0), a2, voffA);
;             PG8_WAIT_V(8); PG8_WAIT_L(0); PG8_BAR; PG8_MMA(1, 0, At, B0); PG8_MMA(1, 1, At, B1); PG8_BAR; PG8_SCHED;
;             PG8_LDB(B0, 1, 0); PG8_LDB(B1, 1, 1); PG8_SCHED; PG8_LDA(At, 1, 0); PG8_STAGE(PG8_SA(0, 1), a2 + hstep, voffA);
	s_add_i32 s55, s55, s39
	v_lshl_add_u64 v[146:147], s[30:31], 0, v[138:139]
	s_mov_b32 m0, s55
	ds_read_b128 v[188:191], v153 offset:16384
	ds_read_b128 v[192:195], v153 offset:17408
	ds_read_b128 v[196:199], v153 offset:18432
	ds_read_b128 v[200:203], v153 offset:19456
	ds_read_b128 v[204:207], v153 offset:20480
	ds_read_b128 v[208:211], v153 offset:21504
	ds_read_b128 v[212:215], v153 offset:22528
	ds_read_b128 v[216:219], v153 offset:23552
	global_load_lds_dwordx4 v[146:147], off
	s_add_i32 m0, s55, 0x2000
	s_add_u32 s56, s30, 0x40000
	v_lshl_add_u64 v[220:221], s[30:31], 0, v[134:135]
	s_addc_u32 s57, s31, 0
	s_add_i32 s55, s58, s39
	global_load_lds_dwordx4 v[220:221], off
	v_lshl_add_u64 v[222:223], s[56:57], 0, v[138:139]
	s_mov_b32 m0, s55
	v_lshl_add_u64 v[228:229], s[34:35], 0, v[136:137]
	global_load_lds_dwordx4 v[222:223], off
	v_lshl_add_u64 v[222:223], s[56:57], 0, v[134:135]
	s_add_i32 m0, s55, 0x2000
	s_nop 0
	global_load_lds_dwordx4 v[222:223], off
	v_lshl_add_u64 v[222:223], s[34:35], 0, v[140:141]
	s_mov_b32 m0, s40
	s_nop 0
	global_load_lds_dwordx4 v[222:223], off
	s_mov_b32 m0, s41
	s_nop 0
	global_load_lds_dwordx4 v[228:229], off
	s_waitcnt vmcnt(8)
	s_waitcnt lgkmcnt(0)
	s_barrier
	s_setprio 1
	s_waitcnt lgkmcnt(0)
	v_mfma_f32_16x16x32_bf16 v[30:33], v[130:133], v[188:191], v[30:33]
	v_mfma_f32_16x16x32_bf16 v[26:29], v[158:161], v[188:191], v[26:29]
	v_mfma_f32_16x16x32_bf16 v[22:25], v[130:133], v[196:199], v[22:25]
	v_mfma_f32_16x16x32_bf16 v[18:21], v[158:161], v[196:199], v[18:21]
	v_mfma_f32_16x16x32_bf16 v[14:17], v[130:133], v[204:207], v[14:17]
	v_mfma_f32_16x16x32_bf16 v[10:13], v[158:161], v[204:207], v[10:13]
	v_mfma_f32_16x16x32_bf16 v[6:9], v[130:133], v[212:215], v[6:9]
	v_mfma_f32_16x16x32_bf16 v[2:5], v[158:161], v[212:215], v[2:5]
	v_mfma_f32_16x16x32_bf16 v[30:33], v[154:157], v[192:195], v[30:33]
	v_mfma_f32_16x16x32_bf16 v[26:29], v[162:165], v[192:195], v[26:29]
	v_mfma_f32_16x16x32_bf16 v[22:25], v[154:157], v[200:203], v[22:25]
	v_mfma_f32_16x16x32_bf16 v[18:21], v[162:165], v[200:203], v[18:21]
	v_mfma_f32_16x16x32_bf16 v[14:17], v[154:157], v[208:211], v[14:17]
	v_mfma_f32_16x16x32_bf16 v[10:13], v[162:165], v[208:211], v[10:13]
	v_mfma_f32_16x16x32_bf16 v[6:9], v[154:157], v[216:219], v[6:9]
	v_mfma_f32_16x16x32_bf16 v[2:5], v[162:165], v[216:219], v[2:5]
	s_setprio 0
	s_setprio 1
	v_mfma_f32_16x16x32_bf16 v[94:97], v[166:169], v[188:191], v[94:97]
	v_mfma_f32_16x16x32_bf16 v[90:93], v[180:183], v[188:191], v[90:93]
	v_mfma_f32_16x16x32_bf16 v[86:89], v[166:169], v[196:199], v[86:89]
	v_mfma_f32_16x16x32_bf16 v[82:85], v[180:183], v[196:199], v[82:85]
	v_mfma_f32_16x16x32_bf16 v[78:81], v[166:169], v[204:207], v[78:81]
	v_mfma_f32_16x16x32_bf16 v[74:77], v[180:183], v[204:207], v[74:77]
	v_mfma_f32_16x16x32_bf16 v[38:41], v[166:169], v[212:215], v[38:41]
	v_mfma_f32_16x16x32_bf16 v[34:37], v[180:183], v[212:215], v[34:37]
	v_mfma_f32_16x16x32_bf16 v[94:97], v[170:173], v[192:195], v[94:97]
	v_mfma_f32_16x16x32_bf16 v[90:93], v[184:187], v[192:195], v[90:93]
	v_mfma_f32_16x16x32_bf16 v[86:89], v[170:173], v[200:203], v[86:89]
	v_mfma_f32_16x16x32_bf16 v[82:85], v[184:187], v[200:203], v[82:85]
	v_mfma_f32_16x16x32_bf16 v[78:81], v[170:173], v[208:211], v[78:81]
	v_mfma_f32_16x16x32_bf16 v[74:77], v[184:187], v[208:211], v[74:77]
	v_mfma_f32_16x16x32_bf16 v[38:41], v[170:173], v[216:219], v[38:41]
	v_mfma_f32_16x16x32_bf16 v[34:37], v[184:187], v[216:219], v[34:37]
	s_setprio 0
	s_barrier
	s_add_i32 s55, 0, 0x18000
	v_add_u32_e32 v148, s55, v151
	s_add_i32 s56, 0, 0x1c000
	ds_read_b128 v[130:133], v148
	ds_read_b128 v[154:157], v148 offset:1024
	ds_read_b128 v[158:161], v148 offset:2048
	ds_read_b128 v[162:165], v148 offset:3072
	v_add_u32_e32 v148, s56, v151
	ds_read_b128 v[166:169], v148
	ds_read_b128 v[170:173], v148 offset:1024
	ds_read_b128 v[180:183], v148 offset:2048
	ds_read_b128 v[184:187], v148 offset:3072
	s_add_u32 s34, s34, 0x40000
	s_addc_u32 s35, s35, 0
	s_mov_b32 m0, s42
	v_lshl_add_u64 v[230:231], s[34:35], 0, v[140:141]
	ds_read_b128 v[188:191], v153 offset:32768
	ds_read_b128 v[192:195], v153 offset:33792
	ds_read_b128 v[196:199], v153 offset:34816
	ds_read_b128 v[200:203], v153 offset:35840
	ds_read_b128 v[204:207], v153 offset:36864
	ds_read_b128 v[208:211], v153 offset:37888
	ds_read_b128 v[212:215], v153 offset:38912
	ds_read_b128 v[216:219], v153 offset:39936
	global_load_lds_dwordx4 v[230:231], off
	v_lshl_add_u64 v[230:231], s[34:35], 0, v[136:137]
	s_mov_b32 m0, s43
	s_nop 0
	global_load_lds_dwordx4 v[230:231], off
	s_waitcnt vmcnt(8)
	s_waitcnt lgkmcnt(0)
	s_barrier
; #define PG8_STAGE(bufoff, gbase, voff) do { _Pragma("unroll") for (int _i = 0; _i < 2; ++_i) \
;         __builtin_amdgcn_global_load_lds((const unsigned*)((const char*)(gbase) + (voff)[_i]), (PG8_LAS unsigned*)(lds + (bufoff) + ldsw + _i * 8192), 16, 0, 0); } while (0)
; #define PG8_LDA(dst, b, h) do { _Pragma("unroll") for (int m = 0; m < 4; ++m) _Pragma("unroll") for (int k = 0; k < 2; ++k) dst[m][k] = *(const PG8_LAS bf16x8*)(lds + PG8_SA(b, h) + aoff + m * 2048 + k * 1024); } while (0)
; #define PG8_MMA(ai, bj, At, Bt) do { __builtin_amdgcn_s_setprio(1); _Pragma("unroll") for (int m = 0; m < 4; ++m) _Pragma("unroll") for (int n = 0; n < 2; ++n) _Pragma("unroll") for (int k = 0; k < 2; ++k) \
;         acc[ai][bj][m][n] = __builtin_amdgcn_mfma_f32_16x16x32_bf16(Bt[n][k], At[m][k], acc[ai][bj][m][n], 0, 0, 0); __builtin_amdgcn_s_setprio(0); } while (0)
; #define PG8_WAIT_V(n) asm volatile("s_waitcnt vmcnt(" #n ")" ::: "memory")
; #define PG8_WAIT_L(n) asm volatile("s_waitcnt lgkmcnt(" #n ")" ::: "memory")
; #define PG8_BAR __builtin_amdgcn_s_barrier()
; #define PG8_SCHED __builtin_amdgcn_sched_barrier(0)
; template <class Epi, class Sched, bool ALIGN_EPI = false, bool SP2 = false>
; __device__ __forceinline__ void gemm_phase(PG8_LAS unsigned char* lds, const Gemm g, const Sched& S, const Epi& E) {
;     ...
;             PG8_WAIT_V(8); PG8_WAIT_L(0); PG8_BAR; PG8_MMA(0, 0, At, B0); PG8_MMA(0, 1, At, B1); PG8_BAR; PG8_SCHED;
;             PG8_LDA(At, 1, 1); PG8_STAGE(PG8_SB(1, 0), b3, voffB); PG8_STAGE(PG8_SB(1, 1), b3 + hstep, voffB); PG8_STAGE(PG8_SA(1, 0), a3, voffA);
;             PG8_WAIT_V(8); PG8_WAIT_L(0); PG8_BAR; PG8_MMA(1, 0, At, B0); PG8_MMA(1, 1, At, B1); PG8_BAR; PG8_SCHED;
	s_setprio 1
	s_waitcnt lgkmcnt(0)
	v_mfma_f32_16x16x32_bf16 v[70:73], v[130:133], v[188:191], v[70:73]
	v_mfma_f32_16x16x32_bf16 v[66:69], v[158:161], v[188:191], v[66:69]
	v_mfma_f32_16x16x32_bf16 v[62:65], v[130:133], v[196:199], v[62:65]
	v_mfma_f32_16x16x32_bf16 v[58:61], v[158:161], v[196:199], v[58:61]
	v_mfma_f32_16x16x32_bf16 v[54:57], v[130:133], v[204:207], v[54:57]
	v_mfma_f32_16x16x32_bf16 v[50:53], v[158:161], v[204:207], v[50:53]
	v_mfma_f32_16x16x32_bf16 v[46:49], v[130:133], v[212:215], v[46:49]
	v_mfma_f32_16x16x32_bf16 v[42:45], v[158:161], v[212:215], v[42:45]
	v_mfma_f32_16x16x32_bf16 v[70:73], v[154:157], v[192:195], v[70:73]
	v_mfma_f32_16x16x32_bf16 v[66:69], v[162:165], v[192:195], v[66:69]
	v_mfma_f32_16x16x32_bf16 v[62:65], v[154:157], v[200:203], v[62:65]
	v_mfma_f32_16x16x32_bf16 v[58:61], v[162:165], v[200:203], v[58:61]
	v_mfma_f32_16x16x32_bf16 v[54:57], v[154:157], v[208:211], v[54:57]
	v_mfma_f32_16x16x32_bf16 v[50:53], v[162:165], v[208:211], v[50:53]
	v_mfma_f32_16x16x32_bf16 v[46:49], v[154:157], v[216:219], v[46:49]
	v_mfma_f32_16x16x32_bf16 v[42:45], v[162:165], v[216:219], v[42:45]
	s_setprio 0
	s_setprio 1
	v_mfma_f32_16x16x32_bf16 v[126:129], v[166:169], v[188:191], v[126:129]
	v_mfma_f32_16x16x32_bf16 v[122:125], v[180:183], v[188:191], v[122:125]
	v_mfma_f32_16x16x32_bf16 v[118:121], v[166:169], v[196:199], v[118:121]
	v_mfma_f32_16x16x32_bf16 v[114:117], v[180:183], v[196:199], v[114:117]
	v_mfma_f32_16x16x32_bf16 v[110:113], v[166:169], v[204:207], v[110:113]
	v_mfma_f32_16x16x32_bf16 v[106:109], v[180:183], v[204:207], v[106:109]
	v_mfma_f32_16x16x32_bf16 v[102:105], v[166:169], v[212:215], v[102:105]
	v_mfma_f32_16x16x32_bf16 v[98:101], v[180:183], v[212:215], v[98:101]
	v_mfma_f32_16x16x32_bf16 v[126:129], v[170:173], v[192:195], v[126:129]
	v_mfma_f32_16x16x32_bf16 v[122:125], v[184:187], v[192:195], v[122:125]
	v_mfma_f32_16x16x32_bf16 v[118:121], v[170:173], v[200:203], v[118:121]
	v_mfma_f32_16x16x32_bf16 v[114:117], v[184:187], v[200:203], v[114:117]
	v_mfma_f32_16x16x32_bf16 v[110:113], v[170:173], v[208:211], v[110:113]
	v_mfma_f32_16x16x32_bf16 v[106:109], v[184:187], v[208:211], v[106:109]
	v_mfma_f32_16x16x32_bf16 v[102:105], v[170:173], v[216:219], v[102:105]
	v_mfma_f32_16x16x32_bf16 v[98:101], v[184:187], v[216:219], v[98:101]
	s_setprio 0
	s_barrier
	s_add_i32 s34, s55, s39
	v_lshl_add_u64 v[146:147], v[146:147], 0, s[96:97]
	s_mov_b32 m0, s34
	ds_read_b128 v[188:191], v153 offset:49152
	ds_read_b128 v[192:195], v153 offset:50176
	ds_read_b128 v[196:199], v153 offset:51200
	ds_read_b128 v[200:203], v153 offset:52224
	ds_read_b128 v[204:207], v153 offset:53248
	ds_read_b128 v[208:211], v153 offset:54272
	ds_read_b128 v[212:215], v153 offset:55296
	ds_read_b128 v[216:219], v153 offset:56320
	global_load_lds_dwordx4 v[146:147], off
	s_add_i32 m0, s34, 0x2000
	s_add_u32 s30, s30, 0x40080
	v_lshl_add_u64 v[146:147], v[220:221], 0, s[96:97]
	s_addc_u32 s31, s31, 0
	s_add_i32 s34, s56, s39
	global_load_lds_dwordx4 v[146:147], off
	v_lshl_add_u64 v[146:147], s[30:31], 0, v[138:139]
	s_mov_b32 m0, s34
	s_nop 0
	global_load_lds_dwordx4 v[146:147], off
	v_lshl_add_u64 v[146:147], s[30:31], 0, v[134:135]
	s_add_i32 m0, s34, 0x2000
	s_nop 0
	global_load_lds_dwordx4 v[146:147], off
	v_lshl_add_u64 v[146:147], v[222:223], 0, s[96:97]
	s_mov_b32 m0, s48
	s_nop 0
	global_load_lds_dwordx4 v[146:147], off
	v_lshl_add_u64 v[146:147], v[228:229], 0, s[96:97]
	s_mov_b32 m0, s49
	s_nop 0
	global_load_lds_dwordx4 v[146:147], off
	s_waitcnt vmcnt(8)
	s_waitcnt lgkmcnt(0)
	s_barrier
	s_setprio 1
	s_waitcnt lgkmcnt(0)
	v_mfma_f32_16x16x32_bf16 v[30:33], v[130:133], v[188:191], v[30:33]
	v_mfma_f32_16x16x32_bf16 v[26:29], v[158:161], v[188:191], v[26:29]
	v_mfma_f32_16x16x32_bf16 v[22:25], v[130:133], v[196:199], v[22:25]
	v_mfma_f32_16x16x32_bf16 v[18:21], v[158:161], v[196:199], v[18:21]
	v_mfma_f32_16x16x32_bf16 v[14:17], v[130:133], v[204:207], v[14:17]
	v_mfma_f32_16x16x32_bf16 v[10:13], v[158:161], v[204:207], v[10:13]
	v_mfma_f32_16x16x32_bf16 v[6:9], v[130:133], v[212:215], v[6:9]
	v_mfma_f32_16x16x32_bf16 v[2:5], v[158:161], v[212:215], v[2:5]
	v_mfma_f32_16x16x32_bf16 v[30:33], v[154:157], v[192:195], v[30:33]
	v_mfma_f32_16x16x32_bf16 v[26:29], v[162:165], v[192:195], v[26:29]
	v_mfma_f32_16x16x32_bf16 v[22:25], v[154:157], v[200:203], v[22:25]
	v_mfma_f32_16x16x32_bf16 v[18:21], v[162:165], v[200:203], v[18:21]
	v_mfma_f32_16x16x32_bf16 v[14:17], v[154:157], v[208:211], v[14:17]
	v_mfma_f32_16x16x32_bf16 v[10:13], v[162:165], v[208:211], v[10:13]
	v_mfma_f32_16x16x32_bf16 v[6:9], v[154:157], v[216:219], v[6:9]
	v_mfma_f32_16x16x32_bf16 v[2:5], v[162:165], v[216:219], v[2:5]
	s_setprio 0
	s_setprio 1
	v_mfma_f32_16x16x32_bf16 v[94:97], v[166:169], v[188:191], v[94:97]
	v_mfma_f32_16x16x32_bf16 v[90:93], v[180:183], v[188:191], v[90:93]
	v_mfma_f32_16x16x32_bf16 v[86:89], v[166:169], v[196:199], v[86:89]
	v_mfma_f32_16x16x32_bf16 v[82:85], v[180:183], v[196:199], v[82:85]
	v_mfma_f32_16x16x32_bf16 v[78:81], v[166:169], v[204:207], v[78:81]
	v_mfma_f32_16x16x32_bf16 v[74:77], v[180:183], v[204:207], v[74:77]
	v_mfma_f32_16x16x32_bf16 v[38:41], v[166:169], v[212:215], v[38:41]
	v_mfma_f32_16x16x32_bf16 v[34:37], v[180:183], v[212:215], v[34:37]
	v_mfma_f32_16x16x32_bf16 v[94:97], v[170:173], v[192:195], v[94:97]
	v_mfma_f32_16x16x32_bf16 v[90:93], v[184:187], v[192:195], v[90:93]
	v_mfma_f32_16x16x32_bf16 v[86:89], v[170:173], v[200:203], v[86:89]
	v_mfma_f32_16x16x32_bf16 v[82:85], v[184:187], v[200:203], v[82:85]
	v_mfma_f32_16x16x32_bf16 v[78:81], v[170:173], v[208:211], v[78:81]
	v_mfma_f32_16x16x32_bf16 v[74:77], v[184:187], v[208:211], v[74:77]
	v_mfma_f32_16x16x32_bf16 v[38:41], v[170:173], v[216:219], v[38:41]
	v_mfma_f32_16x16x32_bf16 v[34:37], v[184:187], v[216:219], v[34:37]
	s_setprio 0
	s_barrier
	s_add_i32 s54, s54, 2
	s_add_u32 s28, s28, 0x100
	s_addc_u32 s29, s29, 0
	s_add_u32 s52, s52, 0x100
	s_addc_u32 s53, s53, 0
	s_cmp_gt_u32 s54, 13
	s_cbranch_scc0 .LBB0_185
	s_and_b64 vcc, exec, s[16:17]
	s_cbranch_vccz .LBB0_188
	s_barrier

; #define PG8_STAGE(bufoff, gbase, voff) do { _Pragma("unroll") for (int _i = 0; _i < 2; ++_i) \
;         __builtin_amdgcn_global_load_lds((const unsigned*)((const char*)(gbase) + (voff)[_i]), (PG8_LAS unsigned*)(lds + (bufoff) + ldsw + _i * 8192), 16, 0, 0); } while (0)
; #define PG8_LDA(dst, b, h) do { _Pragma("unroll") for (int m = 0; m < 4; ++m) _Pragma("unroll") for (int k = 0; k < 2; ++k) dst[m][k] = *(const PG8_LAS bf16x8*)(lds + PG8_SA(b, h) + aoff + m * 2048 + k * 1024); } while (0)
; #define PG8_LDB(dst, b, h) do { _Pragma("unroll") for (int n = 0; n < 2; ++n) _Pragma("unroll") for (int k = 0; k < 2; ++k) dst[n][k] = *(const PG8_LAS bf16x8*)(lds + PG8_SB(b, h) + boff + n * 2048 + k * 1024); } while (0)
; #define PG8_SCHED __builtin_amdgcn_sched_barrier(0)
; template <class Epi, class Sched, bool ALIGN_EPI = false, bool SP2 = false>
; __device__ __forceinline__ void gemm_phase(PG8_LAS unsigned char* lds, const Gemm g, const Sched& S, const Epi& E) {
;     ...
; #pragma unroll
;     for (int a = 0; a < 2; ++a)
; #pragma unroll
;         for (int b = 0; b < 2; ++b)
; #pragma unroll
;             for (int m = 0; m < 4; ++m)
; #pragma unroll
;                 for (int n = 0; n < 2; ++n) acc[a][b][m][n] = (f32x4){0.f, 0.f, 0.f, 0.f};
;     ...
;             const char* a1 = cA + (size_t)(t + 1) * kstep;
;             const char* a2 = last ? nA : cA + (size_t)(t + 2) * kstep; const char* b2 = last ? nB : cB + (size_t)(t + 2) * kstep;
;             const char* a3 = a2 + kstep; const char* b3 = b2 + kstep;
;             if (last && has_next) S.a_ready(nxt);
;             if constexpr (SP2) {
;             PG8_LDB(B0, 0, 0); PG8_LDB(B1, 0, 1); PG8_SCHED; PG8_LDA(At, 0, 0); PG8_STAGE(PG8_SA(1, 1), a1 + hstep, voffA);
.LBB0_632:
	s_ashr_i32 s29, s28, 31
	s_lshl_b64 s[30:31], s[28:29], 19
	s_add_u32 s30, s38, s30
	s_addc_u32 s31, s39, s31
	s_and_b64 s[34:35], s[8:9], exec
	s_cselect_b32 s5, s31, s11
	s_cselect_b32 s25, s30, s10
	s_ashr_i32 s27, s26, 31
	s_lshl_b64 s[34:35], s[26:27], 19
	s_add_u32 s34, s40, s34
	s_addc_u32 s35, s41, s35
	s_and_b64 s[36:37], s[8:9], exec
	s_cselect_b32 s27, s35, s13
	s_cselect_b32 s29, s34, s12
	s_add_u32 s10, s10, 0x40080
	s_addc_u32 s11, s11, 0
	s_add_u32 s33, s12, 0x100
	s_addc_u32 s54, s13, 0
	s_mov_b32 s55, -2
	s_waitcnt lgkmcnt(0)
.LBB0_633:
	s_add_u32 s12, s10, 0xfffc0080
	s_addc_u32 s13, s11, -1
	s_add_i32 s56, 0, 0x10000
	s_cmp_eq_u32 s55, 12
	s_cselect_b32 s37, s5, s13
	s_cselect_b32 s36, s25, s12
	s_cselect_b32 s13, s27, s54
	s_cselect_b32 s12, s29, s33
	s_add_i32 s58, 0, 0x14000
	v_add_u32_e32 v94, s56, v203
	v_add_u32_e32 v134, s58, v203
	ds_read_b128 v[66:69], v94
	ds_read_b128 v[70:73], v94 offset:1024
	ds_read_b128 v[82:85], v94 offset:2048
	ds_read_b128 v[94:97], v94 offset:3072
	ds_read_b128 v[106:109], v134
	ds_read_b128 v[118:121], v134 offset:1024
	ds_read_b128 v[130:133], v134 offset:2048
	ds_read_b128 v[134:137], v134 offset:3072
	v_lshl_add_u64 v[200:201], s[10:11], 0, v[184:185]
	s_add_i32 m0, s43, 0xc000
	ds_read_b128 v[162:165], v204
	ds_read_b128 v[166:169], v204 offset:1024
	ds_read_b128 v[188:191], v204 offset:2048
	ds_read_b128 v[192:195], v204 offset:3072
	ds_read_b128 v[196:199], v204 offset:4096
	ds_read_b128 v[206:209], v204 offset:5120
	ds_read_b128 v[210:213], v204 offset:6144
	ds_read_b128 v[214:217], v204 offset:7168
	global_load_lds_dwordx4 v[200:201], off
	v_lshl_add_u64 v[200:201], s[10:11], 0, v[186:187]
	s_add_i32 m0, s43, 0xe000
	s_nop 0
	global_load_lds_dwordx4 v[200:201], off
	s_cmp_lg_u32 s55, -2
	s_cbranch_scc1 .Lodout_noz
	v_mov_b32_e32 v2, 0
	v_mov_b32_e32 v3, v2
	v_mov_b32_e32 v4, v2
	v_mov_b32_e32 v5, v2
	v_mov_b32_e32 v6, v2
	v_mov_b32_e32 v7, v2
	v_mov_b32_e32 v8, v2
	v_mov_b32_e32 v9, v2
	v_mov_b32_e32 v18, v2
	v_mov_b32_e32 v19, v2
	v_mov_b32_e32 v20, v2
	v_mov_b32_e32 v21, v2
	v_mov_b32_e32 v22, v2
	v_mov_b32_e32 v23, v2
	v_mov_b32_e32 v24, v2
	v_mov_b32_e32 v25, v2
	v_mov_b32_e32 v34, v2
	v_mov_b32_e32 v35, v2
	v_mov_b32_e32 v36, v2
	v_mov_b32_e32 v37, v2
	v_mov_b32_e32 v38, v2
	v_mov_b32_e32 v39, v2
	v_mov_b32_e32 v40, v2
	v_mov_b32_e32 v41, v2
	v_mov_b32_e32 v50, v2
	v_mov_b32_e32 v51, v2
	v_mov_b32_e32 v52, v2
	v_mov_b32_e32 v53, v2
	v_mov_b32_e32 v54, v2
	v_mov_b32_e32 v55, v2
	v_mov_b32_e32 v56, v2
	v_mov_b32_e32 v57, v2
	v_mov_b32_e32 v10, v2
	v_mov_b32_e32 v11, v2
	v_mov_b32_e32 v12, v2
	v_mov_b32_e32 v13, v2
	v_mov_b32_e32 v14, v2
	v_mov_b32_e32 v15, v2
	v_mov_b32_e32 v16, v2
	v_mov_b32_e32 v17, v2
	v_mov_b32_e32 v26, v2
	v_mov_b32_e32 v27, v2
	v_mov_b32_e32 v28, v2
	v_mov_b32_e32 v29, v2
	v_mov_b32_e32 v30, v2
	v_mov_b32_e32 v31, v2
	v_mov_b32_e32 v32, v2
	v_mov_b32_e32 v33, v2
	v_mov_b32_e32 v42, v2
	v_mov_b32_e32 v43, v2
	v_mov_b32_e32 v44, v2
	v_mov_b32_e32 v45, v2
	v_mov_b32_e32 v46, v2
	v_mov_b32_e32 v47, v2
	v_mov_b32_e32 v48, v2
	v_mov_b32_e32 v49, v2
	v_mov_b32_e32 v58, v2
	v_mov_b32_e32 v59, v2
	v_mov_b32_e32 v60, v2
	v_mov_b32_e32 v61, v2
	v_mov_b32_e32 v62, v2
	v_mov_b32_e32 v63, v2
	v_mov_b32_e32 v64, v2
	v_mov_b32_e32 v65, v2
	v_mov_b32_e32 v74, v2
	v_mov_b32_e32 v75, v2
	v_mov_b32_e32 v76, v2
	v_mov_b32_e32 v77, v2
	v_mov_b32_e32 v78, v2
	v_mov_b32_e32 v79, v2
	v_mov_b32_e32 v80, v2
	v_mov_b32_e32 v81, v2
	v_mov_b32_e32 v98, v2
	v_mov_b32_e32 v99, v2
	v_mov_b32_e32 v100, v2
	v_mov_b32_e32 v101, v2
	v_mov_b32_e32 v102, v2
	v_mov_b32_e32 v103, v2
	v_mov_b32_e32 v104, v2
	v_mov_b32_e32 v105, v2
	v_mov_b32_e32 v122, v2
	v_mov_b32_e32 v123, v2
	v_mov_b32_e32 v124, v2
	v_mov_b32_e32 v125, v2
	v_mov_b32_e32 v126, v2
	v_mov_b32_e32 v127, v2
	v_mov_b32_e32 v128, v2
	v_mov_b32_e32 v129, v2
	v_mov_b32_e32 v146, v2
	v_mov_b32_e32 v147, v2
	v_mov_b32_e32 v148, v2
	v_mov_b32_e32 v149, v2
	v_mov_b32_e32 v150, v2
	v_mov_b32_e32 v151, v2
	v_mov_b32_e32 v152, v2
	v_mov_b32_e32 v153, v2
	v_mov_b32_e32 v86, v2
	v_mov_b32_e32 v87, v2
	v_mov_b32_e32 v88, v2
	v_mov_b32_e32 v89, v2
	v_mov_b32_e32 v90, v2
	v_mov_b32_e32 v91, v2
	v_mov_b32_e32 v92, v2
	v_mov_b32_e32 v93, v2
	v_mov_b32_e32 v110, v2
	v_mov_b32_e32 v111, v2
	v_mov_b32_e32 v112, v2
	v_mov_b32_e32 v113, v2
	v_mov_b32_e32 v114, v2
	v_mov_b32_e32 v115, v2
	v_mov_b32_e32 v116, v2
	v_mov_b32_e32 v117, v2
	v_mov_b32_e32 v138, v2
	v_mov_b32_e32 v139, v2
	v_mov_b32_e32 v140, v2
	v_mov_b32_e32 v141, v2
	v_mov_b32_e32 v142, v2
	v_mov_b32_e32 v143, v2
	v_mov_b32_e32 v144, v2
	v_mov_b32_e32 v145, v2
	v_mov_b32_e32 v154, v2
	v_mov_b32_e32 v155, v2
	v_mov_b32_e32 v156, v2
	v_mov_b32_e32 v157, v2
	v_mov_b32_e32 v158, v2
	v_mov_b32_e32 v159, v2
	v_mov_b32_e32 v160, v2
	v_mov_b32_e32 v161, v2
; #define PG8_STAGE(bufoff, gbase, voff) do { _Pragma("unroll") for (int _i = 0; _i < 2; ++_i) \
;         __builtin_amdgcn_global_load_lds((const unsigned*)((const char*)(gbase) + (voff)[_i]), (PG8_LAS unsigned*)(lds + (bufoff) + ldsw + _i * 8192), 16, 0, 0); } while (0)
; #define PG8_LDA(dst, b, h) do { _Pragma("unroll") for (int m = 0; m < 4; ++m) _Pragma("unroll") for (int k = 0; k < 2; ++k) dst[m][k] = *(const PG8_LAS bf16x8*)(lds + PG8_SA(b, h) + aoff + m * 2048 + k * 1024); } while (0)
; #define PG8_LDB(dst, b, h) do { _Pragma("unroll") for (int n = 0; n < 2; ++n) _Pragma("unroll") for (int k = 0; k < 2; ++k) dst[n][k] = *(const PG8_LAS bf16x8*)(lds + PG8_SB(b, h) + boff + n * 2048 + k * 1024); } while (0)
; #define PG8_MMA(ai, bj, At, Bt) do { __builtin_amdgcn_s_setprio(1); _Pragma("unroll") for (int m = 0; m < 4; ++m) _Pragma("unroll") for (int n = 0; n < 2; ++n) _Pragma("unroll") for (int k = 0; k < 2; ++k) \
;         acc[ai][bj][m][n] = __builtin_amdgcn_mfma_f32_16x16x32_bf16(Bt[n][k], At[m][k], acc[ai][bj][m][n], 0, 0, 0); __builtin_amdgcn_s_setprio(0); } while (0)
; #define PG8_WAIT_V(n) asm volatile("s_waitcnt vmcnt(" #n ")" ::: "memory")
; #define PG8_WAIT_L(n) asm volatile("s_waitcnt lgkmcnt(" #n ")" ::: "memory")
; #define PG8_BAR __builtin_amdgcn_s_barrier()
; #define PG8_SCHED __builtin_amdgcn_sched_barrier(0)
; template <class Epi, class Sched, bool ALIGN_EPI = false, bool SP2 = false>
; __device__ __forceinline__ void gemm_phase(PG8_LAS unsigned char* lds, const Gemm g, const Sched& S, const Epi& E) {
;     ...
;             PG8_LDB(B0, 0, 0); PG8_LDB(B1, 0, 1); PG8_SCHED; PG8_LDA(At, 0, 0); PG8_STAGE(PG8_SA(1, 1), a1 + hstep, voffA);
;             PG8_WAIT_V(8); PG8_WAIT_L(0); PG8_BAR; PG8_MMA(0, 0, At, B0); PG8_MMA(0, 1, At, B1); PG8_BAR; PG8_SCHED;
;             PG8_LDA(At, 0, 1); PG8_STAGE(PG8_SB(0, 0), b2, voffB); PG8_STAGE(PG8_SB(0, 1), b2 + hstep, voffB); PG8_STAGE(PG8_SA(0, 0), a2, voffA);
;             PG8_WAIT_V(8); PG8_WAIT_L(0); PG8_BAR; PG8_MMA(1, 0, At, B0); PG8_MMA(1, 1, At, B1); PG8_BAR; PG8_SCHED;
.Lodout_noz:
	s_waitcnt vmcnt(8)
	s_waitcnt lgkmcnt(0)
	s_barrier
	s_setprio 1
	s_waitcnt lgkmcnt(0)
	v_mfma_f32_16x16x32_bf16 v[158:161], v[66:69], v[162:165], v[158:161]
	v_mfma_f32_16x16x32_bf16 v[154:157], v[82:85], v[162:165], v[154:157]
	v_mfma_f32_16x16x32_bf16 v[142:145], v[66:69], v[188:191], v[142:145]
	v_mfma_f32_16x16x32_bf16 v[138:141], v[82:85], v[188:191], v[138:141]
	v_mfma_f32_16x16x32_bf16 v[114:117], v[66:69], v[196:199], v[114:117]
	v_mfma_f32_16x16x32_bf16 v[110:113], v[82:85], v[196:199], v[110:113]
	v_mfma_f32_16x16x32_bf16 v[90:93], v[66:69], v[210:213], v[90:93]
	v_mfma_f32_16x16x32_bf16 v[86:89], v[82:85], v[210:213], v[86:89]
	v_mfma_f32_16x16x32_bf16 v[158:161], v[70:73], v[166:169], v[158:161]
	v_mfma_f32_16x16x32_bf16 v[154:157], v[94:97], v[166:169], v[154:157]
	v_mfma_f32_16x16x32_bf16 v[142:145], v[70:73], v[192:195], v[142:145]
	v_mfma_f32_16x16x32_bf16 v[138:141], v[94:97], v[192:195], v[138:141]
	v_mfma_f32_16x16x32_bf16 v[114:117], v[70:73], v[206:209], v[114:117]
	v_mfma_f32_16x16x32_bf16 v[110:113], v[94:97], v[206:209], v[110:113]
	v_mfma_f32_16x16x32_bf16 v[90:93], v[70:73], v[214:217], v[90:93]
	v_mfma_f32_16x16x32_bf16 v[86:89], v[94:97], v[214:217], v[86:89]
	s_setprio 0
	s_setprio 1
	v_mfma_f32_16x16x32_bf16 v[150:153], v[106:109], v[162:165], v[150:153]
	v_mfma_f32_16x16x32_bf16 v[146:149], v[130:133], v[162:165], v[146:149]
	v_mfma_f32_16x16x32_bf16 v[126:129], v[106:109], v[188:191], v[126:129]
	v_mfma_f32_16x16x32_bf16 v[122:125], v[130:133], v[188:191], v[122:125]
	v_mfma_f32_16x16x32_bf16 v[102:105], v[106:109], v[196:199], v[102:105]
	v_mfma_f32_16x16x32_bf16 v[98:101], v[130:133], v[196:199], v[98:101]
	v_mfma_f32_16x16x32_bf16 v[78:81], v[106:109], v[210:213], v[78:81]
	v_mfma_f32_16x16x32_bf16 v[74:77], v[130:133], v[210:213], v[74:77]
	v_mfma_f32_16x16x32_bf16 v[150:153], v[118:121], v[166:169], v[150:153]
	v_mfma_f32_16x16x32_bf16 v[146:149], v[134:137], v[166:169], v[146:149]
	v_mfma_f32_16x16x32_bf16 v[126:129], v[118:121], v[192:195], v[126:129]
	v_mfma_f32_16x16x32_bf16 v[122:125], v[134:137], v[192:195], v[122:125]
	v_mfma_f32_16x16x32_bf16 v[102:105], v[118:121], v[206:209], v[102:105]
	v_mfma_f32_16x16x32_bf16 v[98:101], v[134:137], v[206:209], v[98:101]
	v_mfma_f32_16x16x32_bf16 v[78:81], v[118:121], v[214:217], v[78:81]
	v_mfma_f32_16x16x32_bf16 v[74:77], v[134:137], v[214:217], v[74:77]
	s_setprio 0
	s_barrier
	s_add_i32 s56, s56, s42
	v_lshl_add_u64 v[200:201], s[12:13], 0, v[180:181]
	s_mov_b32 m0, s56
	ds_read_b128 v[162:165], v204 offset:16384
	ds_read_b128 v[166:169], v204 offset:17408
	ds_read_b128 v[188:191], v204 offset:18432
	ds_read_b128 v[192:195], v204 offset:19456
	ds_read_b128 v[196:199], v204 offset:20480
	ds_read_b128 v[206:209], v204 offset:21504
	ds_read_b128 v[210:213], v204 offset:22528
	ds_read_b128 v[214:217], v204 offset:23552
	global_load_lds_dwordx4 v[200:201], off
	s_add_i32 m0, s56, 0x2000
	s_add_u32 s56, s12, 0x40000
	v_lshl_add_u64 v[218:219], s[12:13], 0, v[170:171]
	s_addc_u32 s57, s13, 0
	s_add_i32 s58, s58, s42
	global_load_lds_dwordx4 v[218:219], off
	v_lshl_add_u64 v[220:221], s[56:57], 0, v[180:181]
	s_mov_b32 m0, s58
	v_lshl_add_u64 v[222:223], s[36:37], 0, v[172:173]
	global_load_lds_dwordx4 v[220:221], off
	v_lshl_add_u64 v[220:221], s[56:57], 0, v[170:171]
	s_add_i32 m0, s58, 0x2000
	s_nop 0
	global_load_lds_dwordx4 v[220:221], off
	v_lshl_add_u64 v[220:221], s[36:37], 0, v[182:183]
	s_mov_b32 m0, s43
	s_nop 0
	global_load_lds_dwordx4 v[220:221], off
	s_mov_b32 m0, s44
	s_nop 0
	global_load_lds_dwordx4 v[222:223], off
	s_waitcnt vmcnt(8)
	s_waitcnt lgkmcnt(0)
	s_barrier
	s_setprio 1
	s_waitcnt lgkmcnt(0)
	v_mfma_f32_16x16x32_bf16 v[62:65], v[66:69], v[162:165], v[62:65]
	v_mfma_f32_16x16x32_bf16 v[58:61], v[82:85], v[162:165], v[58:61]
	v_mfma_f32_16x16x32_bf16 v[46:49], v[66:69], v[188:191], v[46:49]
	v_mfma_f32_16x16x32_bf16 v[42:45], v[82:85], v[188:191], v[42:45]
	v_mfma_f32_16x16x32_bf16 v[30:33], v[66:69], v[196:199], v[30:33]
	v_mfma_f32_16x16x32_bf16 v[26:29], v[82:85], v[196:199], v[26:29]
	v_mfma_f32_16x16x32_bf16 v[14:17], v[66:69], v[210:213], v[14:17]
	v_mfma_f32_16x16x32_bf16 v[10:13], v[82:85], v[210:213], v[10:13]
	v_mfma_f32_16x16x32_bf16 v[62:65], v[70:73], v[166:169], v[62:65]
	v_mfma_f32_16x16x32_bf16 v[58:61], v[94:97], v[166:169], v[58:61]
	v_mfma_f32_16x16x32_bf16 v[46:49], v[70:73], v[192:195], v[46:49]
	v_mfma_f32_16x16x32_bf16 v[42:45], v[94:97], v[192:195], v[42:45]
	v_mfma_f32_16x16x32_bf16 v[30:33], v[70:73], v[206:209], v[30:33]
	v_mfma_f32_16x16x32_bf16 v[26:29], v[94:97], v[206:209], v[26:29]
	v_mfma_f32_16x16x32_bf16 v[14:17], v[70:73], v[214:217], v[14:17]
	v_mfma_f32_16x16x32_bf16 v[10:13], v[94:97], v[214:217], v[10:13]
	s_setprio 0
	s_setprio 1
	v_mfma_f32_16x16x32_bf16 v[54:57], v[106:109], v[162:165], v[54:57]
	v_mfma_f32_16x16x32_bf16 v[50:53], v[130:133], v[162:165], v[50:53]
	v_mfma_f32_16x16x32_bf16 v[38:41], v[106:109], v[188:191], v[38:41]
	v_mfma_f32_16x16x32_bf16 v[34:37], v[130:133], v[188:191], v[34:37]
	v_mfma_f32_16x16x32_bf16 v[22:25], v[106:109], v[196:199], v[22:25]
	v_mfma_f32_16x16x32_bf16 v[18:21], v[130:133], v[196:199], v[18:21]
	v_mfma_f32_16x16x32_bf16 v[6:9], v[106:109], v[210:213], v[6:9]
	v_mfma_f32_16x16x32_bf16 v[2:5], v[130:133], v[210:213], v[2:5]
	v_mfma_f32_16x16x32_bf16 v[54:57], v[118:121], v[166:169], v[54:57]
	v_mfma_f32_16x16x32_bf16 v[50:53], v[134:137], v[166:169], v[50:53]
	v_mfma_f32_16x16x32_bf16 v[38:41], v[118:121], v[192:195], v[38:41]
	v_mfma_f32_16x16x32_bf16 v[34:37], v[134:137], v[192:195], v[34:37]
	v_mfma_f32_16x16x32_bf16 v[22:25], v[118:121], v[206:209], v[22:25]
	v_mfma_f32_16x16x32_bf16 v[18:21], v[134:137], v[206:209], v[18:21]
	v_mfma_f32_16x16x32_bf16 v[6:9], v[118:121], v[214:217], v[6:9]
	v_mfma_f32_16x16x32_bf16 v[2:5], v[134:137], v[214:217], v[2:5]
	s_setprio 0
	s_barrier
; #define PG8_STAGE(bufoff, gbase, voff) do { _Pragma("unroll") for (int _i = 0; _i < 2; ++_i) \
;         __builtin_amdgcn_global_load_lds((const unsigned*)((const char*)(gbase) + (voff)[_i]), (PG8_LAS unsigned*)(lds + (bufoff) + ldsw + _i * 8192), 16, 0, 0); } while (0)
; #define PG8_LDA(dst, b, h) do { _Pragma("unroll") for (int m = 0; m < 4; ++m) _Pragma("unroll") for (int k = 0; k < 2; ++k) dst[m][k] = *(const PG8_LAS bf16x8*)(lds + PG8_SA(b, h) + aoff + m * 2048 + k * 1024); } while (0)
; #define PG8_LDB(dst, b, h) do { _Pragma("unroll") for (int n = 0; n < 2; ++n) _Pragma("unroll") for (int k = 0; k < 2; ++k) dst[n][k] = *(const PG8_LAS bf16x8*)(lds + PG8_SB(b, h) + boff + n * 2048 + k * 1024); } while (0)
; #define PG8_MMA(ai, bj, At, Bt) do { __builtin_amdgcn_s_setprio(1); _Pragma("unroll") for (int m = 0; m < 4; ++m) _Pragma("unroll") for (int n = 0; n < 2; ++n) _Pragma("unroll") for (int k = 0; k < 2; ++k) \
;         acc[ai][bj][m][n] = __builtin_amdgcn_mfma_f32_16x16x32_bf16(Bt[n][k], At[m][k], acc[ai][bj][m][n], 0, 0, 0); __builtin_amdgcn_s_setprio(0); } while (0)
; #define PG8_WAIT_V(n) asm volatile("s_waitcnt vmcnt(" #n ")" ::: "memory")
; #define PG8_WAIT_L(n) asm volatile("s_waitcnt lgkmcnt(" #n ")" ::: "memory")
; #define PG8_BAR __builtin_amdgcn_s_barrier()
; #define PG8_SCHED __builtin_amdgcn_sched_barrier(0)
; template <class Epi, class Sched, bool ALIGN_EPI = false, bool SP2 = false>
; __device__ __forceinline__ void gemm_phase(PG8_LAS unsigned char* lds, const Gemm g, const Sched& S, const Epi& E) {
;     ...
;             PG8_LDB(B0, 1, 0); PG8_LDB(B1, 1, 1); PG8_SCHED; PG8_LDA(At, 1, 0); PG8_STAGE(PG8_SA(0, 1), a2 + hstep, voffA);
;             PG8_WAIT_V(8); PG8_WAIT_L(0); PG8_BAR; PG8_MMA(0, 0, At, B0); PG8_MMA(0, 1, At, B1); PG8_BAR; PG8_SCHED;
	s_add_i32 s56, 0, 0x18000
	s_add_i32 s57, 0, 0x1c000
	v_add_u32_e32 v94, s56, v203
	v_add_u32_e32 v134, s57, v203
	ds_read_b128 v[66:69], v94
	ds_read_b128 v[70:73], v94 offset:1024
	ds_read_b128 v[82:85], v94 offset:2048
	ds_read_b128 v[94:97], v94 offset:3072
	ds_read_b128 v[106:109], v134
	ds_read_b128 v[118:121], v134 offset:1024
	ds_read_b128 v[130:133], v134 offset:2048
	ds_read_b128 v[134:137], v134 offset:3072
	s_add_u32 s36, s36, 0x40000
	s_addc_u32 s37, s37, 0
	s_mov_b32 m0, s45
	v_lshl_add_u64 v[228:229], s[36:37], 0, v[182:183]
	ds_read_b128 v[162:165], v204 offset:32768
	ds_read_b128 v[166:169], v204 offset:33792
	ds_read_b128 v[188:191], v204 offset:34816
	ds_read_b128 v[192:195], v204 offset:35840
	ds_read_b128 v[196:199], v204 offset:36864
	ds_read_b128 v[206:209], v204 offset:37888
	ds_read_b128 v[210:213], v204 offset:38912
	ds_read_b128 v[214:217], v204 offset:39936
	global_load_lds_dwordx4 v[228:229], off
	v_lshl_add_u64 v[228:229], s[36:37], 0, v[172:173]
	s_mov_b32 m0, s46
	s_nop 0
	global_load_lds_dwordx4 v[228:229], off
	s_waitcnt vmcnt(8)
	s_waitcnt lgkmcnt(0)
	s_barrier
	s_setprio 1
	s_waitcnt lgkmcnt(0)
	v_mfma_f32_16x16x32_bf16 v[158:161], v[66:69], v[162:165], v[158:161]
	v_mfma_f32_16x16x32_bf16 v[154:157], v[82:85], v[162:165], v[154:157]
	v_mfma_f32_16x16x32_bf16 v[142:145], v[66:69], v[188:191], v[142:145]
	v_mfma_f32_16x16x32_bf16 v[138:141], v[82:85], v[188:191], v[138:141]
	v_mfma_f32_16x16x32_bf16 v[114:117], v[66:69], v[196:199], v[114:117]
	v_mfma_f32_16x16x32_bf16 v[110:113], v[82:85], v[196:199], v[110:113]
	v_mfma_f32_16x16x32_bf16 v[90:93], v[66:69], v[210:213], v[90:93]
	v_mfma_f32_16x16x32_bf16 v[86:89], v[82:85], v[210:213], v[86:89]
	v_mfma_f32_16x16x32_bf16 v[158:161], v[70:73], v[166:169], v[158:161]
	v_mfma_f32_16x16x32_bf16 v[154:157], v[94:97], v[166:169], v[154:157]
	v_mfma_f32_16x16x32_bf16 v[142:145], v[70:73], v[192:195], v[142:145]
	v_mfma_f32_16x16x32_bf16 v[138:141], v[94:97], v[192:195], v[138:141]
	v_mfma_f32_16x16x32_bf16 v[114:117], v[70:73], v[206:209], v[114:117]
	v_mfma_f32_16x16x32_bf16 v[110:113], v[94:97], v[206:209], v[110:113]
	v_mfma_f32_16x16x32_bf16 v[90:93], v[70:73], v[214:217], v[90:93]
	v_mfma_f32_16x16x32_bf16 v[86:89], v[94:97], v[214:217], v[86:89]
	s_setprio 0
	s_setprio 1
	v_mfma_f32_16x16x32_bf16 v[150:153], v[106:109], v[162:165], v[150:153]
	v_mfma_f32_16x16x32_bf16 v[146:149], v[130:133], v[162:165], v[146:149]
	v_mfma_f32_16x16x32_bf16 v[126:129], v[106:109], v[188:191], v[126:129]
	v_mfma_f32_16x16x32_bf16 v[122:125], v[130:133], v[188:191], v[122:125]
	v_mfma_f32_16x16x32_bf16 v[102:105], v[106:109], v[196:199], v[102:105]
	v_mfma_f32_16x16x32_bf16 v[98:101], v[130:133], v[196:199], v[98:101]
	v_mfma_f32_16x16x32_bf16 v[78:81], v[106:109], v[210:213], v[78:81]
	v_mfma_f32_16x16x32_bf16 v[74:77], v[130:133], v[210:213], v[74:77]
	v_mfma_f32_16x16x32_bf16 v[150:153], v[118:121], v[166:169], v[150:153]
	v_mfma_f32_16x16x32_bf16 v[146:149], v[134:137], v[166:169], v[146:149]
	v_mfma_f32_16x16x32_bf16 v[126:129], v[118:121], v[192:195], v[126:129]
	v_mfma_f32_16x16x32_bf16 v[122:125], v[134:137], v[192:195], v[122:125]
	v_mfma_f32_16x16x32_bf16 v[102:105], v[118:121], v[206:209], v[102:105]
	v_mfma_f32_16x16x32_bf16 v[98:101], v[134:137], v[206:209], v[98:101]
	v_mfma_f32_16x16x32_bf16 v[78:81], v[118:121], v[214:217], v[78:81]
	v_mfma_f32_16x16x32_bf16 v[74:77], v[134:137], v[214:217], v[74:77]
	s_setprio 0
	s_barrier
; #define PG8_STAGE(bufoff, gbase, voff) do { _Pragma("unroll") for (int _i = 0; _i < 2; ++_i) \
;         __builtin_amdgcn_global_load_lds((const unsigned*)((const char*)(gbase) + (voff)[_i]), (PG8_LAS unsigned*)(lds + (bufoff) + ldsw + _i * 8192), 16, 0, 0); } while (0)
; #define PG8_LDA(dst, b, h) do { _Pragma("unroll") for (int m = 0; m < 4; ++m) _Pragma("unroll") for (int k = 0; k < 2; ++k) dst[m][k] = *(const PG8_LAS bf16x8*)(lds + PG8_SA(b, h) + aoff + m * 2048 + k * 1024); } while (0)
; #define PG8_MMA(ai, bj, At, Bt) do { __builtin_amdgcn_s_setprio(1); _Pragma("unroll") for (int m = 0; m < 4; ++m) _Pragma("unroll") for (int n = 0; n < 2; ++n) _Pragma("unroll") for (int k = 0; k < 2; ++k) \
;         acc[ai][bj][m][n] = __builtin_amdgcn_mfma_f32_16x16x32_bf16(Bt[n][k], At[m][k], acc[ai][bj][m][n], 0, 0, 0); __builtin_amdgcn_s_setprio(0); } while (0)
; #define PG8_WAIT_V(n) asm volatile("s_waitcnt vmcnt(" #n ")" ::: "memory")
; #define PG8_WAIT_L(n) asm volatile("s_waitcnt lgkmcnt(" #n ")" ::: "memory")
; #define PG8_BAR __builtin_amdgcn_s_barrier()
; #define PG8_SCHED __builtin_amdgcn_sched_barrier(0)
; template <class Epi, class Sched, bool ALIGN_EPI = false, bool SP2 = false>
; __device__ __forceinline__ void gemm_phase(PG8_LAS unsigned char* lds, const Gemm g, const Sched& S, const Epi& E) {
;     ...
;             PG8_WAIT_V(8); PG8_WAIT_L(0); PG8_BAR; PG8_MMA(0, 0, At, B0); PG8_MMA(0, 1, At, B1); PG8_BAR; PG8_SCHED;
;             PG8_LDA(At, 1, 1); PG8_STAGE(PG8_SB(1, 0), b3, voffB); PG8_STAGE(PG8_SB(1, 1), b3 + hstep, voffB); PG8_STAGE(PG8_SA(1, 0), a3, voffA);
;             PG8_WAIT_V(8); PG8_WAIT_L(0); PG8_BAR; PG8_MMA(1, 0, At, B0); PG8_MMA(1, 1, At, B1); PG8_BAR; PG8_SCHED;
	s_add_i32 s36, s56, s42
	v_lshl_add_u64 v[200:201], v[200:201], 0, s[96:97]
	s_mov_b32 m0, s36
	ds_read_b128 v[162:165], v204 offset:49152
	ds_read_b128 v[166:169], v204 offset:50176
	ds_read_b128 v[188:191], v204 offset:51200
	ds_read_b128 v[192:195], v204 offset:52224
	ds_read_b128 v[196:199], v204 offset:53248
	ds_read_b128 v[206:209], v204 offset:54272
	ds_read_b128 v[210:213], v204 offset:55296
	ds_read_b128 v[214:217], v204 offset:56320
	global_load_lds_dwordx4 v[200:201], off
	s_add_i32 m0, s36, 0x2000
	s_add_u32 s12, s12, 0x40080
	v_lshl_add_u64 v[200:201], v[218:219], 0, s[96:97]
	s_addc_u32 s13, s13, 0
	s_add_i32 s36, s57, s42
	global_load_lds_dwordx4 v[200:201], off
	v_lshl_add_u64 v[200:201], s[12:13], 0, v[180:181]
	s_mov_b32 m0, s36
	s_nop 0
	global_load_lds_dwordx4 v[200:201], off
	v_lshl_add_u64 v[200:201], s[12:13], 0, v[170:171]
	s_add_i32 m0, s36, 0x2000
	s_nop 0
	global_load_lds_dwordx4 v[200:201], off
	v_lshl_add_u64 v[200:201], v[220:221], 0, s[96:97]
	s_mov_b32 m0, s50
	s_nop 0
	global_load_lds_dwordx4 v[200:201], off
	v_lshl_add_u64 v[200:201], v[222:223], 0, s[96:97]
	s_mov_b32 m0, s51
	s_nop 0
	global_load_lds_dwordx4 v[200:201], off
	s_waitcnt vmcnt(8)
	s_waitcnt lgkmcnt(0)
	s_barrier
	s_setprio 1
	s_waitcnt lgkmcnt(0)
	v_mfma_f32_16x16x32_bf16 v[62:65], v[66:69], v[162:165], v[62:65]
	v_mfma_f32_16x16x32_bf16 v[58:61], v[82:85], v[162:165], v[58:61]
	v_mfma_f32_16x16x32_bf16 v[46:49], v[66:69], v[188:191], v[46:49]
	v_mfma_f32_16x16x32_bf16 v[42:45], v[82:85], v[188:191], v[42:45]
	v_mfma_f32_16x16x32_bf16 v[30:33], v[66:69], v[196:199], v[30:33]
	v_mfma_f32_16x16x32_bf16 v[26:29], v[82:85], v[196:199], v[26:29]
	v_mfma_f32_16x16x32_bf16 v[14:17], v[66:69], v[210:213], v[14:17]
	v_mfma_f32_16x16x32_bf16 v[10:13], v[82:85], v[210:213], v[10:13]
	v_mfma_f32_16x16x32_bf16 v[62:65], v[70:73], v[166:169], v[62:65]
	v_mfma_f32_16x16x32_bf16 v[58:61], v[94:97], v[166:169], v[58:61]
	v_mfma_f32_16x16x32_bf16 v[46:49], v[70:73], v[192:195], v[46:49]
	v_mfma_f32_16x16x32_bf16 v[42:45], v[94:97], v[192:195], v[42:45]
	v_mfma_f32_16x16x32_bf16 v[30:33], v[70:73], v[206:209], v[30:33]
	v_mfma_f32_16x16x32_bf16 v[26:29], v[94:97], v[206:209], v[26:29]
	v_mfma_f32_16x16x32_bf16 v[14:17], v[70:73], v[214:217], v[14:17]
	v_mfma_f32_16x16x32_bf16 v[10:13], v[94:97], v[214:217], v[10:13]
	s_setprio 0
	s_setprio 1
	v_mfma_f32_16x16x32_bf16 v[54:57], v[106:109], v[162:165], v[54:57]
	v_mfma_f32_16x16x32_bf16 v[50:53], v[130:133], v[162:165], v[50:53]
	v_mfma_f32_16x16x32_bf16 v[38:41], v[106:109], v[188:191], v[38:41]
	v_mfma_f32_16x16x32_bf16 v[34:37], v[130:133], v[188:191], v[34:37]
	v_mfma_f32_16x16x32_bf16 v[22:25], v[106:109], v[196:199], v[22:25]
	v_mfma_f32_16x16x32_bf16 v[18:21], v[130:133], v[196:199], v[18:21]
	v_mfma_f32_16x16x32_bf16 v[6:9], v[106:109], v[210:213], v[6:9]
	v_mfma_f32_16x16x32_bf16 v[2:5], v[130:133], v[210:213], v[2:5]
	v_mfma_f32_16x16x32_bf16 v[54:57], v[118:121], v[166:169], v[54:57]
	v_mfma_f32_16x16x32_bf16 v[50:53], v[134:137], v[166:169], v[50:53]
	v_mfma_f32_16x16x32_bf16 v[38:41], v[118:121], v[192:195], v[38:41]
	v_mfma_f32_16x16x32_bf16 v[34:37], v[134:137], v[192:195], v[34:37]
	v_mfma_f32_16x16x32_bf16 v[22:25], v[118:121], v[206:209], v[22:25]
	v_mfma_f32_16x16x32_bf16 v[18:21], v[134:137], v[206:209], v[18:21]
	v_mfma_f32_16x16x32_bf16 v[6:9], v[118:121], v[214:217], v[6:9]
	v_mfma_f32_16x16x32_bf16 v[2:5], v[134:137], v[214:217], v[2:5]
	s_setprio 0
	s_barrier
	s_add_i32 s55, s55, 2
	s_add_u32 s10, s10, 0x100
	s_addc_u32 s11, s11, 0
	s_add_u32 s33, s33, 0x100
	s_addc_u32 s54, s54, 0
	s_cmp_gt_u32 s55, 13
	s_cbranch_scc0 .LBB0_633
	s_and_b64 vcc, exec, s[20:21]
	s_cbranch_vccz .LBB0_636
	s_barrier

; template <class Epi, class Sched, bool ALIGN_EPI = false, bool SP2 = false>
; __device__ __forceinline__ void gemm_phase(PG8_LAS unsigned char* lds, const Gemm g, const Sched& S, const Epi& E) {
;     ...
;         const bool has_next = S.next(ui + 1, nxt);
;         const char* nA = has_next ? (const char*)g.A + (size_t)nxt.pm * tstep : cA; const char* nB = has_next ? (const char*)g.Bt + (size_t)nxt.pn * tstep : cB;
;         for (int t = 0; t < nt; t += 2) {
;             const bool last = (t == nt - 2);
;             const char* a1 = cA + (size_t)(t + 1) * kstep;
;             const char* a2 = last ? nA : cA + (size_t)(t + 2) * kstep; const char* b2 = last ? nB : cB + (size_t)(t + 2) * kstep;
;             const char* a3 = a2 + kstep; const char* b3 = b2 + kstep;
.LBB0_811:
	s_ashr_i32 s19, s18, 31
	s_lshl_b64 s[20:21], s[18:19], 19
	s_add_u32 s20, s2, s20
	s_addc_u32 s21, s30, s21
	s_and_b64 s[22:23], s[6:7], exec
	s_cselect_b32 s19, s21, s25
	s_cselect_b32 s33, s20, s24
	s_ashr_i32 s17, s16, 31
	s_lshl_b64 s[22:23], s[16:17], 19
	s_add_u32 s22, s31, s22
	s_addc_u32 s23, s34, s23
	s_and_b64 s[28:29], s[6:7], exec
	s_cselect_b32 s17, s23, s27
	s_cselect_b32 s45, s22, s26
	s_add_u32 s24, s24, 0x40080
	s_addc_u32 s25, s25, 0
	s_add_u32 s46, s26, 0x100
	s_addc_u32 s47, s27, 0
	s_mov_b32 s48, -2

; #define PG8_STAGE(bufoff, gbase, voff) do { _Pragma("unroll") for (int _i = 0; _i < 2; ++_i) \
;         __builtin_amdgcn_global_load_lds((const unsigned*)((const char*)(gbase) + (voff)[_i]), (PG8_LAS unsigned*)(lds + (bufoff) + ldsw + _i * 8192), 16, 0, 0); } while (0)
; #define PG8_LDA(dst, b, h) do { _Pragma("unroll") for (int m = 0; m < 4; ++m) _Pragma("unroll") for (int k = 0; k < 2; ++k) dst[m][k] = *(const PG8_LAS bf16x8*)(lds + PG8_SA(b, h) + aoff + m * 2048 + k * 1024); } while (0)
; #define PG8_LDB(dst, b, h) do { _Pragma("unroll") for (int n = 0; n < 2; ++n) _Pragma("unroll") for (int k = 0; k < 2; ++k) dst[n][k] = *(const PG8_LAS bf16x8*)(lds + PG8_SB(b, h) + boff + n * 2048 + k * 1024); } while (0)
; #define PG8_MMA(ai, bj, At, Bt) do { __builtin_amdgcn_s_setprio(1); _Pragma("unroll") for (int m = 0; m < 4; ++m) _Pragma("unroll") for (int n = 0; n < 2; ++n) _Pragma("unroll") for (int k = 0; k < 2; ++k) \
;         acc[ai][bj][m][n] = __builtin_amdgcn_mfma_f32_16x16x32_bf16(Bt[n][k], At[m][k], acc[ai][bj][m][n], 0, 0, 0); __builtin_amdgcn_s_setprio(0); } while (0)
; #define PG8_WAIT_V(n) asm volatile("s_waitcnt vmcnt(" #n ")" ::: "memory")
; #define PG8_WAIT_L(n) asm volatile("s_waitcnt lgkmcnt(" #n ")" ::: "memory")
; #define PG8_BAR __builtin_amdgcn_s_barrier()
; #define PG8_SCHED __builtin_amdgcn_sched_barrier(0)
; template <class Epi, class Sched, bool ALIGN_EPI = false, bool SP2 = false>
; __device__ __forceinline__ void gemm_phase(PG8_LAS unsigned char* lds, const Gemm g, const Sched& S, const Epi& E) {
;     ...
; #pragma unroll
;     for (int a = 0; a < 2; ++a)
; #pragma unroll
;         for (int b = 0; b < 2; ++b)
; #pragma unroll
;             for (int m = 0; m < 4; ++m)
; #pragma unroll
;                 for (int n = 0; n < 2; ++n) acc[a][b][m][n] = (f32x4){0.f, 0.f, 0.f, 0.f};
;     ...
;             PG8_LDB(B0, 0, 0); PG8_LDB(B1, 0, 1); PG8_SCHED; PG8_LDA(At, 0, 0); PG8_STAGE(PG8_SA(1, 1), a1 + hstep, voffA);
;             PG8_WAIT_V(8); PG8_WAIT_L(0); PG8_BAR; PG8_MMA(0, 0, At, B0); PG8_MMA(0, 1, At, B1); PG8_BAR; PG8_SCHED;
.Levin_nopf:
	ds_read_b128 v[150:153], v142
	ds_read_b128 v[154:157], v142 offset:1024
	ds_read_b128 v[158:161], v142 offset:2048
	ds_read_b128 v[162:165], v142 offset:3072
	v_add_u32_e32 v142, s52, v145
	ds_read_b128 v[166:169], v142
	ds_read_b128 v[170:173], v142 offset:1024
	ds_read_b128 v[180:183], v142 offset:2048
	ds_read_b128 v[184:187], v142 offset:3072
	v_lshl_add_u64 v[146:147], s[24:25], 0, v[138:139]
	s_add_i32 m0, s36, 0xc000
	ds_read_b128 v[188:191], v149
	ds_read_b128 v[192:195], v149 offset:1024
	ds_read_b128 v[196:199], v149 offset:2048
	ds_read_b128 v[200:203], v149 offset:3072
	ds_read_b128 v[204:207], v149 offset:4096
	ds_read_b128 v[208:211], v149 offset:5120
	ds_read_b128 v[212:215], v149 offset:6144
	ds_read_b128 v[216:219], v149 offset:7168
	global_load_lds_dwordx4 v[146:147], off
	v_lshl_add_u64 v[146:147], s[24:25], 0, v[140:141]
	s_add_i32 m0, s36, 0xe000
	s_nop 0
	global_load_lds_dwordx4 v[146:147], off
	s_cmp_lg_u32 s48, -2
	s_cbranch_scc1 .Levin_noz
	v_mov_b32_e32 v2, 0
	v_mov_b32_e32 v3, v2
	v_mov_b32_e32 v4, v2
	v_mov_b32_e32 v5, v2
	v_mov_b32_e32 v6, v2
	v_mov_b32_e32 v7, v2
	v_mov_b32_e32 v8, v2
	v_mov_b32_e32 v9, v2
	v_mov_b32_e32 v14, v2
	v_mov_b32_e32 v15, v2
	v_mov_b32_e32 v16, v2
	v_mov_b32_e32 v17, v2
	v_mov_b32_e32 v22, v2
	v_mov_b32_e32 v23, v2
	v_mov_b32_e32 v24, v2
	v_mov_b32_e32 v25, v2
	v_mov_b32_e32 v30, v2
	v_mov_b32_e32 v31, v2
	v_mov_b32_e32 v32, v2
	v_mov_b32_e32 v33, v2
	v_mov_b32_e32 v38, v2
	v_mov_b32_e32 v39, v2
	v_mov_b32_e32 v40, v2
	v_mov_b32_e32 v41, v2
	v_mov_b32_e32 v46, v2
	v_mov_b32_e32 v47, v2
	v_mov_b32_e32 v48, v2
	v_mov_b32_e32 v49, v2
	v_mov_b32_e32 v54, v2
	v_mov_b32_e32 v55, v2
	v_mov_b32_e32 v56, v2
	v_mov_b32_e32 v57, v2
	v_mov_b32_e32 v10, v2
	v_mov_b32_e32 v11, v2
	v_mov_b32_e32 v12, v2
	v_mov_b32_e32 v13, v2
	v_mov_b32_e32 v18, v2
	v_mov_b32_e32 v19, v2
	v_mov_b32_e32 v20, v2
	v_mov_b32_e32 v21, v2
	v_mov_b32_e32 v26, v2
	v_mov_b32_e32 v27, v2
	v_mov_b32_e32 v28, v2
	v_mov_b32_e32 v29, v2
	v_mov_b32_e32 v34, v2
	v_mov_b32_e32 v35, v2
	v_mov_b32_e32 v36, v2
	v_mov_b32_e32 v37, v2
	v_mov_b32_e32 v42, v2
	v_mov_b32_e32 v43, v2
	v_mov_b32_e32 v44, v2
	v_mov_b32_e32 v45, v2
	v_mov_b32_e32 v50, v2
	v_mov_b32_e32 v51, v2
	v_mov_b32_e32 v52, v2
	v_mov_b32_e32 v53, v2
	v_mov_b32_e32 v58, v2
	v_mov_b32_e32 v59, v2
	v_mov_b32_e32 v60, v2
	v_mov_b32_e32 v61, v2
	v_mov_b32_e32 v62, v2
	v_mov_b32_e32 v63, v2
	v_mov_b32_e32 v64, v2
	v_mov_b32_e32 v65, v2
	v_mov_b32_e32 v66, v2
	v_mov_b32_e32 v67, v2
	v_mov_b32_e32 v68, v2
	v_mov_b32_e32 v69, v2
	v_mov_b32_e32 v70, v2
	v_mov_b32_e32 v71, v2
	v_mov_b32_e32 v72, v2
	v_mov_b32_e32 v73, v2
	v_mov_b32_e32 v78, v2
	v_mov_b32_e32 v79, v2
	v_mov_b32_e32 v80, v2
	v_mov_b32_e32 v81, v2
	v_mov_b32_e32 v86, v2
	v_mov_b32_e32 v87, v2
	v_mov_b32_e32 v88, v2
	v_mov_b32_e32 v89, v2
	v_mov_b32_e32 v94, v2
	v_mov_b32_e32 v95, v2
	v_mov_b32_e32 v96, v2
	v_mov_b32_e32 v97, v2
	v_mov_b32_e32 v102, v2
	v_mov_b32_e32 v103, v2
	v_mov_b32_e32 v104, v2
	v_mov_b32_e32 v105, v2
	v_mov_b32_e32 v110, v2
	v_mov_b32_e32 v111, v2
	v_mov_b32_e32 v112, v2
	v_mov_b32_e32 v113, v2
	v_mov_b32_e32 v118, v2
	v_mov_b32_e32 v119, v2
	v_mov_b32_e32 v120, v2
	v_mov_b32_e32 v121, v2
	v_mov_b32_e32 v74, v2
	v_mov_b32_e32 v75, v2
	v_mov_b32_e32 v76, v2
	v_mov_b32_e32 v77, v2
	v_mov_b32_e32 v82, v2
	v_mov_b32_e32 v83, v2
	v_mov_b32_e32 v84, v2
	v_mov_b32_e32 v85, v2
	v_mov_b32_e32 v90, v2
	v_mov_b32_e32 v91, v2
	v_mov_b32_e32 v92, v2
	v_mov_b32_e32 v93, v2
	v_mov_b32_e32 v98, v2
	v_mov_b32_e32 v99, v2
	v_mov_b32_e32 v100, v2
	v_mov_b32_e32 v101, v2
	v_mov_b32_e32 v106, v2
	v_mov_b32_e32 v107, v2
	v_mov_b32_e32 v108, v2
	v_mov_b32_e32 v109, v2
	v_mov_b32_e32 v114, v2
	v_mov_b32_e32 v115, v2
	v_mov_b32_e32 v116, v2
	v_mov_b32_e32 v117, v2
	v_mov_b32_e32 v122, v2
	v_mov_b32_e32 v123, v2
	v_mov_b32_e32 v124, v2
	v_mov_b32_e32 v125, v2
	v_mov_b32_e32 v126, v2
	v_mov_b32_e32 v127, v2
	v_mov_b32_e32 v128, v2
	v_mov_b32_e32 v129, v2
.Levin_noz:
	s_waitcnt vmcnt(8)
	s_waitcnt lgkmcnt(0)
	s_barrier
	s_setprio 1
	s_waitcnt lgkmcnt(0)
	v_mfma_f32_16x16x32_bf16 v[126:129], v[150:153], v[188:191], v[126:129]
	v_mfma_f32_16x16x32_bf16 v[122:125], v[158:161], v[188:191], v[122:125]
	v_mfma_f32_16x16x32_bf16 v[114:117], v[150:153], v[196:199], v[114:117]
	v_mfma_f32_16x16x32_bf16 v[106:109], v[158:161], v[196:199], v[106:109]
	v_mfma_f32_16x16x32_bf16 v[98:101], v[150:153], v[204:207], v[98:101]
	v_mfma_f32_16x16x32_bf16 v[90:93], v[158:161], v[204:207], v[90:93]
	v_mfma_f32_16x16x32_bf16 v[82:85], v[150:153], v[212:215], v[82:85]
	v_mfma_f32_16x16x32_bf16 v[74:77], v[158:161], v[212:215], v[74:77]
	v_mfma_f32_16x16x32_bf16 v[126:129], v[154:157], v[192:195], v[126:129]
	v_mfma_f32_16x16x32_bf16 v[122:125], v[162:165], v[192:195], v[122:125]
	v_mfma_f32_16x16x32_bf16 v[114:117], v[154:157], v[200:203], v[114:117]
	v_mfma_f32_16x16x32_bf16 v[106:109], v[162:165], v[200:203], v[106:109]
	v_mfma_f32_16x16x32_bf16 v[98:101], v[154:157], v[208:211], v[98:101]
	v_mfma_f32_16x16x32_bf16 v[90:93], v[162:165], v[208:211], v[90:93]
	v_mfma_f32_16x16x32_bf16 v[82:85], v[154:157], v[216:219], v[82:85]
	v_mfma_f32_16x16x32_bf16 v[74:77], v[162:165], v[216:219], v[74:77]
	s_setprio 0
	s_setprio 1
	v_mfma_f32_16x16x32_bf16 v[118:121], v[166:169], v[188:191], v[118:121]
	v_mfma_f32_16x16x32_bf16 v[110:113], v[180:183], v[188:191], v[110:113]
	v_mfma_f32_16x16x32_bf16 v[102:105], v[166:169], v[196:199], v[102:105]
	v_mfma_f32_16x16x32_bf16 v[94:97], v[180:183], v[196:199], v[94:97]
	v_mfma_f32_16x16x32_bf16 v[86:89], v[166:169], v[204:207], v[86:89]
	v_mfma_f32_16x16x32_bf16 v[78:81], v[180:183], v[204:207], v[78:81]
	v_mfma_f32_16x16x32_bf16 v[70:73], v[166:169], v[212:215], v[70:73]
	v_mfma_f32_16x16x32_bf16 v[66:69], v[180:183], v[212:215], v[66:69]
	v_mfma_f32_16x16x32_bf16 v[118:121], v[170:173], v[192:195], v[118:121]
	v_mfma_f32_16x16x32_bf16 v[110:113], v[184:187], v[192:195], v[110:113]
	v_mfma_f32_16x16x32_bf16 v[102:105], v[170:173], v[200:203], v[102:105]
	v_mfma_f32_16x16x32_bf16 v[94:97], v[184:187], v[200:203], v[94:97]
	v_mfma_f32_16x16x32_bf16 v[86:89], v[170:173], v[208:211], v[86:89]
	v_mfma_f32_16x16x32_bf16 v[78:81], v[184:187], v[208:211], v[78:81]
	v_mfma_f32_16x16x32_bf16 v[70:73], v[170:173], v[216:219], v[70:73]
	v_mfma_f32_16x16x32_bf16 v[66:69], v[184:187], v[216:219], v[66:69]
	s_setprio 0
	s_barrier
; #define PG8_STAGE(bufoff, gbase, voff) do { _Pragma("unroll") for (int _i = 0; _i < 2; ++_i) \
;         __builtin_amdgcn_global_load_lds((const unsigned*)((const char*)(gbase) + (voff)[_i]), (PG8_LAS unsigned*)(lds + (bufoff) + ldsw + _i * 8192), 16, 0, 0); } while (0)
; #define PG8_LDA(dst, b, h) do { _Pragma("unroll") for (int m = 0; m < 4; ++m) _Pragma("unroll") for (int k = 0; k < 2; ++k) dst[m][k] = *(const PG8_LAS bf16x8*)(lds + PG8_SA(b, h) + aoff + m * 2048 + k * 1024); } while (0)
; #define PG8_LDB(dst, b, h) do { _Pragma("unroll") for (int n = 0; n < 2; ++n) _Pragma("unroll") for (int k = 0; k < 2; ++k) dst[n][k] = *(const PG8_LAS bf16x8*)(lds + PG8_SB(b, h) + boff + n * 2048 + k * 1024); } while (0)
; #define PG8_MMA(ai, bj, At, Bt) do { __builtin_amdgcn_s_setprio(1); _Pragma("unroll") for (int m = 0; m < 4; ++m) _Pragma("unroll") for (int n = 0; n < 2; ++n) _Pragma("unroll") for (int k = 0; k < 2; ++k) \
;         acc[ai][bj][m][n] = __builtin_amdgcn_mfma_f32_16x16x32_bf16(Bt[n][k], At[m][k], acc[ai][bj][m][n], 0, 0, 0); __builtin_amdgcn_s_setprio(0); } while (0)
; #define PG8_WAIT_V(n) asm volatile("s_waitcnt vmcnt(" #n ")" ::: "memory")
; #define PG8_WAIT_L(n) asm volatile("s_waitcnt lgkmcnt(" #n ")" ::: "memory")
; #define PG8_BAR __builtin_amdgcn_s_barrier()
; #define PG8_SCHED __builtin_amdgcn_sched_barrier(0)
; template <class Epi, class Sched, bool ALIGN_EPI = false, bool SP2 = false>
; __device__ __forceinline__ void gemm_phase(PG8_LAS unsigned char* lds, const Gemm g, const Sched& S, const Epi& E) {
;     ...
;             PG8_LDA(At, 0, 1); PG8_STAGE(PG8_SB(0, 0), b2, voffB); PG8_STAGE(PG8_SB(0, 1), b2 + hstep, voffB); PG8_STAGE(PG8_SA(0, 0), a2, voffA);
;             PG8_WAIT_V(8); PG8_WAIT_L(0); PG8_BAR; PG8_MMA(1, 0, At, B0); PG8_MMA(1, 1, At, B1); PG8_BAR; PG8_SCHED;
;             PG8_LDB(B0, 1, 0); PG8_LDB(B1, 1, 1); PG8_SCHED; PG8_LDA(At, 1, 0); PG8_STAGE(PG8_SA(0, 1), a2 + hstep, voffA);
	s_add_i32 s49, s49, s35
	v_lshl_add_u64 v[146:147], s[26:27], 0, v[134:135]
	s_mov_b32 m0, s49
	ds_read_b128 v[188:191], v149 offset:16384
	ds_read_b128 v[192:195], v149 offset:17408
	ds_read_b128 v[196:199], v149 offset:18432
	ds_read_b128 v[200:203], v149 offset:19456
	ds_read_b128 v[204:207], v149 offset:20480
	ds_read_b128 v[208:211], v149 offset:21504
	ds_read_b128 v[212:215], v149 offset:22528
	ds_read_b128 v[216:219], v149 offset:23552
	global_load_lds_dwordx4 v[146:147], off
	s_add_i32 m0, s49, 0x2000
	s_add_u32 s50, s26, 0x40000
	v_lshl_add_u64 v[220:221], s[26:27], 0, v[130:131]
	s_addc_u32 s51, s27, 0
	s_add_i32 s49, s52, s35
	global_load_lds_dwordx4 v[220:221], off
	v_lshl_add_u64 v[222:223], s[50:51], 0, v[134:135]
	s_mov_b32 m0, s49
	v_lshl_add_u64 v[228:229], s[28:29], 0, v[132:133]
	global_load_lds_dwordx4 v[222:223], off
	v_lshl_add_u64 v[222:223], s[50:51], 0, v[130:131]
	s_add_i32 m0, s49, 0x2000
	s_nop 0
	global_load_lds_dwordx4 v[222:223], off
	v_lshl_add_u64 v[222:223], s[28:29], 0, v[136:137]
	s_mov_b32 m0, s36
	s_nop 0
	global_load_lds_dwordx4 v[222:223], off
	s_mov_b32 m0, s37
	s_nop 0
	global_load_lds_dwordx4 v[228:229], off
	s_waitcnt vmcnt(8)
	s_waitcnt lgkmcnt(0)
	s_barrier
	s_setprio 1
	s_waitcnt lgkmcnt(0)
	v_mfma_f32_16x16x32_bf16 v[62:65], v[150:153], v[188:191], v[62:65]
	v_mfma_f32_16x16x32_bf16 v[58:61], v[158:161], v[188:191], v[58:61]
	v_mfma_f32_16x16x32_bf16 v[50:53], v[150:153], v[196:199], v[50:53]
	v_mfma_f32_16x16x32_bf16 v[42:45], v[158:161], v[196:199], v[42:45]
	v_mfma_f32_16x16x32_bf16 v[34:37], v[150:153], v[204:207], v[34:37]
	v_mfma_f32_16x16x32_bf16 v[26:29], v[158:161], v[204:207], v[26:29]
	v_mfma_f32_16x16x32_bf16 v[18:21], v[150:153], v[212:215], v[18:21]
	v_mfma_f32_16x16x32_bf16 v[10:13], v[158:161], v[212:215], v[10:13]
	v_mfma_f32_16x16x32_bf16 v[62:65], v[154:157], v[192:195], v[62:65]
	v_mfma_f32_16x16x32_bf16 v[58:61], v[162:165], v[192:195], v[58:61]
	v_mfma_f32_16x16x32_bf16 v[50:53], v[154:157], v[200:203], v[50:53]
	v_mfma_f32_16x16x32_bf16 v[42:45], v[162:165], v[200:203], v[42:45]
	v_mfma_f32_16x16x32_bf16 v[34:37], v[154:157], v[208:211], v[34:37]
	v_mfma_f32_16x16x32_bf16 v[26:29], v[162:165], v[208:211], v[26:29]
	v_mfma_f32_16x16x32_bf16 v[18:21], v[154:157], v[216:219], v[18:21]
	v_mfma_f32_16x16x32_bf16 v[10:13], v[162:165], v[216:219], v[10:13]
	s_setprio 0
	s_setprio 1
	v_mfma_f32_16x16x32_bf16 v[54:57], v[166:169], v[188:191], v[54:57]
	v_mfma_f32_16x16x32_bf16 v[46:49], v[180:183], v[188:191], v[46:49]
	v_mfma_f32_16x16x32_bf16 v[38:41], v[166:169], v[196:199], v[38:41]
	v_mfma_f32_16x16x32_bf16 v[30:33], v[180:183], v[196:199], v[30:33]
	v_mfma_f32_16x16x32_bf16 v[22:25], v[166:169], v[204:207], v[22:25]
	v_mfma_f32_16x16x32_bf16 v[14:17], v[180:183], v[204:207], v[14:17]
	v_mfma_f32_16x16x32_bf16 v[6:9], v[166:169], v[212:215], v[6:9]
	v_mfma_f32_16x16x32_bf16 v[2:5], v[180:183], v[212:215], v[2:5]
	v_mfma_f32_16x16x32_bf16 v[54:57], v[170:173], v[192:195], v[54:57]
	v_mfma_f32_16x16x32_bf16 v[46:49], v[184:187], v[192:195], v[46:49]
	v_mfma_f32_16x16x32_bf16 v[38:41], v[170:173], v[200:203], v[38:41]
	v_mfma_f32_16x16x32_bf16 v[30:33], v[184:187], v[200:203], v[30:33]
	v_mfma_f32_16x16x32_bf16 v[22:25], v[170:173], v[208:211], v[22:25]
	v_mfma_f32_16x16x32_bf16 v[14:17], v[184:187], v[208:211], v[14:17]
	v_mfma_f32_16x16x32_bf16 v[6:9], v[170:173], v[216:219], v[6:9]
	v_mfma_f32_16x16x32_bf16 v[2:5], v[184:187], v[216:219], v[2:5]
	s_setprio 0
	s_barrier
	s_add_i32 s49, 0, 0x18000
	v_add_u32_e32 v142, s49, v145
	s_add_i32 s50, 0, 0x1c000
	ds_read_b128 v[150:153], v142
	ds_read_b128 v[154:157], v142 offset:1024
	ds_read_b128 v[158:161], v142 offset:2048
	ds_read_b128 v[162:165], v142 offset:3072
	v_add_u32_e32 v142, s50, v145
	ds_read_b128 v[166:169], v142
	ds_read_b128 v[170:173], v142 offset:1024
	ds_read_b128 v[180:183], v142 offset:2048
	ds_read_b128 v[184:187], v142 offset:3072
	s_add_u32 s28, s28, 0x40000
	s_addc_u32 s29, s29, 0
	s_mov_b32 m0, s38
	v_lshl_add_u64 v[230:231], s[28:29], 0, v[136:137]
	ds_read_b128 v[188:191], v149 offset:32768
	ds_read_b128 v[192:195], v149 offset:33792
	ds_read_b128 v[196:199], v149 offset:34816
	ds_read_b128 v[200:203], v149 offset:35840
	ds_read_b128 v[204:207], v149 offset:36864
	ds_read_b128 v[208:211], v149 offset:37888
	ds_read_b128 v[212:215], v149 offset:38912
	ds_read_b128 v[216:219], v149 offset:39936
	global_load_lds_dwordx4 v[230:231], off
	v_lshl_add_u64 v[230:231], s[28:29], 0, v[132:133]
	s_mov_b32 m0, s39
	s_nop 0
	global_load_lds_dwordx4 v[230:231], off
	s_waitcnt vmcnt(8)
	s_waitcnt lgkmcnt(0)
	s_barrier
; #define PG8_STAGE(bufoff, gbase, voff) do { _Pragma("unroll") for (int _i = 0; _i < 2; ++_i) \
;         __builtin_amdgcn_global_load_lds((const unsigned*)((const char*)(gbase) + (voff)[_i]), (PG8_LAS unsigned*)(lds + (bufoff) + ldsw + _i * 8192), 16, 0, 0); } while (0)
; #define PG8_LDA(dst, b, h) do { _Pragma("unroll") for (int m = 0; m < 4; ++m) _Pragma("unroll") for (int k = 0; k < 2; ++k) dst[m][k] = *(const PG8_LAS bf16x8*)(lds + PG8_SA(b, h) + aoff + m * 2048 + k * 1024); } while (0)
; #define PG8_MMA(ai, bj, At, Bt) do { __builtin_amdgcn_s_setprio(1); _Pragma("unroll") for (int m = 0; m < 4; ++m) _Pragma("unroll") for (int n = 0; n < 2; ++n) _Pragma("unroll") for (int k = 0; k < 2; ++k) \
;         acc[ai][bj][m][n] = __builtin_amdgcn_mfma_f32_16x16x32_bf16(Bt[n][k], At[m][k], acc[ai][bj][m][n], 0, 0, 0); __builtin_amdgcn_s_setprio(0); } while (0)
; #define PG8_WAIT_V(n) asm volatile("s_waitcnt vmcnt(" #n ")" ::: "memory")
; #define PG8_WAIT_L(n) asm volatile("s_waitcnt lgkmcnt(" #n ")" ::: "memory")
; #define PG8_BAR __builtin_amdgcn_s_barrier()
; #define PG8_SCHED __builtin_amdgcn_sched_barrier(0)
; template <class Epi, class Sched, bool ALIGN_EPI = false, bool SP2 = false>
; __device__ __forceinline__ void gemm_phase(PG8_LAS unsigned char* lds, const Gemm g, const Sched& S, const Epi& E) {
;     ...
;             PG8_WAIT_V(8); PG8_WAIT_L(0); PG8_BAR; PG8_MMA(0, 0, At, B0); PG8_MMA(0, 1, At, B1); PG8_BAR; PG8_SCHED;
;             PG8_LDA(At, 1, 1); PG8_STAGE(PG8_SB(1, 0), b3, voffB); PG8_STAGE(PG8_SB(1, 1), b3 + hstep, voffB); PG8_STAGE(PG8_SA(1, 0), a3, voffA);
;             PG8_WAIT_V(8); PG8_WAIT_L(0); PG8_BAR; PG8_MMA(1, 0, At, B0); PG8_MMA(1, 1, At, B1); PG8_BAR; PG8_SCHED;
	s_setprio 1
	s_waitcnt lgkmcnt(0)
	v_mfma_f32_16x16x32_bf16 v[126:129], v[150:153], v[188:191], v[126:129]
	v_mfma_f32_16x16x32_bf16 v[122:125], v[158:161], v[188:191], v[122:125]
	v_mfma_f32_16x16x32_bf16 v[114:117], v[150:153], v[196:199], v[114:117]
	v_mfma_f32_16x16x32_bf16 v[106:109], v[158:161], v[196:199], v[106:109]
	v_mfma_f32_16x16x32_bf16 v[98:101], v[150:153], v[204:207], v[98:101]
	v_mfma_f32_16x16x32_bf16 v[90:93], v[158:161], v[204:207], v[90:93]
	v_mfma_f32_16x16x32_bf16 v[82:85], v[150:153], v[212:215], v[82:85]
	v_mfma_f32_16x16x32_bf16 v[74:77], v[158:161], v[212:215], v[74:77]
	v_mfma_f32_16x16x32_bf16 v[126:129], v[154:157], v[192:195], v[126:129]
	v_mfma_f32_16x16x32_bf16 v[122:125], v[162:165], v[192:195], v[122:125]
	v_mfma_f32_16x16x32_bf16 v[114:117], v[154:157], v[200:203], v[114:117]
	v_mfma_f32_16x16x32_bf16 v[106:109], v[162:165], v[200:203], v[106:109]
	v_mfma_f32_16x16x32_bf16 v[98:101], v[154:157], v[208:211], v[98:101]
	v_mfma_f32_16x16x32_bf16 v[90:93], v[162:165], v[208:211], v[90:93]
	v_mfma_f32_16x16x32_bf16 v[82:85], v[154:157], v[216:219], v[82:85]
	v_mfma_f32_16x16x32_bf16 v[74:77], v[162:165], v[216:219], v[74:77]
	s_setprio 0
	s_setprio 1
	v_mfma_f32_16x16x32_bf16 v[118:121], v[166:169], v[188:191], v[118:121]
	v_mfma_f32_16x16x32_bf16 v[110:113], v[180:183], v[188:191], v[110:113]
	v_mfma_f32_16x16x32_bf16 v[102:105], v[166:169], v[196:199], v[102:105]
	v_mfma_f32_16x16x32_bf16 v[94:97], v[180:183], v[196:199], v[94:97]
	v_mfma_f32_16x16x32_bf16 v[86:89], v[166:169], v[204:207], v[86:89]
	v_mfma_f32_16x16x32_bf16 v[78:81], v[180:183], v[204:207], v[78:81]
	v_mfma_f32_16x16x32_bf16 v[70:73], v[166:169], v[212:215], v[70:73]
	v_mfma_f32_16x16x32_bf16 v[66:69], v[180:183], v[212:215], v[66:69]
	v_mfma_f32_16x16x32_bf16 v[118:121], v[170:173], v[192:195], v[118:121]
	v_mfma_f32_16x16x32_bf16 v[110:113], v[184:187], v[192:195], v[110:113]
	v_mfma_f32_16x16x32_bf16 v[102:105], v[170:173], v[200:203], v[102:105]
	v_mfma_f32_16x16x32_bf16 v[94:97], v[184:187], v[200:203], v[94:97]
	v_mfma_f32_16x16x32_bf16 v[86:89], v[170:173], v[208:211], v[86:89]
	v_mfma_f32_16x16x32_bf16 v[78:81], v[184:187], v[208:211], v[78:81]
	v_mfma_f32_16x16x32_bf16 v[70:73], v[170:173], v[216:219], v[70:73]
	v_mfma_f32_16x16x32_bf16 v[66:69], v[184:187], v[216:219], v[66:69]
	s_setprio 0
	s_barrier
	s_add_i32 s28, s49, s35
	v_lshl_add_u64 v[146:147], v[146:147], 0, s[96:97]
	s_mov_b32 m0, s28
	ds_read_b128 v[188:191], v149 offset:49152
	ds_read_b128 v[192:195], v149 offset:50176
	ds_read_b128 v[196:199], v149 offset:51200
	ds_read_b128 v[200:203], v149 offset:52224
	ds_read_b128 v[204:207], v149 offset:53248
	ds_read_b128 v[208:211], v149 offset:54272
	ds_read_b128 v[212:215], v149 offset:55296
	ds_read_b128 v[216:219], v149 offset:56320
	global_load_lds_dwordx4 v[146:147], off
	s_add_i32 m0, s28, 0x2000
	s_add_u32 s26, s26, 0x40080
	v_lshl_add_u64 v[146:147], v[220:221], 0, s[96:97]
	s_addc_u32 s27, s27, 0
	s_add_i32 s28, s50, s35
	global_load_lds_dwordx4 v[146:147], off
	v_lshl_add_u64 v[146:147], s[26:27], 0, v[134:135]
	s_mov_b32 m0, s28
	s_nop 0
	global_load_lds_dwordx4 v[146:147], off
	v_lshl_add_u64 v[146:147], s[26:27], 0, v[130:131]
	s_add_i32 m0, s28, 0x2000
	s_nop 0
	global_load_lds_dwordx4 v[146:147], off
	v_lshl_add_u64 v[146:147], v[222:223], 0, s[96:97]
	s_mov_b32 m0, s42
	s_nop 0
	global_load_lds_dwordx4 v[146:147], off
	v_lshl_add_u64 v[146:147], v[228:229], 0, s[96:97]
	s_mov_b32 m0, s43
	s_nop 0
	global_load_lds_dwordx4 v[146:147], off
	s_waitcnt vmcnt(8)
	s_waitcnt lgkmcnt(0)
	s_barrier
	s_setprio 1
	s_waitcnt lgkmcnt(0)
	v_mfma_f32_16x16x32_bf16 v[62:65], v[150:153], v[188:191], v[62:65]
	v_mfma_f32_16x16x32_bf16 v[58:61], v[158:161], v[188:191], v[58:61]
	v_mfma_f32_16x16x32_bf16 v[50:53], v[150:153], v[196:199], v[50:53]
	v_mfma_f32_16x16x32_bf16 v[42:45], v[158:161], v[196:199], v[42:45]
	v_mfma_f32_16x16x32_bf16 v[34:37], v[150:153], v[204:207], v[34:37]
	v_mfma_f32_16x16x32_bf16 v[26:29], v[158:161], v[204:207], v[26:29]
	v_mfma_f32_16x16x32_bf16 v[18:21], v[150:153], v[212:215], v[18:21]
	v_mfma_f32_16x16x32_bf16 v[10:13], v[158:161], v[212:215], v[10:13]
	v_mfma_f32_16x16x32_bf16 v[62:65], v[154:157], v[192:195], v[62:65]
	v_mfma_f32_16x16x32_bf16 v[58:61], v[162:165], v[192:195], v[58:61]
	v_mfma_f32_16x16x32_bf16 v[50:53], v[154:157], v[200:203], v[50:53]
	v_mfma_f32_16x16x32_bf16 v[42:45], v[162:165], v[200:203], v[42:45]
	v_mfma_f32_16x16x32_bf16 v[34:37], v[154:157], v[208:211], v[34:37]
	v_mfma_f32_16x16x32_bf16 v[26:29], v[162:165], v[208:211], v[26:29]
	v_mfma_f32_16x16x32_bf16 v[18:21], v[154:157], v[216:219], v[18:21]
	v_mfma_f32_16x16x32_bf16 v[10:13], v[162:165], v[216:219], v[10:13]
	s_setprio 0
	s_setprio 1
	v_mfma_f32_16x16x32_bf16 v[54:57], v[166:169], v[188:191], v[54:57]
	v_mfma_f32_16x16x32_bf16 v[46:49], v[180:183], v[188:191], v[46:49]
	v_mfma_f32_16x16x32_bf16 v[38:41], v[166:169], v[196:199], v[38:41]
	v_mfma_f32_16x16x32_bf16 v[30:33], v[180:183], v[196:199], v[30:33]
	v_mfma_f32_16x16x32_bf16 v[22:25], v[166:169], v[204:207], v[22:25]
	v_mfma_f32_16x16x32_bf16 v[14:17], v[180:183], v[204:207], v[14:17]
	v_mfma_f32_16x16x32_bf16 v[6:9], v[166:169], v[212:215], v[6:9]
	v_mfma_f32_16x16x32_bf16 v[2:5], v[180:183], v[212:215], v[2:5]
	v_mfma_f32_16x16x32_bf16 v[54:57], v[170:173], v[192:195], v[54:57]
	v_mfma_f32_16x16x32_bf16 v[46:49], v[184:187], v[192:195], v[46:49]
	v_mfma_f32_16x16x32_bf16 v[38:41], v[170:173], v[200:203], v[38:41]
	v_mfma_f32_16x16x32_bf16 v[30:33], v[184:187], v[200:203], v[30:33]
	v_mfma_f32_16x16x32_bf16 v[22:25], v[170:173], v[208:211], v[22:25]
	v_mfma_f32_16x16x32_bf16 v[14:17], v[184:187], v[208:211], v[14:17]
	v_mfma_f32_16x16x32_bf16 v[6:9], v[170:173], v[216:219], v[6:9]
	v_mfma_f32_16x16x32_bf16 v[2:5], v[184:187], v[216:219], v[2:5]
	s_setprio 0
	s_barrier
	s_add_i32 s48, s48, 2
	s_add_u32 s24, s24, 0x100
	s_addc_u32 s25, s25, 0
	s_add_u32 s46, s46, 0x100
	s_addc_u32 s47, s47, 0
	s_cmp_gt_u32 s48, 13
	s_cbranch_scc0 .LBB0_812
	s_and_b64 vcc, exec, s[14:15]
	s_cbranch_vccz .LBB0_815
	s_barrier

; #define PG8_STAGE(bufoff, gbase, voff) do { _Pragma("unroll") for (int _i = 0; _i < 2; ++_i) \
;         __builtin_amdgcn_global_load_lds((const unsigned*)((const char*)(gbase) + (voff)[_i]), (PG8_LAS unsigned*)(lds + (bufoff) + ldsw + _i * 8192), 16, 0, 0); } while (0)
; #define PG8_LDA(dst, b, h) do { _Pragma("unroll") for (int m = 0; m < 4; ++m) _Pragma("unroll") for (int k = 0; k < 2; ++k) dst[m][k] = *(const PG8_LAS bf16x8*)(lds + PG8_SA(b, h) + aoff + m * 2048 + k * 1024); } while (0)
; #define PG8_LDB(dst, b, h) do { _Pragma("unroll") for (int n = 0; n < 2; ++n) _Pragma("unroll") for (int k = 0; k < 2; ++k) dst[n][k] = *(const PG8_LAS bf16x8*)(lds + PG8_SB(b, h) + boff + n * 2048 + k * 1024); } while (0)
; #define PG8_SCHED __builtin_amdgcn_sched_barrier(0)
; template <class Epi, class Sched, bool ALIGN_EPI = false, bool SP2 = false>
; __device__ __forceinline__ void gemm_phase(PG8_LAS unsigned char* lds, const Gemm g, const Sched& S, const Epi& E) {
;     ...
; #pragma unroll
;     for (int a = 0; a < 2; ++a)
; #pragma unroll
;         for (int b = 0; b < 2; ++b)
; #pragma unroll
;             for (int m = 0; m < 4; ++m)
; #pragma unroll
;                 for (int n = 0; n < 2; ++n) acc[a][b][m][n] = (f32x4){0.f, 0.f, 0.f, 0.f};
;     ...
;             const char* a1 = cA + (size_t)(t + 1) * kstep;
;             const char* a2 = last ? nA : cA + (size_t)(t + 2) * kstep; const char* b2 = last ? nB : cB + (size_t)(t + 2) * kstep;
;             const char* a3 = a2 + kstep; const char* b3 = b2 + kstep;
;             if (last && has_next) S.a_ready(nxt);
;             if constexpr (SP2) {
;             PG8_LDB(B0, 0, 0); PG8_LDB(B1, 0, 1); PG8_SCHED; PG8_LDA(At, 0, 0); PG8_STAGE(PG8_SA(1, 1), a1 + hstep, voffA);
.LBB0_1074:
	s_ashr_i32 s29, s28, 31
	s_lshl_b64 s[30:31], s[28:29], 19
	s_add_u32 s30, s2, s30
	s_addc_u32 s31, s39, s31
	s_and_b64 s[34:35], s[6:7], exec
	s_cselect_b32 s5, s31, s9
	s_cselect_b32 s25, s30, s8
	s_ashr_i32 s27, s26, 31
	s_lshl_b64 s[34:35], s[26:27], 19
	s_add_u32 s34, s40, s34
	s_addc_u32 s35, s41, s35
	s_and_b64 s[36:37], s[6:7], exec
	s_cselect_b32 s27, s35, s11
	s_cselect_b32 s29, s34, s10
	s_add_u32 s8, s8, 0x40080
	s_addc_u32 s9, s9, 0
	s_add_u32 s33, s10, 0x100
	s_addc_u32 s54, s11, 0
	s_mov_b32 s55, -2
	s_waitcnt lgkmcnt(0)
.LBB0_1075:
	s_add_u32 s10, s8, 0xfffc0080
	s_addc_u32 s11, s9, -1
	s_add_i32 s56, 0, 0x10000
	s_cmp_eq_u32 s55, 12
	s_cselect_b32 s37, s5, s11
	s_cselect_b32 s36, s25, s10
	s_cselect_b32 s11, s27, s54
	s_cselect_b32 s10, s29, s33
	s_add_i32 s58, 0, 0x14000
	v_add_u32_e32 v94, s56, v203
	v_add_u32_e32 v134, s58, v203
	ds_read_b128 v[66:69], v94
	ds_read_b128 v[70:73], v94 offset:1024
	ds_read_b128 v[82:85], v94 offset:2048
	ds_read_b128 v[94:97], v94 offset:3072
	ds_read_b128 v[106:109], v134
	ds_read_b128 v[118:121], v134 offset:1024
	ds_read_b128 v[130:133], v134 offset:2048
	ds_read_b128 v[134:137], v134 offset:3072
	v_lshl_add_u64 v[200:201], s[8:9], 0, v[184:185]
	s_add_i32 m0, s43, 0xc000
	ds_read_b128 v[162:165], v204
	ds_read_b128 v[166:169], v204 offset:1024
	ds_read_b128 v[188:191], v204 offset:2048
	ds_read_b128 v[192:195], v204 offset:3072
	ds_read_b128 v[196:199], v204 offset:4096
	ds_read_b128 v[206:209], v204 offset:5120
	ds_read_b128 v[210:213], v204 offset:6144
	ds_read_b128 v[214:217], v204 offset:7168
	global_load_lds_dwordx4 v[200:201], off
	v_lshl_add_u64 v[200:201], s[8:9], 0, v[186:187]
	s_add_i32 m0, s43, 0xe000
	s_nop 0
	global_load_lds_dwordx4 v[200:201], off
	s_cmp_lg_u32 s55, -2
	s_cbranch_scc1 .Levout_noz
	v_mov_b32_e32 v2, 0
	v_mov_b32_e32 v3, v2
	v_mov_b32_e32 v4, v2
	v_mov_b32_e32 v5, v2
	v_mov_b32_e32 v6, v2
	v_mov_b32_e32 v7, v2
	v_mov_b32_e32 v8, v2
	v_mov_b32_e32 v9, v2
	v_mov_b32_e32 v18, v2
	v_mov_b32_e32 v19, v2
	v_mov_b32_e32 v20, v2
	v_mov_b32_e32 v21, v2
	v_mov_b32_e32 v22, v2
	v_mov_b32_e32 v23, v2
	v_mov_b32_e32 v24, v2
	v_mov_b32_e32 v25, v2
	v_mov_b32_e32 v34, v2
	v_mov_b32_e32 v35, v2
	v_mov_b32_e32 v36, v2
	v_mov_b32_e32 v37, v2
	v_mov_b32_e32 v38, v2
	v_mov_b32_e32 v39, v2
	v_mov_b32_e32 v40, v2
	v_mov_b32_e32 v41, v2
	v_mov_b32_e32 v50, v2
	v_mov_b32_e32 v51, v2
	v_mov_b32_e32 v52, v2
	v_mov_b32_e32 v53, v2
	v_mov_b32_e32 v54, v2
	v_mov_b32_e32 v55, v2
	v_mov_b32_e32 v56, v2
	v_mov_b32_e32 v57, v2
	v_mov_b32_e32 v10, v2
	v_mov_b32_e32 v11, v2
	v_mov_b32_e32 v12, v2
	v_mov_b32_e32 v13, v2
	v_mov_b32_e32 v14, v2
	v_mov_b32_e32 v15, v2
	v_mov_b32_e32 v16, v2
	v_mov_b32_e32 v17, v2
	v_mov_b32_e32 v26, v2
	v_mov_b32_e32 v27, v2
	v_mov_b32_e32 v28, v2
	v_mov_b32_e32 v29, v2
	v_mov_b32_e32 v30, v2
	v_mov_b32_e32 v31, v2
	v_mov_b32_e32 v32, v2
	v_mov_b32_e32 v33, v2
	v_mov_b32_e32 v42, v2
	v_mov_b32_e32 v43, v2
	v_mov_b32_e32 v44, v2
	v_mov_b32_e32 v45, v2
	v_mov_b32_e32 v46, v2
	v_mov_b32_e32 v47, v2
	v_mov_b32_e32 v48, v2
	v_mov_b32_e32 v49, v2
	v_mov_b32_e32 v58, v2
	v_mov_b32_e32 v59, v2
	v_mov_b32_e32 v60, v2
	v_mov_b32_e32 v61, v2
	v_mov_b32_e32 v62, v2
	v_mov_b32_e32 v63, v2
	v_mov_b32_e32 v64, v2
	v_mov_b32_e32 v65, v2
	v_mov_b32_e32 v74, v2
	v_mov_b32_e32 v75, v2
	v_mov_b32_e32 v76, v2
	v_mov_b32_e32 v77, v2
	v_mov_b32_e32 v78, v2
	v_mov_b32_e32 v79, v2
	v_mov_b32_e32 v80, v2
	v_mov_b32_e32 v81, v2
	v_mov_b32_e32 v98, v2
	v_mov_b32_e32 v99, v2
	v_mov_b32_e32 v100, v2
	v_mov_b32_e32 v101, v2
	v_mov_b32_e32 v102, v2
	v_mov_b32_e32 v103, v2
	v_mov_b32_e32 v104, v2
	v_mov_b32_e32 v105, v2
	v_mov_b32_e32 v122, v2
	v_mov_b32_e32 v123, v2
	v_mov_b32_e32 v124, v2
	v_mov_b32_e32 v125, v2
	v_mov_b32_e32 v126, v2
	v_mov_b32_e32 v127, v2
	v_mov_b32_e32 v128, v2
	v_mov_b32_e32 v129, v2
	v_mov_b32_e32 v146, v2
	v_mov_b32_e32 v147, v2
	v_mov_b32_e32 v148, v2
	v_mov_b32_e32 v149, v2
	v_mov_b32_e32 v150, v2
	v_mov_b32_e32 v151, v2
	v_mov_b32_e32 v152, v2
	v_mov_b32_e32 v153, v2
	v_mov_b32_e32 v86, v2
	v_mov_b32_e32 v87, v2
	v_mov_b32_e32 v88, v2
	v_mov_b32_e32 v89, v2
	v_mov_b32_e32 v90, v2
	v_mov_b32_e32 v91, v2
	v_mov_b32_e32 v92, v2
	v_mov_b32_e32 v93, v2
	v_mov_b32_e32 v110, v2
	v_mov_b32_e32 v111, v2
	v_mov_b32_e32 v112, v2
	v_mov_b32_e32 v113, v2
	v_mov_b32_e32 v114, v2
	v_mov_b32_e32 v115, v2
	v_mov_b32_e32 v116, v2
	v_mov_b32_e32 v117, v2
	v_mov_b32_e32 v138, v2
	v_mov_b32_e32 v139, v2
	v_mov_b32_e32 v140, v2
	v_mov_b32_e32 v141, v2
	v_mov_b32_e32 v142, v2
	v_mov_b32_e32 v143, v2
	v_mov_b32_e32 v144, v2
	v_mov_b32_e32 v145, v2
	v_mov_b32_e32 v154, v2
	v_mov_b32_e32 v155, v2
	v_mov_b32_e32 v156, v2
	v_mov_b32_e32 v157, v2
	v_mov_b32_e32 v158, v2
	v_mov_b32_e32 v159, v2
	v_mov_b32_e32 v160, v2
	v_mov_b32_e32 v161, v2
; #define PG8_STAGE(bufoff, gbase, voff) do { _Pragma("unroll") for (int _i = 0; _i < 2; ++_i) \
;         __builtin_amdgcn_global_load_lds((const unsigned*)((const char*)(gbase) + (voff)[_i]), (PG8_LAS unsigned*)(lds + (bufoff) + ldsw + _i * 8192), 16, 0, 0); } while (0)
; #define PG8_LDA(dst, b, h) do { _Pragma("unroll") for (int m = 0; m < 4; ++m) _Pragma("unroll") for (int k = 0; k < 2; ++k) dst[m][k] = *(const PG8_LAS bf16x8*)(lds + PG8_SA(b, h) + aoff + m * 2048 + k * 1024); } while (0)
; #define PG8_LDB(dst, b, h) do { _Pragma("unroll") for (int n = 0; n < 2; ++n) _Pragma("unroll") for (int k = 0; k < 2; ++k) dst[n][k] = *(const PG8_LAS bf16x8*)(lds + PG8_SB(b, h) + boff + n * 2048 + k * 1024); } while (0)
; #define PG8_MMA(ai, bj, At, Bt) do { __builtin_amdgcn_s_setprio(1); _Pragma("unroll") for (int m = 0; m < 4; ++m) _Pragma("unroll") for (int n = 0; n < 2; ++n) _Pragma("unroll") for (int k = 0; k < 2; ++k) \
;         acc[ai][bj][m][n] = __builtin_amdgcn_mfma_f32_16x16x32_bf16(Bt[n][k], At[m][k], acc[ai][bj][m][n], 0, 0, 0); __builtin_amdgcn_s_setprio(0); } while (0)
; #define PG8_WAIT_V(n) asm volatile("s_waitcnt vmcnt(" #n ")" ::: "memory")
; #define PG8_WAIT_L(n) asm volatile("s_waitcnt lgkmcnt(" #n ")" ::: "memory")
; #define PG8_BAR __builtin_amdgcn_s_barrier()
; #define PG8_SCHED __builtin_amdgcn_sched_barrier(0)
; template <class Epi, class Sched, bool ALIGN_EPI = false, bool SP2 = false>
; __device__ __forceinline__ void gemm_phase(PG8_LAS unsigned char* lds, const Gemm g, const Sched& S, const Epi& E) {
;     ...
;             PG8_LDB(B0, 0, 0); PG8_LDB(B1, 0, 1); PG8_SCHED; PG8_LDA(At, 0, 0); PG8_STAGE(PG8_SA(1, 1), a1 + hstep, voffA);
;             PG8_WAIT_V(8); PG8_WAIT_L(0); PG8_BAR; PG8_MMA(0, 0, At, B0); PG8_MMA(0, 1, At, B1); PG8_BAR; PG8_SCHED;
;             PG8_LDA(At, 0, 1); PG8_STAGE(PG8_SB(0, 0), b2, voffB); PG8_STAGE(PG8_SB(0, 1), b2 + hstep, voffB); PG8_STAGE(PG8_SA(0, 0), a2, voffA);
;             PG8_WAIT_V(8); PG8_WAIT_L(0); PG8_BAR; PG8_MMA(1, 0, At, B0); PG8_MMA(1, 1, At, B1); PG8_BAR; PG8_SCHED;
.Levout_noz:
	s_waitcnt vmcnt(8)
	s_waitcnt lgkmcnt(0)
	s_barrier
	s_setprio 1
	s_waitcnt lgkmcnt(0)
	v_mfma_f32_16x16x32_bf16 v[158:161], v[66:69], v[162:165], v[158:161]
	v_mfma_f32_16x16x32_bf16 v[154:157], v[82:85], v[162:165], v[154:157]
	v_mfma_f32_16x16x32_bf16 v[142:145], v[66:69], v[188:191], v[142:145]
	v_mfma_f32_16x16x32_bf16 v[138:141], v[82:85], v[188:191], v[138:141]
	v_mfma_f32_16x16x32_bf16 v[114:117], v[66:69], v[196:199], v[114:117]
	v_mfma_f32_16x16x32_bf16 v[110:113], v[82:85], v[196:199], v[110:113]
	v_mfma_f32_16x16x32_bf16 v[90:93], v[66:69], v[210:213], v[90:93]
	v_mfma_f32_16x16x32_bf16 v[86:89], v[82:85], v[210:213], v[86:89]
	v_mfma_f32_16x16x32_bf16 v[158:161], v[70:73], v[166:169], v[158:161]
	v_mfma_f32_16x16x32_bf16 v[154:157], v[94:97], v[166:169], v[154:157]
	v_mfma_f32_16x16x32_bf16 v[142:145], v[70:73], v[192:195], v[142:145]
	v_mfma_f32_16x16x32_bf16 v[138:141], v[94:97], v[192:195], v[138:141]
	v_mfma_f32_16x16x32_bf16 v[114:117], v[70:73], v[206:209], v[114:117]
	v_mfma_f32_16x16x32_bf16 v[110:113], v[94:97], v[206:209], v[110:113]
	v_mfma_f32_16x16x32_bf16 v[90:93], v[70:73], v[214:217], v[90:93]
	v_mfma_f32_16x16x32_bf16 v[86:89], v[94:97], v[214:217], v[86:89]
	s_setprio 0
	s_setprio 1
	v_mfma_f32_16x16x32_bf16 v[150:153], v[106:109], v[162:165], v[150:153]
	v_mfma_f32_16x16x32_bf16 v[146:149], v[130:133], v[162:165], v[146:149]
	v_mfma_f32_16x16x32_bf16 v[126:129], v[106:109], v[188:191], v[126:129]
	v_mfma_f32_16x16x32_bf16 v[122:125], v[130:133], v[188:191], v[122:125]
	v_mfma_f32_16x16x32_bf16 v[102:105], v[106:109], v[196:199], v[102:105]
	v_mfma_f32_16x16x32_bf16 v[98:101], v[130:133], v[196:199], v[98:101]
	v_mfma_f32_16x16x32_bf16 v[78:81], v[106:109], v[210:213], v[78:81]
	v_mfma_f32_16x16x32_bf16 v[74:77], v[130:133], v[210:213], v[74:77]
	v_mfma_f32_16x16x32_bf16 v[150:153], v[118:121], v[166:169], v[150:153]
	v_mfma_f32_16x16x32_bf16 v[146:149], v[134:137], v[166:169], v[146:149]
	v_mfma_f32_16x16x32_bf16 v[126:129], v[118:121], v[192:195], v[126:129]
	v_mfma_f32_16x16x32_bf16 v[122:125], v[134:137], v[192:195], v[122:125]
	v_mfma_f32_16x16x32_bf16 v[102:105], v[118:121], v[206:209], v[102:105]
	v_mfma_f32_16x16x32_bf16 v[98:101], v[134:137], v[206:209], v[98:101]
	v_mfma_f32_16x16x32_bf16 v[78:81], v[118:121], v[214:217], v[78:81]
	v_mfma_f32_16x16x32_bf16 v[74:77], v[134:137], v[214:217], v[74:77]
	s_setprio 0
	s_barrier
	s_add_i32 s56, s56, s42
	v_lshl_add_u64 v[200:201], s[10:11], 0, v[180:181]
	s_mov_b32 m0, s56
	ds_read_b128 v[162:165], v204 offset:16384
	ds_read_b128 v[166:169], v204 offset:17408
	ds_read_b128 v[188:191], v204 offset:18432
	ds_read_b128 v[192:195], v204 offset:19456
	ds_read_b128 v[196:199], v204 offset:20480
	ds_read_b128 v[206:209], v204 offset:21504
	ds_read_b128 v[210:213], v204 offset:22528
	ds_read_b128 v[214:217], v204 offset:23552
	global_load_lds_dwordx4 v[200:201], off
	s_add_i32 m0, s56, 0x2000
	s_add_u32 s56, s10, 0x40000
	v_lshl_add_u64 v[218:219], s[10:11], 0, v[170:171]
	s_addc_u32 s57, s11, 0
	s_add_i32 s58, s58, s42
	global_load_lds_dwordx4 v[218:219], off
	v_lshl_add_u64 v[220:221], s[56:57], 0, v[180:181]
	s_mov_b32 m0, s58
	v_lshl_add_u64 v[222:223], s[36:37], 0, v[172:173]
	global_load_lds_dwordx4 v[220:221], off
	v_lshl_add_u64 v[220:221], s[56:57], 0, v[170:171]
	s_add_i32 m0, s58, 0x2000
	s_nop 0
	global_load_lds_dwordx4 v[220:221], off
	v_lshl_add_u64 v[220:221], s[36:37], 0, v[182:183]
	s_mov_b32 m0, s43
	s_nop 0
	global_load_lds_dwordx4 v[220:221], off
	s_mov_b32 m0, s44
	s_nop 0
	global_load_lds_dwordx4 v[222:223], off
	s_waitcnt vmcnt(8)
	s_waitcnt lgkmcnt(0)
	s_barrier
	s_setprio 1
	s_waitcnt lgkmcnt(0)
	v_mfma_f32_16x16x32_bf16 v[62:65], v[66:69], v[162:165], v[62:65]
	v_mfma_f32_16x16x32_bf16 v[58:61], v[82:85], v[162:165], v[58:61]
	v_mfma_f32_16x16x32_bf16 v[46:49], v[66:69], v[188:191], v[46:49]
	v_mfma_f32_16x16x32_bf16 v[42:45], v[82:85], v[188:191], v[42:45]
	v_mfma_f32_16x16x32_bf16 v[30:33], v[66:69], v[196:199], v[30:33]
	v_mfma_f32_16x16x32_bf16 v[26:29], v[82:85], v[196:199], v[26:29]
	v_mfma_f32_16x16x32_bf16 v[14:17], v[66:69], v[210:213], v[14:17]
	v_mfma_f32_16x16x32_bf16 v[10:13], v[82:85], v[210:213], v[10:13]
	v_mfma_f32_16x16x32_bf16 v[62:65], v[70:73], v[166:169], v[62:65]
	v_mfma_f32_16x16x32_bf16 v[58:61], v[94:97], v[166:169], v[58:61]
	v_mfma_f32_16x16x32_bf16 v[46:49], v[70:73], v[192:195], v[46:49]
	v_mfma_f32_16x16x32_bf16 v[42:45], v[94:97], v[192:195], v[42:45]
	v_mfma_f32_16x16x32_bf16 v[30:33], v[70:73], v[206:209], v[30:33]
	v_mfma_f32_16x16x32_bf16 v[26:29], v[94:97], v[206:209], v[26:29]
	v_mfma_f32_16x16x32_bf16 v[14:17], v[70:73], v[214:217], v[14:17]
	v_mfma_f32_16x16x32_bf16 v[10:13], v[94:97], v[214:217], v[10:13]
	s_setprio 0
	s_setprio 1
	v_mfma_f32_16x16x32_bf16 v[54:57], v[106:109], v[162:165], v[54:57]
	v_mfma_f32_16x16x32_bf16 v[50:53], v[130:133], v[162:165], v[50:53]
	v_mfma_f32_16x16x32_bf16 v[38:41], v[106:109], v[188:191], v[38:41]
	v_mfma_f32_16x16x32_bf16 v[34:37], v[130:133], v[188:191], v[34:37]
	v_mfma_f32_16x16x32_bf16 v[22:25], v[106:109], v[196:199], v[22:25]
	v_mfma_f32_16x16x32_bf16 v[18:21], v[130:133], v[196:199], v[18:21]
	v_mfma_f32_16x16x32_bf16 v[6:9], v[106:109], v[210:213], v[6:9]
	v_mfma_f32_16x16x32_bf16 v[2:5], v[130:133], v[210:213], v[2:5]
	v_mfma_f32_16x16x32_bf16 v[54:57], v[118:121], v[166:169], v[54:57]
	v_mfma_f32_16x16x32_bf16 v[50:53], v[134:137], v[166:169], v[50:53]
	v_mfma_f32_16x16x32_bf16 v[38:41], v[118:121], v[192:195], v[38:41]
	v_mfma_f32_16x16x32_bf16 v[34:37], v[134:137], v[192:195], v[34:37]
	v_mfma_f32_16x16x32_bf16 v[22:25], v[118:121], v[206:209], v[22:25]
	v_mfma_f32_16x16x32_bf16 v[18:21], v[134:137], v[206:209], v[18:21]
	v_mfma_f32_16x16x32_bf16 v[6:9], v[118:121], v[214:217], v[6:9]
	v_mfma_f32_16x16x32_bf16 v[2:5], v[134:137], v[214:217], v[2:5]
	s_setprio 0
	s_barrier
; #define PG8_STAGE(bufoff, gbase, voff) do { _Pragma("unroll") for (int _i = 0; _i < 2; ++_i) \
;         __builtin_amdgcn_global_load_lds((const unsigned*)((const char*)(gbase) + (voff)[_i]), (PG8_LAS unsigned*)(lds + (bufoff) + ldsw + _i * 8192), 16, 0, 0); } while (0)
; #define PG8_LDA(dst, b, h) do { _Pragma("unroll") for (int m = 0; m < 4; ++m) _Pragma("unroll") for (int k = 0; k < 2; ++k) dst[m][k] = *(const PG8_LAS bf16x8*)(lds + PG8_SA(b, h) + aoff + m * 2048 + k * 1024); } while (0)
; #define PG8_LDB(dst, b, h) do { _Pragma("unroll") for (int n = 0; n < 2; ++n) _Pragma("unroll") for (int k = 0; k < 2; ++k) dst[n][k] = *(const PG8_LAS bf16x8*)(lds + PG8_SB(b, h) + boff + n * 2048 + k * 1024); } while (0)
; #define PG8_MMA(ai, bj, At, Bt) do { __builtin_amdgcn_s_setprio(1); _Pragma("unroll") for (int m = 0; m < 4; ++m) _Pragma("unroll") for (int n = 0; n < 2; ++n) _Pragma("unroll") for (int k = 0; k < 2; ++k) \
;         acc[ai][bj][m][n] = __builtin_amdgcn_mfma_f32_16x16x32_bf16(Bt[n][k], At[m][k], acc[ai][bj][m][n], 0, 0, 0); __builtin_amdgcn_s_setprio(0); } while (0)
; #define PG8_WAIT_V(n) asm volatile("s_waitcnt vmcnt(" #n ")" ::: "memory")
; #define PG8_WAIT_L(n) asm volatile("s_waitcnt lgkmcnt(" #n ")" ::: "memory")
; #define PG8_BAR __builtin_amdgcn_s_barrier()
; #define PG8_SCHED __builtin_amdgcn_sched_barrier(0)
; template <class Epi, class Sched, bool ALIGN_EPI = false, bool SP2 = false>
; __device__ __forceinline__ void gemm_phase(PG8_LAS unsigned char* lds, const Gemm g, const Sched& S, const Epi& E) {
;     ...
;             PG8_LDB(B0, 1, 0); PG8_LDB(B1, 1, 1); PG8_SCHED; PG8_LDA(At, 1, 0); PG8_STAGE(PG8_SA(0, 1), a2 + hstep, voffA);
;             PG8_WAIT_V(8); PG8_WAIT_L(0); PG8_BAR; PG8_MMA(0, 0, At, B0); PG8_MMA(0, 1, At, B1); PG8_BAR; PG8_SCHED;
	s_add_i32 s56, 0, 0x18000
	s_add_i32 s57, 0, 0x1c000
	v_add_u32_e32 v94, s56, v203
	v_add_u32_e32 v134, s57, v203
	ds_read_b128 v[66:69], v94
	ds_read_b128 v[70:73], v94 offset:1024
	ds_read_b128 v[82:85], v94 offset:2048
	ds_read_b128 v[94:97], v94 offset:3072
	ds_read_b128 v[106:109], v134
	ds_read_b128 v[118:121], v134 offset:1024
	ds_read_b128 v[130:133], v134 offset:2048
	ds_read_b128 v[134:137], v134 offset:3072
	s_add_u32 s36, s36, 0x40000
	s_addc_u32 s37, s37, 0
	s_mov_b32 m0, s45
	v_lshl_add_u64 v[228:229], s[36:37], 0, v[182:183]
	ds_read_b128 v[162:165], v204 offset:32768
	ds_read_b128 v[166:169], v204 offset:33792
	ds_read_b128 v[188:191], v204 offset:34816
	ds_read_b128 v[192:195], v204 offset:35840
	ds_read_b128 v[196:199], v204 offset:36864
	ds_read_b128 v[206:209], v204 offset:37888
	ds_read_b128 v[210:213], v204 offset:38912
	ds_read_b128 v[214:217], v204 offset:39936
	global_load_lds_dwordx4 v[228:229], off
	v_lshl_add_u64 v[228:229], s[36:37], 0, v[172:173]
	s_mov_b32 m0, s46
	s_nop 0
	global_load_lds_dwordx4 v[228:229], off
	s_waitcnt vmcnt(8)
	s_waitcnt lgkmcnt(0)
	s_barrier
	s_setprio 1
	s_waitcnt lgkmcnt(0)
	v_mfma_f32_16x16x32_bf16 v[158:161], v[66:69], v[162:165], v[158:161]
	v_mfma_f32_16x16x32_bf16 v[154:157], v[82:85], v[162:165], v[154:157]
	v_mfma_f32_16x16x32_bf16 v[142:145], v[66:69], v[188:191], v[142:145]
	v_mfma_f32_16x16x32_bf16 v[138:141], v[82:85], v[188:191], v[138:141]
	v_mfma_f32_16x16x32_bf16 v[114:117], v[66:69], v[196:199], v[114:117]
	v_mfma_f32_16x16x32_bf16 v[110:113], v[82:85], v[196:199], v[110:113]
	v_mfma_f32_16x16x32_bf16 v[90:93], v[66:69], v[210:213], v[90:93]
	v_mfma_f32_16x16x32_bf16 v[86:89], v[82:85], v[210:213], v[86:89]
	v_mfma_f32_16x16x32_bf16 v[158:161], v[70:73], v[166:169], v[158:161]
	v_mfma_f32_16x16x32_bf16 v[154:157], v[94:97], v[166:169], v[154:157]
	v_mfma_f32_16x16x32_bf16 v[142:145], v[70:73], v[192:195], v[142:145]
	v_mfma_f32_16x16x32_bf16 v[138:141], v[94:97], v[192:195], v[138:141]
	v_mfma_f32_16x16x32_bf16 v[114:117], v[70:73], v[206:209], v[114:117]
	v_mfma_f32_16x16x32_bf16 v[110:113], v[94:97], v[206:209], v[110:113]
	v_mfma_f32_16x16x32_bf16 v[90:93], v[70:73], v[214:217], v[90:93]
	v_mfma_f32_16x16x32_bf16 v[86:89], v[94:97], v[214:217], v[86:89]
	s_setprio 0
	s_setprio 1
	v_mfma_f32_16x16x32_bf16 v[150:153], v[106:109], v[162:165], v[150:153]
	v_mfma_f32_16x16x32_bf16 v[146:149], v[130:133], v[162:165], v[146:149]
	v_mfma_f32_16x16x32_bf16 v[126:129], v[106:109], v[188:191], v[126:129]
	v_mfma_f32_16x16x32_bf16 v[122:125], v[130:133], v[188:191], v[122:125]
	v_mfma_f32_16x16x32_bf16 v[102:105], v[106:109], v[196:199], v[102:105]
	v_mfma_f32_16x16x32_bf16 v[98:101], v[130:133], v[196:199], v[98:101]
	v_mfma_f32_16x16x32_bf16 v[78:81], v[106:109], v[210:213], v[78:81]
	v_mfma_f32_16x16x32_bf16 v[74:77], v[130:133], v[210:213], v[74:77]
	v_mfma_f32_16x16x32_bf16 v[150:153], v[118:121], v[166:169], v[150:153]
	v_mfma_f32_16x16x32_bf16 v[146:149], v[134:137], v[166:169], v[146:149]
	v_mfma_f32_16x16x32_bf16 v[126:129], v[118:121], v[192:195], v[126:129]
	v_mfma_f32_16x16x32_bf16 v[122:125], v[134:137], v[192:195], v[122:125]
	v_mfma_f32_16x16x32_bf16 v[102:105], v[118:121], v[206:209], v[102:105]
	v_mfma_f32_16x16x32_bf16 v[98:101], v[134:137], v[206:209], v[98:101]
	v_mfma_f32_16x16x32_bf16 v[78:81], v[118:121], v[214:217], v[78:81]
	v_mfma_f32_16x16x32_bf16 v[74:77], v[134:137], v[214:217], v[74:77]
	s_setprio 0
	s_barrier
; #define PG8_STAGE(bufoff, gbase, voff) do { _Pragma("unroll") for (int _i = 0; _i < 2; ++_i) \
;         __builtin_amdgcn_global_load_lds((const unsigned*)((const char*)(gbase) + (voff)[_i]), (PG8_LAS unsigned*)(lds + (bufoff) + ldsw + _i * 8192), 16, 0, 0); } while (0)
; #define PG8_LDA(dst, b, h) do { _Pragma("unroll") for (int m = 0; m < 4; ++m) _Pragma("unroll") for (int k = 0; k < 2; ++k) dst[m][k] = *(const PG8_LAS bf16x8*)(lds + PG8_SA(b, h) + aoff + m * 2048 + k * 1024); } while (0)
; #define PG8_MMA(ai, bj, At, Bt) do { __builtin_amdgcn_s_setprio(1); _Pragma("unroll") for (int m = 0; m < 4; ++m) _Pragma("unroll") for (int n = 0; n < 2; ++n) _Pragma("unroll") for (int k = 0; k < 2; ++k) \
;         acc[ai][bj][m][n] = __builtin_amdgcn_mfma_f32_16x16x32_bf16(Bt[n][k], At[m][k], acc[ai][bj][m][n], 0, 0, 0); __builtin_amdgcn_s_setprio(0); } while (0)
; #define PG8_WAIT_V(n) asm volatile("s_waitcnt vmcnt(" #n ")" ::: "memory")
; #define PG8_WAIT_L(n) asm volatile("s_waitcnt lgkmcnt(" #n ")" ::: "memory")
; #define PG8_BAR __builtin_amdgcn_s_barrier()
; #define PG8_SCHED __builtin_amdgcn_sched_barrier(0)
; template <class Epi, class Sched, bool ALIGN_EPI = false, bool SP2 = false>
; __device__ __forceinline__ void gemm_phase(PG8_LAS unsigned char* lds, const Gemm g, const Sched& S, const Epi& E) {
;     ...
;             PG8_WAIT_V(8); PG8_WAIT_L(0); PG8_BAR; PG8_MMA(0, 0, At, B0); PG8_MMA(0, 1, At, B1); PG8_BAR; PG8_SCHED;
;             PG8_LDA(At, 1, 1); PG8_STAGE(PG8_SB(1, 0), b3, voffB); PG8_STAGE(PG8_SB(1, 1), b3 + hstep, voffB); PG8_STAGE(PG8_SA(1, 0), a3, voffA);
;             PG8_WAIT_V(8); PG8_WAIT_L(0); PG8_BAR; PG8_MMA(1, 0, At, B0); PG8_MMA(1, 1, At, B1); PG8_BAR; PG8_SCHED;
	s_add_i32 s36, s56, s42
	v_lshl_add_u64 v[200:201], v[200:201], 0, s[96:97]
	s_mov_b32 m0, s36
	ds_read_b128 v[162:165], v204 offset:49152
	ds_read_b128 v[166:169], v204 offset:50176
	ds_read_b128 v[188:191], v204 offset:51200
	ds_read_b128 v[192:195], v204 offset:52224
	ds_read_b128 v[196:199], v204 offset:53248
	ds_read_b128 v[206:209], v204 offset:54272
	ds_read_b128 v[210:213], v204 offset:55296
	ds_read_b128 v[214:217], v204 offset:56320
	global_load_lds_dwordx4 v[200:201], off
	s_add_i32 m0, s36, 0x2000
	s_add_u32 s10, s10, 0x40080
	v_lshl_add_u64 v[200:201], v[218:219], 0, s[96:97]
	s_addc_u32 s11, s11, 0
	s_add_i32 s36, s57, s42
	global_load_lds_dwordx4 v[200:201], off
	v_lshl_add_u64 v[200:201], s[10:11], 0, v[180:181]
	s_mov_b32 m0, s36
	s_nop 0
	global_load_lds_dwordx4 v[200:201], off
	v_lshl_add_u64 v[200:201], s[10:11], 0, v[170:171]
	s_add_i32 m0, s36, 0x2000
	s_nop 0
	global_load_lds_dwordx4 v[200:201], off
	v_lshl_add_u64 v[200:201], v[220:221], 0, s[96:97]
	s_mov_b32 m0, s50
	s_nop 0
	global_load_lds_dwordx4 v[200:201], off
	v_lshl_add_u64 v[200:201], v[222:223], 0, s[96:97]
	s_mov_b32 m0, s51
	s_nop 0
	global_load_lds_dwordx4 v[200:201], off
	s_waitcnt vmcnt(8)
	s_waitcnt lgkmcnt(0)
	s_barrier
	s_setprio 1
	s_waitcnt lgkmcnt(0)
	v_mfma_f32_16x16x32_bf16 v[62:65], v[66:69], v[162:165], v[62:65]
	v_mfma_f32_16x16x32_bf16 v[58:61], v[82:85], v[162:165], v[58:61]
	v_mfma_f32_16x16x32_bf16 v[46:49], v[66:69], v[188:191], v[46:49]
	v_mfma_f32_16x16x32_bf16 v[42:45], v[82:85], v[188:191], v[42:45]
	v_mfma_f32_16x16x32_bf16 v[30:33], v[66:69], v[196:199], v[30:33]
	v_mfma_f32_16x16x32_bf16 v[26:29], v[82:85], v[196:199], v[26:29]
	v_mfma_f32_16x16x32_bf16 v[14:17], v[66:69], v[210:213], v[14:17]
	v_mfma_f32_16x16x32_bf16 v[10:13], v[82:85], v[210:213], v[10:13]
	v_mfma_f32_16x16x32_bf16 v[62:65], v[70:73], v[166:169], v[62:65]
	v_mfma_f32_16x16x32_bf16 v[58:61], v[94:97], v[166:169], v[58:61]
	v_mfma_f32_16x16x32_bf16 v[46:49], v[70:73], v[192:195], v[46:49]
	v_mfma_f32_16x16x32_bf16 v[42:45], v[94:97], v[192:195], v[42:45]
	v_mfma_f32_16x16x32_bf16 v[30:33], v[70:73], v[206:209], v[30:33]
	v_mfma_f32_16x16x32_bf16 v[26:29], v[94:97], v[206:209], v[26:29]
	v_mfma_f32_16x16x32_bf16 v[14:17], v[70:73], v[214:217], v[14:17]
	v_mfma_f32_16x16x32_bf16 v[10:13], v[94:97], v[214:217], v[10:13]
	s_setprio 0
	s_setprio 1
	v_mfma_f32_16x16x32_bf16 v[54:57], v[106:109], v[162:165], v[54:57]
	v_mfma_f32_16x16x32_bf16 v[50:53], v[130:133], v[162:165], v[50:53]
	v_mfma_f32_16x16x32_bf16 v[38:41], v[106:109], v[188:191], v[38:41]
	v_mfma_f32_16x16x32_bf16 v[34:37], v[130:133], v[188:191], v[34:37]
	v_mfma_f32_16x16x32_bf16 v[22:25], v[106:109], v[196:199], v[22:25]
	v_mfma_f32_16x16x32_bf16 v[18:21], v[130:133], v[196:199], v[18:21]
	v_mfma_f32_16x16x32_bf16 v[6:9], v[106:109], v[210:213], v[6:9]
	v_mfma_f32_16x16x32_bf16 v[2:5], v[130:133], v[210:213], v[2:5]
	v_mfma_f32_16x16x32_bf16 v[54:57], v[118:121], v[166:169], v[54:57]
	v_mfma_f32_16x16x32_bf16 v[50:53], v[134:137], v[166:169], v[50:53]
	v_mfma_f32_16x16x32_bf16 v[38:41], v[118:121], v[192:195], v[38:41]
	v_mfma_f32_16x16x32_bf16 v[34:37], v[134:137], v[192:195], v[34:37]
	v_mfma_f32_16x16x32_bf16 v[22:25], v[118:121], v[206:209], v[22:25]
	v_mfma_f32_16x16x32_bf16 v[18:21], v[134:137], v[206:209], v[18:21]
	v_mfma_f32_16x16x32_bf16 v[6:9], v[118:121], v[214:217], v[6:9]
	v_mfma_f32_16x16x32_bf16 v[2:5], v[134:137], v[214:217], v[2:5]
	s_setprio 0
	s_barrier
	s_add_i32 s55, s55, 2
	s_add_u32 s8, s8, 0x100
	s_addc_u32 s9, s9, 0
	s_add_u32 s33, s33, 0x100
	s_addc_u32 s54, s54, 0
	s_cmp_gt_u32 s55, 13
	s_cbranch_scc0 .LBB0_1075
	s_and_b64 vcc, exec, s[20:21]
	s_cbranch_vccz .LBB0_1078
	s_barrier

; template <class Epi, class Sched, bool ALIGN_EPI = false, bool SP2 = false>
; __device__ __forceinline__ void gemm_phase(PG8_LAS unsigned char* lds, const Gemm g, const Sched& S, const Epi& E) {
;     ...
;         const bool has_next = S.next(ui + 1, nxt);
;         const char* nA = has_next ? (const char*)g.A + (size_t)nxt.pm * tstep : cA; const char* nB = has_next ? (const char*)g.Bt + (size_t)nxt.pn * tstep : cB;
;         for (int t = 0; t < nt; t += 2) {
;             const bool last = (t == nt - 2);
;             const char* a1 = cA + (size_t)(t + 1) * kstep;
;             const char* a2 = last ? nA : cA + (size_t)(t + 2) * kstep; const char* b2 = last ? nB : cB + (size_t)(t + 2) * kstep;
;             const char* a3 = a2 + kstep; const char* b3 = b2 + kstep;
.LBB0_1246:
	s_ashr_i32 s37, s36, 31
	s_lshl_b64 s[8:9], s[36:37], 19
	s_add_u32 s38, s2, s8
	s_addc_u32 s39, s49, s9
	s_and_b64 s[8:9], s[6:7], exec
	s_cselect_b32 s37, s39, s47
	s_cselect_b32 s43, s38, s46
	s_ashr_i32 s35, s34, 31
	s_lshl_b64 s[8:9], s[34:35], 19
	s_add_u32 s40, s50, s8
	s_addc_u32 s41, s51, s9
	s_and_b64 s[8:9], s[6:7], exec
	s_cselect_b32 s35, s41, s45
	s_cselect_b32 s65, s40, s44
	s_add_u32 s8, s46, 0x40080
	s_addc_u32 s9, s47, 0
	s_add_u32 s66, s44, 0x100
	s_addc_u32 s67, s45, 0
	s_mov_b32 s68, -2

; #define PG8_STAGE(bufoff, gbase, voff) do { _Pragma("unroll") for (int _i = 0; _i < 2; ++_i) \
;         __builtin_amdgcn_global_load_lds((const unsigned*)((const char*)(gbase) + (voff)[_i]), (PG8_LAS unsigned*)(lds + (bufoff) + ldsw + _i * 8192), 16, 0, 0); } while (0)
; #define PG8_LDA(dst, b, h) do { _Pragma("unroll") for (int m = 0; m < 4; ++m) _Pragma("unroll") for (int k = 0; k < 2; ++k) dst[m][k] = *(const PG8_LAS bf16x8*)(lds + PG8_SA(b, h) + aoff + m * 2048 + k * 1024); } while (0)
; #define PG8_LDB(dst, b, h) do { _Pragma("unroll") for (int n = 0; n < 2; ++n) _Pragma("unroll") for (int k = 0; k < 2; ++k) dst[n][k] = *(const PG8_LAS bf16x8*)(lds + PG8_SB(b, h) + boff + n * 2048 + k * 1024); } while (0)
; #define PG8_MMA(ai, bj, At, Bt) do { __builtin_amdgcn_s_setprio(1); _Pragma("unroll") for (int m = 0; m < 4; ++m) _Pragma("unroll") for (int n = 0; n < 2; ++n) _Pragma("unroll") for (int k = 0; k < 2; ++k) \
;         acc[ai][bj][m][n] = __builtin_amdgcn_mfma_f32_16x16x32_bf16(Bt[n][k], At[m][k], acc[ai][bj][m][n], 0, 0, 0); __builtin_amdgcn_s_setprio(0); } while (0)
; #define PG8_WAIT_V(n) asm volatile("s_waitcnt vmcnt(" #n ")" ::: "memory")
; #define PG8_WAIT_L(n) asm volatile("s_waitcnt lgkmcnt(" #n ")" ::: "memory")
; #define PG8_BAR __builtin_amdgcn_s_barrier()
; #define PG8_SCHED __builtin_amdgcn_sched_barrier(0)
; template <class Epi, class Sched, bool ALIGN_EPI = false, bool SP2 = false>
; __device__ __forceinline__ void gemm_phase(PG8_LAS unsigned char* lds, const Gemm g, const Sched& S, const Epi& E) {
;     ...
; #pragma unroll
;     for (int a = 0; a < 2; ++a)
; #pragma unroll
;         for (int b = 0; b < 2; ++b)
; #pragma unroll
;             for (int m = 0; m < 4; ++m)
; #pragma unroll
;                 for (int n = 0; n < 2; ++n) acc[a][b][m][n] = (f32x4){0.f, 0.f, 0.f, 0.f};
;     ...
;             PG8_LDB(B0, 0, 0); PG8_LDB(B1, 0, 1); PG8_SCHED; PG8_LDA(At, 0, 0); PG8_STAGE(PG8_SA(1, 1), a1 + hstep, voffA);
;             PG8_WAIT_V(8); PG8_WAIT_L(0); PG8_BAR; PG8_MMA(0, 0, At, B0); PG8_MMA(0, 1, At, B1); PG8_BAR; PG8_SCHED;
.Lffin_nopf:
	v_add_u32_e32 v118, s69, v229
	v_add_u32_e32 v134, s72, v229
	ds_read_b128 v[106:109], v118
	ds_read_b128 v[110:113], v118 offset:1024
	ds_read_b128 v[114:117], v118 offset:2048
	ds_read_b128 v[118:121], v118 offset:3072
	ds_read_b128 v[122:125], v134
	ds_read_b128 v[126:129], v134 offset:1024
	ds_read_b128 v[130:133], v134 offset:2048
	ds_read_b128 v[134:137], v134 offset:3072
	v_lshl_add_u64 v[212:213], s[8:9], 0, v[188:189]
	s_add_i32 m0, s53, 0xc000
	ds_read_b128 v[162:165], v230
	ds_read_b128 v[166:169], v230 offset:1024
	ds_read_b128 v[170:173], v230 offset:2048
	ds_read_b128 v[192:195], v230 offset:3072
	ds_read_b128 v[196:199], v230 offset:4096
	ds_read_b128 v[200:203], v230 offset:5120
	ds_read_b128 v[204:207], v230 offset:6144
	ds_read_b128 v[208:211], v230 offset:7168
	global_load_lds_dwordx4 v[212:213], off
	v_lshl_add_u64 v[212:213], s[8:9], 0, v[190:191]
	s_add_i32 m0, s53, 0xe000
	s_nop 0
	global_load_lds_dwordx4 v[212:213], off
	s_cmp_lg_u32 s68, -2
	s_cbranch_scc1 .Lffin_noz
	v_mov_b32_e32 v2, 0
	v_mov_b32_e32 v3, v2
	v_mov_b32_e32 v4, v2
	v_mov_b32_e32 v5, v2
	v_mov_b32_e32 v6, v2
	v_mov_b32_e32 v7, v2
	v_mov_b32_e32 v8, v2
	v_mov_b32_e32 v9, v2
	v_mov_b32_e32 v18, v2
	v_mov_b32_e32 v19, v2
	v_mov_b32_e32 v20, v2
	v_mov_b32_e32 v21, v2
	v_mov_b32_e32 v22, v2
	v_mov_b32_e32 v23, v2
	v_mov_b32_e32 v24, v2
	v_mov_b32_e32 v25, v2
	v_mov_b32_e32 v34, v2
	v_mov_b32_e32 v35, v2
	v_mov_b32_e32 v36, v2
	v_mov_b32_e32 v37, v2
	v_mov_b32_e32 v38, v2
	v_mov_b32_e32 v39, v2
	v_mov_b32_e32 v40, v2
	v_mov_b32_e32 v41, v2
	v_mov_b32_e32 v50, v2
	v_mov_b32_e32 v51, v2
	v_mov_b32_e32 v52, v2
	v_mov_b32_e32 v53, v2
	v_mov_b32_e32 v54, v2
	v_mov_b32_e32 v55, v2
	v_mov_b32_e32 v56, v2
	v_mov_b32_e32 v57, v2
	v_mov_b32_e32 v10, v2
	v_mov_b32_e32 v11, v2
	v_mov_b32_e32 v12, v2
	v_mov_b32_e32 v13, v2
	v_mov_b32_e32 v14, v2
	v_mov_b32_e32 v15, v2
	v_mov_b32_e32 v16, v2
	v_mov_b32_e32 v17, v2
	v_mov_b32_e32 v26, v2
	v_mov_b32_e32 v27, v2
	v_mov_b32_e32 v28, v2
	v_mov_b32_e32 v29, v2
	v_mov_b32_e32 v30, v2
	v_mov_b32_e32 v31, v2
	v_mov_b32_e32 v32, v2
	v_mov_b32_e32 v33, v2
	v_mov_b32_e32 v42, v2
	v_mov_b32_e32 v43, v2
	v_mov_b32_e32 v44, v2
	v_mov_b32_e32 v45, v2
	v_mov_b32_e32 v46, v2
	v_mov_b32_e32 v47, v2
	v_mov_b32_e32 v48, v2
	v_mov_b32_e32 v49, v2
	v_mov_b32_e32 v58, v2
	v_mov_b32_e32 v59, v2
	v_mov_b32_e32 v60, v2
	v_mov_b32_e32 v61, v2
	v_mov_b32_e32 v62, v2
	v_mov_b32_e32 v63, v2
	v_mov_b32_e32 v64, v2
	v_mov_b32_e32 v65, v2
	v_mov_b32_e32 v66, v2
	v_mov_b32_e32 v67, v2
	v_mov_b32_e32 v68, v2
	v_mov_b32_e32 v69, v2
	v_mov_b32_e32 v70, v2
	v_mov_b32_e32 v71, v2
	v_mov_b32_e32 v72, v2
	v_mov_b32_e32 v73, v2
	v_mov_b32_e32 v82, v2
	v_mov_b32_e32 v83, v2
	v_mov_b32_e32 v84, v2
	v_mov_b32_e32 v85, v2
	v_mov_b32_e32 v86, v2
	v_mov_b32_e32 v87, v2
	v_mov_b32_e32 v88, v2
	v_mov_b32_e32 v89, v2
	v_mov_b32_e32 v98, v2
	v_mov_b32_e32 v99, v2
	v_mov_b32_e32 v100, v2
	v_mov_b32_e32 v101, v2
	v_mov_b32_e32 v102, v2
	v_mov_b32_e32 v103, v2
	v_mov_b32_e32 v104, v2
	v_mov_b32_e32 v105, v2
	v_mov_b32_e32 v146, v2
	v_mov_b32_e32 v147, v2
	v_mov_b32_e32 v148, v2
	v_mov_b32_e32 v149, v2
	v_mov_b32_e32 v150, v2
	v_mov_b32_e32 v151, v2
	v_mov_b32_e32 v152, v2
	v_mov_b32_e32 v153, v2
	v_mov_b32_e32 v74, v2
	v_mov_b32_e32 v75, v2
	v_mov_b32_e32 v76, v2
	v_mov_b32_e32 v77, v2
	v_mov_b32_e32 v78, v2
	v_mov_b32_e32 v79, v2
	v_mov_b32_e32 v80, v2
	v_mov_b32_e32 v81, v2
	v_mov_b32_e32 v90, v2
	v_mov_b32_e32 v91, v2
	v_mov_b32_e32 v92, v2
	v_mov_b32_e32 v93, v2
	v_mov_b32_e32 v94, v2
	v_mov_b32_e32 v95, v2
	v_mov_b32_e32 v96, v2
	v_mov_b32_e32 v97, v2
	v_mov_b32_e32 v138, v2
	v_mov_b32_e32 v139, v2
	v_mov_b32_e32 v140, v2
	v_mov_b32_e32 v141, v2
	v_mov_b32_e32 v142, v2
	v_mov_b32_e32 v143, v2
	v_mov_b32_e32 v144, v2
	v_mov_b32_e32 v145, v2
	v_mov_b32_e32 v154, v2
	v_mov_b32_e32 v155, v2
	v_mov_b32_e32 v156, v2
	v_mov_b32_e32 v157, v2
	v_mov_b32_e32 v158, v2
	v_mov_b32_e32 v159, v2
	v_mov_b32_e32 v160, v2
	v_mov_b32_e32 v161, v2
.Lffin_noz:
	s_waitcnt vmcnt(8)
	s_waitcnt lgkmcnt(0)
	s_barrier
	s_setprio 1
	s_waitcnt lgkmcnt(0)
	v_mfma_f32_16x16x32_bf16 v[158:161], v[106:109], v[162:165], v[158:161]
	v_mfma_f32_16x16x32_bf16 v[154:157], v[114:117], v[162:165], v[154:157]
	v_mfma_f32_16x16x32_bf16 v[142:145], v[106:109], v[170:173], v[142:145]
	v_mfma_f32_16x16x32_bf16 v[138:141], v[114:117], v[170:173], v[138:141]
	v_mfma_f32_16x16x32_bf16 v[94:97], v[106:109], v[196:199], v[94:97]
	v_mfma_f32_16x16x32_bf16 v[90:93], v[114:117], v[196:199], v[90:93]
	v_mfma_f32_16x16x32_bf16 v[78:81], v[106:109], v[204:207], v[78:81]
	v_mfma_f32_16x16x32_bf16 v[74:77], v[114:117], v[204:207], v[74:77]
	v_mfma_f32_16x16x32_bf16 v[158:161], v[110:113], v[166:169], v[158:161]
	v_mfma_f32_16x16x32_bf16 v[154:157], v[118:121], v[166:169], v[154:157]
	v_mfma_f32_16x16x32_bf16 v[142:145], v[110:113], v[192:195], v[142:145]
	v_mfma_f32_16x16x32_bf16 v[138:141], v[118:121], v[192:195], v[138:141]
	v_mfma_f32_16x16x32_bf16 v[94:97], v[110:113], v[200:203], v[94:97]
	v_mfma_f32_16x16x32_bf16 v[90:93], v[118:121], v[200:203], v[90:93]
	v_mfma_f32_16x16x32_bf16 v[78:81], v[110:113], v[208:211], v[78:81]
	v_mfma_f32_16x16x32_bf16 v[74:77], v[118:121], v[208:211], v[74:77]
	s_setprio 0
	s_setprio 1
	v_mfma_f32_16x16x32_bf16 v[150:153], v[122:125], v[162:165], v[150:153]
	v_mfma_f32_16x16x32_bf16 v[146:149], v[130:133], v[162:165], v[146:149]
	v_mfma_f32_16x16x32_bf16 v[102:105], v[122:125], v[170:173], v[102:105]
	v_mfma_f32_16x16x32_bf16 v[98:101], v[130:133], v[170:173], v[98:101]
	v_mfma_f32_16x16x32_bf16 v[86:89], v[122:125], v[196:199], v[86:89]
	v_mfma_f32_16x16x32_bf16 v[82:85], v[130:133], v[196:199], v[82:85]
	v_mfma_f32_16x16x32_bf16 v[70:73], v[122:125], v[204:207], v[70:73]
	v_mfma_f32_16x16x32_bf16 v[66:69], v[130:133], v[204:207], v[66:69]
	v_mfma_f32_16x16x32_bf16 v[150:153], v[126:129], v[166:169], v[150:153]
	v_mfma_f32_16x16x32_bf16 v[146:149], v[134:137], v[166:169], v[146:149]
	v_mfma_f32_16x16x32_bf16 v[102:105], v[126:129], v[192:195], v[102:105]
	v_mfma_f32_16x16x32_bf16 v[98:101], v[134:137], v[192:195], v[98:101]
	v_mfma_f32_16x16x32_bf16 v[86:89], v[126:129], v[200:203], v[86:89]
	v_mfma_f32_16x16x32_bf16 v[82:85], v[134:137], v[200:203], v[82:85]
	v_mfma_f32_16x16x32_bf16 v[70:73], v[126:129], v[208:211], v[70:73]
	v_mfma_f32_16x16x32_bf16 v[66:69], v[134:137], v[208:211], v[66:69]
	s_setprio 0
	s_barrier
; #define PG8_STAGE(bufoff, gbase, voff) do { _Pragma("unroll") for (int _i = 0; _i < 2; ++_i) \
;         __builtin_amdgcn_global_load_lds((const unsigned*)((const char*)(gbase) + (voff)[_i]), (PG8_LAS unsigned*)(lds + (bufoff) + ldsw + _i * 8192), 16, 0, 0); } while (0)
; #define PG8_LDA(dst, b, h) do { _Pragma("unroll") for (int m = 0; m < 4; ++m) _Pragma("unroll") for (int k = 0; k < 2; ++k) dst[m][k] = *(const PG8_LAS bf16x8*)(lds + PG8_SA(b, h) + aoff + m * 2048 + k * 1024); } while (0)
; #define PG8_LDB(dst, b, h) do { _Pragma("unroll") for (int n = 0; n < 2; ++n) _Pragma("unroll") for (int k = 0; k < 2; ++k) dst[n][k] = *(const PG8_LAS bf16x8*)(lds + PG8_SB(b, h) + boff + n * 2048 + k * 1024); } while (0)
; #define PG8_MMA(ai, bj, At, Bt) do { __builtin_amdgcn_s_setprio(1); _Pragma("unroll") for (int m = 0; m < 4; ++m) _Pragma("unroll") for (int n = 0; n < 2; ++n) _Pragma("unroll") for (int k = 0; k < 2; ++k) \
;         acc[ai][bj][m][n] = __builtin_amdgcn_mfma_f32_16x16x32_bf16(Bt[n][k], At[m][k], acc[ai][bj][m][n], 0, 0, 0); __builtin_amdgcn_s_setprio(0); } while (0)
; #define PG8_WAIT_V(n) asm volatile("s_waitcnt vmcnt(" #n ")" ::: "memory")
; #define PG8_WAIT_L(n) asm volatile("s_waitcnt lgkmcnt(" #n ")" ::: "memory")
; #define PG8_BAR __builtin_amdgcn_s_barrier()
; #define PG8_SCHED __builtin_amdgcn_sched_barrier(0)
; template <class Epi, class Sched, bool ALIGN_EPI = false, bool SP2 = false>
; __device__ __forceinline__ void gemm_phase(PG8_LAS unsigned char* lds, const Gemm g, const Sched& S, const Epi& E) {
;     ...
;             PG8_LDA(At, 0, 1); PG8_STAGE(PG8_SB(0, 0), b2, voffB); PG8_STAGE(PG8_SB(0, 1), b2 + hstep, voffB); PG8_STAGE(PG8_SA(0, 0), a2, voffA);
;             PG8_WAIT_V(8); PG8_WAIT_L(0); PG8_BAR; PG8_MMA(1, 0, At, B0); PG8_MMA(1, 1, At, B1); PG8_BAR; PG8_SCHED;
;             PG8_LDB(B0, 1, 0); PG8_LDB(B1, 1, 1); PG8_SCHED; PG8_LDA(At, 1, 0); PG8_STAGE(PG8_SA(0, 1), a2 + hstep, voffA);
;             PG8_WAIT_V(8); PG8_WAIT_L(0); PG8_BAR; PG8_MMA(0, 0, At, B0); PG8_MMA(0, 1, At, B1); PG8_BAR; PG8_SCHED;
	s_add_i32 s69, s69, s52
	v_lshl_add_u64 v[212:213], s[44:45], 0, v[184:185]
	s_mov_b32 m0, s69
	ds_read_b128 v[162:165], v230 offset:16384
	ds_read_b128 v[166:169], v230 offset:17408
	ds_read_b128 v[170:173], v230 offset:18432
	ds_read_b128 v[192:195], v230 offset:19456
	ds_read_b128 v[196:199], v230 offset:20480
	ds_read_b128 v[200:203], v230 offset:21504
	ds_read_b128 v[204:207], v230 offset:22528
	ds_read_b128 v[208:211], v230 offset:23552
	global_load_lds_dwordx4 v[212:213], off
	s_add_i32 m0, s69, 0x2000
	s_add_u32 s70, s44, 0x40000
	v_lshl_add_u64 v[214:215], s[44:45], 0, v[180:181]
	s_addc_u32 s71, s45, 0
	s_add_i32 s69, s72, s52
	global_load_lds_dwordx4 v[214:215], off
	v_lshl_add_u64 v[216:217], s[70:71], 0, v[184:185]
	s_mov_b32 m0, s69
	v_lshl_add_u64 v[218:219], s[46:47], 0, v[182:183]
	global_load_lds_dwordx4 v[216:217], off
	v_lshl_add_u64 v[216:217], s[70:71], 0, v[180:181]
	s_add_i32 m0, s69, 0x2000
	s_nop 0
	global_load_lds_dwordx4 v[216:217], off
	v_lshl_add_u64 v[216:217], s[46:47], 0, v[186:187]
	s_mov_b32 m0, s53
	s_nop 0
	global_load_lds_dwordx4 v[216:217], off
	s_mov_b32 m0, s54
	s_nop 0
	global_load_lds_dwordx4 v[218:219], off
	s_waitcnt vmcnt(8)
	s_waitcnt lgkmcnt(0)
	s_barrier
	s_setprio 1
	s_waitcnt lgkmcnt(0)
	v_mfma_f32_16x16x32_bf16 v[62:65], v[106:109], v[162:165], v[62:65]
	v_mfma_f32_16x16x32_bf16 v[58:61], v[114:117], v[162:165], v[58:61]
	v_mfma_f32_16x16x32_bf16 v[46:49], v[106:109], v[170:173], v[46:49]
	v_mfma_f32_16x16x32_bf16 v[42:45], v[114:117], v[170:173], v[42:45]
	v_mfma_f32_16x16x32_bf16 v[30:33], v[106:109], v[196:199], v[30:33]
	v_mfma_f32_16x16x32_bf16 v[26:29], v[114:117], v[196:199], v[26:29]
	v_mfma_f32_16x16x32_bf16 v[14:17], v[106:109], v[204:207], v[14:17]
	v_mfma_f32_16x16x32_bf16 v[10:13], v[114:117], v[204:207], v[10:13]
	v_mfma_f32_16x16x32_bf16 v[62:65], v[110:113], v[166:169], v[62:65]
	v_mfma_f32_16x16x32_bf16 v[58:61], v[118:121], v[166:169], v[58:61]
	v_mfma_f32_16x16x32_bf16 v[46:49], v[110:113], v[192:195], v[46:49]
	v_mfma_f32_16x16x32_bf16 v[42:45], v[118:121], v[192:195], v[42:45]
	v_mfma_f32_16x16x32_bf16 v[30:33], v[110:113], v[200:203], v[30:33]
	v_mfma_f32_16x16x32_bf16 v[26:29], v[118:121], v[200:203], v[26:29]
	v_mfma_f32_16x16x32_bf16 v[14:17], v[110:113], v[208:211], v[14:17]
	v_mfma_f32_16x16x32_bf16 v[10:13], v[118:121], v[208:211], v[10:13]
	s_setprio 0
	s_setprio 1
	v_mfma_f32_16x16x32_bf16 v[54:57], v[122:125], v[162:165], v[54:57]
	v_mfma_f32_16x16x32_bf16 v[50:53], v[130:133], v[162:165], v[50:53]
	v_mfma_f32_16x16x32_bf16 v[38:41], v[122:125], v[170:173], v[38:41]
	v_mfma_f32_16x16x32_bf16 v[34:37], v[130:133], v[170:173], v[34:37]
	v_mfma_f32_16x16x32_bf16 v[22:25], v[122:125], v[196:199], v[22:25]
	v_mfma_f32_16x16x32_bf16 v[18:21], v[130:133], v[196:199], v[18:21]
	v_mfma_f32_16x16x32_bf16 v[6:9], v[122:125], v[204:207], v[6:9]
	v_mfma_f32_16x16x32_bf16 v[2:5], v[130:133], v[204:207], v[2:5]
	v_mfma_f32_16x16x32_bf16 v[54:57], v[126:129], v[166:169], v[54:57]
	v_mfma_f32_16x16x32_bf16 v[50:53], v[134:137], v[166:169], v[50:53]
	v_mfma_f32_16x16x32_bf16 v[38:41], v[126:129], v[192:195], v[38:41]
	v_mfma_f32_16x16x32_bf16 v[34:37], v[134:137], v[192:195], v[34:37]
	v_mfma_f32_16x16x32_bf16 v[22:25], v[126:129], v[200:203], v[22:25]
	v_mfma_f32_16x16x32_bf16 v[18:21], v[134:137], v[200:203], v[18:21]
	v_mfma_f32_16x16x32_bf16 v[6:9], v[126:129], v[208:211], v[6:9]
	v_mfma_f32_16x16x32_bf16 v[2:5], v[134:137], v[208:211], v[2:5]
	s_setprio 0
	s_barrier
	s_add_i32 s69, 0, 0x18000
	s_add_i32 s70, 0, 0x1c000
	v_add_u32_e32 v118, s69, v229
	v_add_u32_e32 v134, s70, v229
	ds_read_b128 v[106:109], v118
	ds_read_b128 v[110:113], v118 offset:1024
	ds_read_b128 v[114:117], v118 offset:2048
	ds_read_b128 v[118:121], v118 offset:3072
	ds_read_b128 v[122:125], v134
	ds_read_b128 v[126:129], v134 offset:1024
	ds_read_b128 v[130:133], v134 offset:2048
	ds_read_b128 v[134:137], v134 offset:3072
	s_add_u32 s46, s46, 0x40000
	s_addc_u32 s47, s47, 0
	s_mov_b32 m0, s55
	v_lshl_add_u64 v[220:221], s[46:47], 0, v[186:187]
	ds_read_b128 v[162:165], v230 offset:32768
	ds_read_b128 v[166:169], v230 offset:33792
	ds_read_b128 v[170:173], v230 offset:34816
	ds_read_b128 v[192:195], v230 offset:35840
	ds_read_b128 v[196:199], v230 offset:36864
	ds_read_b128 v[200:203], v230 offset:37888
	ds_read_b128 v[204:207], v230 offset:38912
	ds_read_b128 v[208:211], v230 offset:39936
	global_load_lds_dwordx4 v[220:221], off
	v_lshl_add_u64 v[220:221], s[46:47], 0, v[182:183]
	s_mov_b32 m0, s56
	s_nop 0
	global_load_lds_dwordx4 v[220:221], off
	s_waitcnt vmcnt(8)
	s_waitcnt lgkmcnt(0)
	s_barrier
; #define PG8_STAGE(bufoff, gbase, voff) do { _Pragma("unroll") for (int _i = 0; _i < 2; ++_i) \
;         __builtin_amdgcn_global_load_lds((const unsigned*)((const char*)(gbase) + (voff)[_i]), (PG8_LAS unsigned*)(lds + (bufoff) + ldsw + _i * 8192), 16, 0, 0); } while (0)
; #define PG8_LDA(dst, b, h) do { _Pragma("unroll") for (int m = 0; m < 4; ++m) _Pragma("unroll") for (int k = 0; k < 2; ++k) dst[m][k] = *(const PG8_LAS bf16x8*)(lds + PG8_SA(b, h) + aoff + m * 2048 + k * 1024); } while (0)
; #define PG8_MMA(ai, bj, At, Bt) do { __builtin_amdgcn_s_setprio(1); _Pragma("unroll") for (int m = 0; m < 4; ++m) _Pragma("unroll") for (int n = 0; n < 2; ++n) _Pragma("unroll") for (int k = 0; k < 2; ++k) \
;         acc[ai][bj][m][n] = __builtin_amdgcn_mfma_f32_16x16x32_bf16(Bt[n][k], At[m][k], acc[ai][bj][m][n], 0, 0, 0); __builtin_amdgcn_s_setprio(0); } while (0)
; #define PG8_WAIT_V(n) asm volatile("s_waitcnt vmcnt(" #n ")" ::: "memory")
; #define PG8_WAIT_L(n) asm volatile("s_waitcnt lgkmcnt(" #n ")" ::: "memory")
; #define PG8_BAR __builtin_amdgcn_s_barrier()
; #define PG8_SCHED __builtin_amdgcn_sched_barrier(0)
; template <class Epi, class Sched, bool ALIGN_EPI = false, bool SP2 = false>
; __device__ __forceinline__ void gemm_phase(PG8_LAS unsigned char* lds, const Gemm g, const Sched& S, const Epi& E) {
;     ...
;             PG8_WAIT_V(8); PG8_WAIT_L(0); PG8_BAR; PG8_MMA(0, 0, At, B0); PG8_MMA(0, 1, At, B1); PG8_BAR; PG8_SCHED;
;             PG8_LDA(At, 1, 1); PG8_STAGE(PG8_SB(1, 0), b3, voffB); PG8_STAGE(PG8_SB(1, 1), b3 + hstep, voffB); PG8_STAGE(PG8_SA(1, 0), a3, voffA);
;             PG8_WAIT_V(8); PG8_WAIT_L(0); PG8_BAR; PG8_MMA(1, 0, At, B0); PG8_MMA(1, 1, At, B1); PG8_BAR; PG8_SCHED;
;     ...
;         if constexpr (ALIGN_EPI) { if (wr == 0) PG8_BAR; }
	s_setprio 1
	s_waitcnt lgkmcnt(0)
	v_mfma_f32_16x16x32_bf16 v[158:161], v[106:109], v[162:165], v[158:161]
	v_mfma_f32_16x16x32_bf16 v[154:157], v[114:117], v[162:165], v[154:157]
	v_mfma_f32_16x16x32_bf16 v[142:145], v[106:109], v[170:173], v[142:145]
	v_mfma_f32_16x16x32_bf16 v[138:141], v[114:117], v[170:173], v[138:141]
	v_mfma_f32_16x16x32_bf16 v[94:97], v[106:109], v[196:199], v[94:97]
	v_mfma_f32_16x16x32_bf16 v[90:93], v[114:117], v[196:199], v[90:93]
	v_mfma_f32_16x16x32_bf16 v[78:81], v[106:109], v[204:207], v[78:81]
	v_mfma_f32_16x16x32_bf16 v[74:77], v[114:117], v[204:207], v[74:77]
	v_mfma_f32_16x16x32_bf16 v[158:161], v[110:113], v[166:169], v[158:161]
	v_mfma_f32_16x16x32_bf16 v[154:157], v[118:121], v[166:169], v[154:157]
	v_mfma_f32_16x16x32_bf16 v[142:145], v[110:113], v[192:195], v[142:145]
	v_mfma_f32_16x16x32_bf16 v[138:141], v[118:121], v[192:195], v[138:141]
	v_mfma_f32_16x16x32_bf16 v[94:97], v[110:113], v[200:203], v[94:97]
	v_mfma_f32_16x16x32_bf16 v[90:93], v[118:121], v[200:203], v[90:93]
	v_mfma_f32_16x16x32_bf16 v[78:81], v[110:113], v[208:211], v[78:81]
	v_mfma_f32_16x16x32_bf16 v[74:77], v[118:121], v[208:211], v[74:77]
	s_setprio 0
	s_setprio 1
	v_mfma_f32_16x16x32_bf16 v[150:153], v[122:125], v[162:165], v[150:153]
	v_mfma_f32_16x16x32_bf16 v[146:149], v[130:133], v[162:165], v[146:149]
	v_mfma_f32_16x16x32_bf16 v[102:105], v[122:125], v[170:173], v[102:105]
	v_mfma_f32_16x16x32_bf16 v[98:101], v[130:133], v[170:173], v[98:101]
	v_mfma_f32_16x16x32_bf16 v[86:89], v[122:125], v[196:199], v[86:89]
	v_mfma_f32_16x16x32_bf16 v[82:85], v[130:133], v[196:199], v[82:85]
	v_mfma_f32_16x16x32_bf16 v[70:73], v[122:125], v[204:207], v[70:73]
	v_mfma_f32_16x16x32_bf16 v[66:69], v[130:133], v[204:207], v[66:69]
	v_mfma_f32_16x16x32_bf16 v[150:153], v[126:129], v[166:169], v[150:153]
	v_mfma_f32_16x16x32_bf16 v[146:149], v[134:137], v[166:169], v[146:149]
	v_mfma_f32_16x16x32_bf16 v[102:105], v[126:129], v[192:195], v[102:105]
	v_mfma_f32_16x16x32_bf16 v[98:101], v[134:137], v[192:195], v[98:101]
	v_mfma_f32_16x16x32_bf16 v[86:89], v[126:129], v[200:203], v[86:89]
	v_mfma_f32_16x16x32_bf16 v[82:85], v[134:137], v[200:203], v[82:85]
	v_mfma_f32_16x16x32_bf16 v[70:73], v[126:129], v[208:211], v[70:73]
	v_mfma_f32_16x16x32_bf16 v[66:69], v[134:137], v[208:211], v[66:69]
	s_setprio 0
	s_barrier
	s_add_i32 s46, s69, s52
	v_lshl_add_u64 v[212:213], v[212:213], 0, s[96:97]
	s_mov_b32 m0, s46
	ds_read_b128 v[162:165], v230 offset:49152
	ds_read_b128 v[166:169], v230 offset:50176
	ds_read_b128 v[170:173], v230 offset:51200
	ds_read_b128 v[192:195], v230 offset:52224
	ds_read_b128 v[196:199], v230 offset:53248
	ds_read_b128 v[200:203], v230 offset:54272
	ds_read_b128 v[204:207], v230 offset:55296
	ds_read_b128 v[208:211], v230 offset:56320
	global_load_lds_dwordx4 v[212:213], off
	s_add_i32 m0, s46, 0x2000
	s_add_u32 s44, s44, 0x40080
	v_lshl_add_u64 v[212:213], v[214:215], 0, s[96:97]
	s_addc_u32 s45, s45, 0
	s_add_i32 s46, s70, s52
	global_load_lds_dwordx4 v[212:213], off
	v_lshl_add_u64 v[212:213], s[44:45], 0, v[184:185]
	s_mov_b32 m0, s46
	s_nop 0
	global_load_lds_dwordx4 v[212:213], off
	v_lshl_add_u64 v[212:213], s[44:45], 0, v[180:181]
	s_add_i32 m0, s46, 0x2000
	s_nop 0
	global_load_lds_dwordx4 v[212:213], off
	v_lshl_add_u64 v[212:213], v[216:217], 0, s[96:97]
	s_mov_b32 m0, s60
	s_nop 0
	global_load_lds_dwordx4 v[212:213], off
	v_lshl_add_u64 v[212:213], v[218:219], 0, s[96:97]
	s_mov_b32 m0, s61
	s_nop 0
	global_load_lds_dwordx4 v[212:213], off
	s_waitcnt vmcnt(8)
	s_waitcnt lgkmcnt(0)
	s_barrier
	s_setprio 1
	s_waitcnt lgkmcnt(0)
	v_mfma_f32_16x16x32_bf16 v[62:65], v[106:109], v[162:165], v[62:65]
	v_mfma_f32_16x16x32_bf16 v[58:61], v[114:117], v[162:165], v[58:61]
	v_mfma_f32_16x16x32_bf16 v[46:49], v[106:109], v[170:173], v[46:49]
	v_mfma_f32_16x16x32_bf16 v[42:45], v[114:117], v[170:173], v[42:45]
	v_mfma_f32_16x16x32_bf16 v[30:33], v[106:109], v[196:199], v[30:33]
	v_mfma_f32_16x16x32_bf16 v[26:29], v[114:117], v[196:199], v[26:29]
	v_mfma_f32_16x16x32_bf16 v[14:17], v[106:109], v[204:207], v[14:17]
	v_mfma_f32_16x16x32_bf16 v[10:13], v[114:117], v[204:207], v[10:13]
	v_mfma_f32_16x16x32_bf16 v[62:65], v[110:113], v[166:169], v[62:65]
	v_mfma_f32_16x16x32_bf16 v[58:61], v[118:121], v[166:169], v[58:61]
	v_mfma_f32_16x16x32_bf16 v[46:49], v[110:113], v[192:195], v[46:49]
	v_mfma_f32_16x16x32_bf16 v[42:45], v[118:121], v[192:195], v[42:45]
	v_mfma_f32_16x16x32_bf16 v[30:33], v[110:113], v[200:203], v[30:33]
	v_mfma_f32_16x16x32_bf16 v[26:29], v[118:121], v[200:203], v[26:29]
	v_mfma_f32_16x16x32_bf16 v[14:17], v[110:113], v[208:211], v[14:17]
	v_mfma_f32_16x16x32_bf16 v[10:13], v[118:121], v[208:211], v[10:13]
	s_setprio 0
	s_setprio 1
	v_mfma_f32_16x16x32_bf16 v[54:57], v[122:125], v[162:165], v[54:57]
	v_mfma_f32_16x16x32_bf16 v[50:53], v[130:133], v[162:165], v[50:53]
	v_mfma_f32_16x16x32_bf16 v[38:41], v[122:125], v[170:173], v[38:41]
	v_mfma_f32_16x16x32_bf16 v[34:37], v[130:133], v[170:173], v[34:37]
	v_mfma_f32_16x16x32_bf16 v[22:25], v[122:125], v[196:199], v[22:25]
	v_mfma_f32_16x16x32_bf16 v[18:21], v[130:133], v[196:199], v[18:21]
	v_mfma_f32_16x16x32_bf16 v[6:9], v[122:125], v[204:207], v[6:9]
	v_mfma_f32_16x16x32_bf16 v[2:5], v[130:133], v[204:207], v[2:5]
	v_mfma_f32_16x16x32_bf16 v[54:57], v[126:129], v[166:169], v[54:57]
	v_mfma_f32_16x16x32_bf16 v[50:53], v[134:137], v[166:169], v[50:53]
	v_mfma_f32_16x16x32_bf16 v[38:41], v[126:129], v[192:195], v[38:41]
	v_mfma_f32_16x16x32_bf16 v[34:37], v[134:137], v[192:195], v[34:37]
	v_mfma_f32_16x16x32_bf16 v[22:25], v[126:129], v[200:203], v[22:25]
	v_mfma_f32_16x16x32_bf16 v[18:21], v[134:137], v[200:203], v[18:21]
	v_mfma_f32_16x16x32_bf16 v[6:9], v[126:129], v[208:211], v[6:9]
	v_mfma_f32_16x16x32_bf16 v[2:5], v[134:137], v[208:211], v[2:5]
	s_setprio 0
	s_barrier
	s_add_i32 s68, s68, 2
	s_add_u32 s8, s8, 0x100
	s_addc_u32 s9, s9, 0
	s_add_u32 s66, s66, 0x100
	s_addc_u32 s67, s67, 0
	s_cmp_gt_u32 s68, 13
	s_cbranch_scc0 .LBB0_1247
	s_and_b64 vcc, exec, s[24:25]
	s_cbranch_vccz .LBB0_1250
	s_barrier

; #define PG8_STAGE(bufoff, gbase, voff) do { _Pragma("unroll") for (int _i = 0; _i < 2; ++_i) \
;         __builtin_amdgcn_global_load_lds((const unsigned*)((const char*)(gbase) + (voff)[_i]), (PG8_LAS unsigned*)(lds + (bufoff) + ldsw + _i * 8192), 16, 0, 0); } while (0)
; #define PG8_LDA(dst, b, h) do { _Pragma("unroll") for (int m = 0; m < 4; ++m) _Pragma("unroll") for (int k = 0; k < 2; ++k) dst[m][k] = *(const PG8_LAS bf16x8*)(lds + PG8_SA(b, h) + aoff + m * 2048 + k * 1024); } while (0)
; #define PG8_LDB(dst, b, h) do { _Pragma("unroll") for (int n = 0; n < 2; ++n) _Pragma("unroll") for (int k = 0; k < 2; ++k) dst[n][k] = *(const PG8_LAS bf16x8*)(lds + PG8_SB(b, h) + boff + n * 2048 + k * 1024); } while (0)
; #define PG8_SCHED __builtin_amdgcn_sched_barrier(0)
; template <class Epi, class Sched, bool ALIGN_EPI = false, bool SP2 = false>
; __device__ __forceinline__ void gemm_phase(PG8_LAS unsigned char* lds, const Gemm g, const Sched& S, const Epi& E) {
;     ...
;         const bool has_next = S.next(ui + 1, nxt);
;         const char* nA = has_next ? (const char*)g.A + (size_t)nxt.pm * tstep : cA; const char* nB = has_next ? (const char*)g.Bt + (size_t)nxt.pn * tstep : cB;
;         for (int t = 0; t < nt; t += 2) {
;             const bool last = (t == nt - 2);
;             const char* a1 = cA + (size_t)(t + 1) * kstep;
;             const char* a2 = last ? nA : cA + (size_t)(t + 2) * kstep; const char* b2 = last ? nB : cB + (size_t)(t + 2) * kstep;
;             const char* a3 = a2 + kstep; const char* b3 = b2 + kstep;
;             if (last && has_next) S.a_ready(nxt);
;             if constexpr (SP2) {
;             PG8_LDB(B0, 0, 0); PG8_LDB(B1, 0, 1); PG8_SCHED; PG8_LDA(At, 0, 0); PG8_STAGE(PG8_SA(1, 1), a1 + hstep, voffA);
;     ...
; #pragma unroll
;         for (int a = 0; a < 2; ++a)
; #pragma unroll
;             for (int b = 0; b < 2; ++b)
; #pragma unroll
;                 for (int m = 0; m < 4; ++m)
; #pragma unroll
;                     for (int n = 0; n < 2; ++n) acc[a][b][m][n] = (f32x4){0.f, 0.f, 0.f, 0.f};
.LBB0_1359:
	s_add_u32 s33, s24, 0x100
	s_addc_u32 s49, s25, 0
	s_mov_b32 s50, -2
	s_waitcnt lgkmcnt(0)
.LBB0_1360:
	s_add_u32 s8, s22, 0x100
	s_addc_u32 s9, s23, 0
	s_add_i32 s51, 0, 0x10000
	s_cmp_eq_u32 s50, 40
	s_cselect_b32 s27, s19, s9
	s_cselect_b32 s26, s18, s8
	s_cselect_b32 s25, s21, s49
	s_cselect_b32 s24, s20, s33
	s_add_i32 s52, 0, 0x14000
	v_add_u32_e32 v134, s51, v185
	v_add_u32_e32 v170, s52, v185
	ds_read_b128 v[114:117], v134
	ds_read_b128 v[118:121], v134 offset:1024
	ds_read_b128 v[122:125], v134 offset:2048
	ds_read_b128 v[134:137], v134 offset:3072
	ds_read_b128 v[146:149], v170
	ds_read_b128 v[150:153], v170 offset:1024
	ds_read_b128 v[166:169], v170 offset:2048
	ds_read_b128 v[170:173], v170 offset:3072
	v_lshl_add_u64 v[216:217], s[22:23], 0, v[162:163]
	s_add_i32 m0, s35, 0xc000
	ds_read_b128 v[180:183], v186
	ds_read_b128 v[188:191], v186 offset:1024
	ds_read_b128 v[192:195], v186 offset:2048
	ds_read_b128 v[196:199], v186 offset:3072
	ds_read_b128 v[200:203], v186 offset:4096
	ds_read_b128 v[204:207], v186 offset:5120
	ds_read_b128 v[208:211], v186 offset:6144
	ds_read_b128 v[212:215], v186 offset:7168
	global_load_lds_dwordx4 v[216:217], off
	v_lshl_add_u64 v[216:217], s[22:23], 0, v[164:165]
	s_add_i32 m0, s35, 0xe000
	s_nop 0
	global_load_lds_dwordx4 v[216:217], off
	s_cmp_lg_u32 s50, -2
	s_cbranch_scc1 .Lffout_noz
	v_mov_b32_e32 v2, 0
	v_mov_b32_e32 v3, v2
	v_mov_b32_e32 v4, v2
	v_mov_b32_e32 v5, v2
	v_mov_b32_e32 v6, v2
	v_mov_b32_e32 v7, v2
	v_mov_b32_e32 v8, v2
	v_mov_b32_e32 v9, v2
	v_mov_b32_e32 v18, v2
	v_mov_b32_e32 v19, v2
	v_mov_b32_e32 v20, v2
	v_mov_b32_e32 v21, v2
	v_mov_b32_e32 v22, v2
	v_mov_b32_e32 v23, v2
	v_mov_b32_e32 v24, v2
	v_mov_b32_e32 v25, v2
	v_mov_b32_e32 v34, v2
	v_mov_b32_e32 v35, v2
	v_mov_b32_e32 v36, v2
	v_mov_b32_e32 v37, v2
	v_mov_b32_e32 v38, v2
	v_mov_b32_e32 v39, v2
	v_mov_b32_e32 v40, v2
	v_mov_b32_e32 v41, v2
	v_mov_b32_e32 v50, v2
	v_mov_b32_e32 v51, v2
	v_mov_b32_e32 v52, v2
	v_mov_b32_e32 v53, v2
	v_mov_b32_e32 v54, v2
	v_mov_b32_e32 v55, v2
	v_mov_b32_e32 v56, v2
	v_mov_b32_e32 v57, v2
	v_mov_b32_e32 v10, v2
	v_mov_b32_e32 v11, v2
	v_mov_b32_e32 v12, v2
	v_mov_b32_e32 v13, v2
	v_mov_b32_e32 v14, v2
	v_mov_b32_e32 v15, v2
	v_mov_b32_e32 v16, v2
	v_mov_b32_e32 v17, v2
	v_mov_b32_e32 v26, v2
	v_mov_b32_e32 v27, v2
	v_mov_b32_e32 v28, v2
	v_mov_b32_e32 v29, v2
	v_mov_b32_e32 v30, v2
	v_mov_b32_e32 v31, v2
	v_mov_b32_e32 v32, v2
	v_mov_b32_e32 v33, v2
	v_mov_b32_e32 v42, v2
	v_mov_b32_e32 v43, v2
	v_mov_b32_e32 v44, v2
	v_mov_b32_e32 v45, v2
	v_mov_b32_e32 v46, v2
	v_mov_b32_e32 v47, v2
	v_mov_b32_e32 v48, v2
	v_mov_b32_e32 v49, v2
	v_mov_b32_e32 v58, v2
	v_mov_b32_e32 v59, v2
	v_mov_b32_e32 v60, v2
	v_mov_b32_e32 v61, v2
	v_mov_b32_e32 v62, v2
	v_mov_b32_e32 v63, v2
	v_mov_b32_e32 v64, v2
	v_mov_b32_e32 v65, v2
	v_mov_b32_e32 v66, v2
	v_mov_b32_e32 v67, v2
	v_mov_b32_e32 v68, v2
	v_mov_b32_e32 v69, v2
	v_mov_b32_e32 v70, v2
	v_mov_b32_e32 v71, v2
	v_mov_b32_e32 v72, v2
	v_mov_b32_e32 v73, v2
	v_mov_b32_e32 v82, v2
	v_mov_b32_e32 v83, v2
	v_mov_b32_e32 v84, v2
	v_mov_b32_e32 v85, v2
	v_mov_b32_e32 v86, v2
	v_mov_b32_e32 v87, v2
	v_mov_b32_e32 v88, v2
	v_mov_b32_e32 v89, v2
	v_mov_b32_e32 v98, v2
	v_mov_b32_e32 v99, v2
	v_mov_b32_e32 v100, v2
	v_mov_b32_e32 v101, v2
	v_mov_b32_e32 v102, v2
	v_mov_b32_e32 v103, v2
	v_mov_b32_e32 v104, v2
	v_mov_b32_e32 v105, v2
	v_mov_b32_e32 v126, v2
	v_mov_b32_e32 v127, v2
	v_mov_b32_e32 v128, v2
	v_mov_b32_e32 v129, v2
	v_mov_b32_e32 v130, v2
	v_mov_b32_e32 v131, v2
	v_mov_b32_e32 v132, v2
	v_mov_b32_e32 v133, v2
	v_mov_b32_e32 v74, v2
	v_mov_b32_e32 v75, v2
	v_mov_b32_e32 v76, v2
	v_mov_b32_e32 v77, v2
	v_mov_b32_e32 v78, v2
	v_mov_b32_e32 v79, v2
	v_mov_b32_e32 v80, v2
	v_mov_b32_e32 v81, v2
	v_mov_b32_e32 v90, v2
	v_mov_b32_e32 v91, v2
	v_mov_b32_e32 v92, v2
	v_mov_b32_e32 v93, v2
	v_mov_b32_e32 v94, v2
	v_mov_b32_e32 v95, v2
	v_mov_b32_e32 v96, v2
	v_mov_b32_e32 v97, v2
	v_mov_b32_e32 v106, v2
	v_mov_b32_e32 v107, v2
	v_mov_b32_e32 v108, v2
	v_mov_b32_e32 v109, v2
	v_mov_b32_e32 v110, v2
	v_mov_b32_e32 v111, v2
	v_mov_b32_e32 v112, v2
	v_mov_b32_e32 v113, v2
	v_mov_b32_e32 v138, v2
	v_mov_b32_e32 v139, v2
	v_mov_b32_e32 v140, v2
	v_mov_b32_e32 v141, v2
	v_mov_b32_e32 v142, v2
	v_mov_b32_e32 v143, v2
	v_mov_b32_e32 v144, v2
	v_mov_b32_e32 v145, v2
; #define PG8_STAGE(bufoff, gbase, voff) do { _Pragma("unroll") for (int _i = 0; _i < 2; ++_i) \
;         __builtin_amdgcn_global_load_lds((const unsigned*)((const char*)(gbase) + (voff)[_i]), (PG8_LAS unsigned*)(lds + (bufoff) + ldsw + _i * 8192), 16, 0, 0); } while (0)
; #define PG8_LDA(dst, b, h) do { _Pragma("unroll") for (int m = 0; m < 4; ++m) _Pragma("unroll") for (int k = 0; k < 2; ++k) dst[m][k] = *(const PG8_LAS bf16x8*)(lds + PG8_SA(b, h) + aoff + m * 2048 + k * 1024); } while (0)
; #define PG8_MMA(ai, bj, At, Bt) do { __builtin_amdgcn_s_setprio(1); _Pragma("unroll") for (int m = 0; m < 4; ++m) _Pragma("unroll") for (int n = 0; n < 2; ++n) _Pragma("unroll") for (int k = 0; k < 2; ++k) \
;         acc[ai][bj][m][n] = __builtin_amdgcn_mfma_f32_16x16x32_bf16(Bt[n][k], At[m][k], acc[ai][bj][m][n], 0, 0, 0); __builtin_amdgcn_s_setprio(0); } while (0)
; #define PG8_WAIT_V(n) asm volatile("s_waitcnt vmcnt(" #n ")" ::: "memory")
; #define PG8_WAIT_L(n) asm volatile("s_waitcnt lgkmcnt(" #n ")" ::: "memory")
; #define PG8_BAR __builtin_amdgcn_s_barrier()
; #define PG8_SCHED __builtin_amdgcn_sched_barrier(0)
; template <class Epi, class Sched, bool ALIGN_EPI = false, bool SP2 = false>
; __device__ __forceinline__ void gemm_phase(PG8_LAS unsigned char* lds, const Gemm g, const Sched& S, const Epi& E) {
;     ...
;             PG8_WAIT_V(8); PG8_WAIT_L(0); PG8_BAR; PG8_MMA(0, 0, At, B0); PG8_MMA(0, 1, At, B1); PG8_BAR; PG8_SCHED;
;             PG8_LDA(At, 0, 1); PG8_STAGE(PG8_SB(0, 0), b2, voffB); PG8_STAGE(PG8_SB(0, 1), b2 + hstep, voffB); PG8_STAGE(PG8_SA(0, 0), a2, voffA);
;             PG8_WAIT_V(8); PG8_WAIT_L(0); PG8_BAR; PG8_MMA(1, 0, At, B0); PG8_MMA(1, 1, At, B1); PG8_BAR; PG8_SCHED;
.Lffout_noz:
	s_waitcnt vmcnt(8)
	s_waitcnt lgkmcnt(0)
	s_barrier
	s_setprio 1
	s_waitcnt lgkmcnt(0)
	v_mfma_f32_16x16x32_bf16 v[142:145], v[114:117], v[180:183], v[142:145]
	v_mfma_f32_16x16x32_bf16 v[138:141], v[122:125], v[180:183], v[138:141]
	v_mfma_f32_16x16x32_bf16 v[110:113], v[114:117], v[192:195], v[110:113]
	v_mfma_f32_16x16x32_bf16 v[106:109], v[122:125], v[192:195], v[106:109]
	v_mfma_f32_16x16x32_bf16 v[94:97], v[114:117], v[200:203], v[94:97]
	v_mfma_f32_16x16x32_bf16 v[90:93], v[122:125], v[200:203], v[90:93]
	v_mfma_f32_16x16x32_bf16 v[78:81], v[114:117], v[208:211], v[78:81]
	v_mfma_f32_16x16x32_bf16 v[74:77], v[122:125], v[208:211], v[74:77]
	v_mfma_f32_16x16x32_bf16 v[142:145], v[118:121], v[188:191], v[142:145]
	v_mfma_f32_16x16x32_bf16 v[138:141], v[134:137], v[188:191], v[138:141]
	v_mfma_f32_16x16x32_bf16 v[110:113], v[118:121], v[196:199], v[110:113]
	v_mfma_f32_16x16x32_bf16 v[106:109], v[134:137], v[196:199], v[106:109]
	v_mfma_f32_16x16x32_bf16 v[94:97], v[118:121], v[204:207], v[94:97]
	v_mfma_f32_16x16x32_bf16 v[90:93], v[134:137], v[204:207], v[90:93]
	v_mfma_f32_16x16x32_bf16 v[78:81], v[118:121], v[212:215], v[78:81]
	v_mfma_f32_16x16x32_bf16 v[74:77], v[134:137], v[212:215], v[74:77]
	s_setprio 0
	s_setprio 1
	v_mfma_f32_16x16x32_bf16 v[130:133], v[146:149], v[180:183], v[130:133]
	v_mfma_f32_16x16x32_bf16 v[126:129], v[166:169], v[180:183], v[126:129]
	v_mfma_f32_16x16x32_bf16 v[102:105], v[146:149], v[192:195], v[102:105]
	v_mfma_f32_16x16x32_bf16 v[98:101], v[166:169], v[192:195], v[98:101]
	v_mfma_f32_16x16x32_bf16 v[86:89], v[146:149], v[200:203], v[86:89]
	v_mfma_f32_16x16x32_bf16 v[82:85], v[166:169], v[200:203], v[82:85]
	v_mfma_f32_16x16x32_bf16 v[70:73], v[146:149], v[208:211], v[70:73]
	v_mfma_f32_16x16x32_bf16 v[66:69], v[166:169], v[208:211], v[66:69]
	v_mfma_f32_16x16x32_bf16 v[130:133], v[150:153], v[188:191], v[130:133]
	v_mfma_f32_16x16x32_bf16 v[126:129], v[170:173], v[188:191], v[126:129]
	v_mfma_f32_16x16x32_bf16 v[102:105], v[150:153], v[196:199], v[102:105]
	v_mfma_f32_16x16x32_bf16 v[98:101], v[170:173], v[196:199], v[98:101]
	v_mfma_f32_16x16x32_bf16 v[86:89], v[150:153], v[204:207], v[86:89]
	v_mfma_f32_16x16x32_bf16 v[82:85], v[170:173], v[204:207], v[82:85]
	v_mfma_f32_16x16x32_bf16 v[70:73], v[150:153], v[212:215], v[70:73]
	v_mfma_f32_16x16x32_bf16 v[66:69], v[170:173], v[212:215], v[66:69]
	s_setprio 0
	s_barrier
	s_add_i32 s22, s51, s34
	v_lshl_add_u64 v[216:217], s[24:25], 0, v[158:159]
	s_mov_b32 m0, s22
	ds_read_b128 v[180:183], v186 offset:16384
	ds_read_b128 v[188:191], v186 offset:17408
	ds_read_b128 v[192:195], v186 offset:18432
	ds_read_b128 v[196:199], v186 offset:19456
	ds_read_b128 v[200:203], v186 offset:20480
	ds_read_b128 v[204:207], v186 offset:21504
	ds_read_b128 v[208:211], v186 offset:22528
	ds_read_b128 v[212:215], v186 offset:23552
	global_load_lds_dwordx4 v[216:217], off
	s_add_i32 m0, s22, 0x2000
	s_add_u32 s22, s24, 0xb0000
	v_lshl_add_u64 v[218:219], s[24:25], 0, v[154:155]
	s_addc_u32 s23, s25, 0
	s_add_i32 s51, s52, s34
	global_load_lds_dwordx4 v[218:219], off
	v_lshl_add_u64 v[220:221], s[22:23], 0, v[158:159]
	s_mov_b32 m0, s51
	v_lshl_add_u64 v[222:223], s[26:27], 0, v[156:157]
	global_load_lds_dwordx4 v[220:221], off
	v_lshl_add_u64 v[220:221], s[22:23], 0, v[154:155]
	s_add_i32 m0, s51, 0x2000
	s_nop 0
	global_load_lds_dwordx4 v[220:221], off
	v_lshl_add_u64 v[220:221], s[26:27], 0, v[160:161]
	s_mov_b32 m0, s35
	s_nop 0
	global_load_lds_dwordx4 v[220:221], off
	s_mov_b32 m0, s36
	s_nop 0
	global_load_lds_dwordx4 v[222:223], off
	s_waitcnt vmcnt(8)
	s_waitcnt lgkmcnt(0)
	s_barrier
	s_setprio 1
	s_waitcnt lgkmcnt(0)
	v_mfma_f32_16x16x32_bf16 v[62:65], v[114:117], v[180:183], v[62:65]
	v_mfma_f32_16x16x32_bf16 v[58:61], v[122:125], v[180:183], v[58:61]
	v_mfma_f32_16x16x32_bf16 v[46:49], v[114:117], v[192:195], v[46:49]
	v_mfma_f32_16x16x32_bf16 v[42:45], v[122:125], v[192:195], v[42:45]
	v_mfma_f32_16x16x32_bf16 v[30:33], v[114:117], v[200:203], v[30:33]
	v_mfma_f32_16x16x32_bf16 v[26:29], v[122:125], v[200:203], v[26:29]
	v_mfma_f32_16x16x32_bf16 v[14:17], v[114:117], v[208:211], v[14:17]
	v_mfma_f32_16x16x32_bf16 v[10:13], v[122:125], v[208:211], v[10:13]
	v_mfma_f32_16x16x32_bf16 v[62:65], v[118:121], v[188:191], v[62:65]
	v_mfma_f32_16x16x32_bf16 v[58:61], v[134:137], v[188:191], v[58:61]
	v_mfma_f32_16x16x32_bf16 v[46:49], v[118:121], v[196:199], v[46:49]
	v_mfma_f32_16x16x32_bf16 v[42:45], v[134:137], v[196:199], v[42:45]
	v_mfma_f32_16x16x32_bf16 v[30:33], v[118:121], v[204:207], v[30:33]
	v_mfma_f32_16x16x32_bf16 v[26:29], v[134:137], v[204:207], v[26:29]
	v_mfma_f32_16x16x32_bf16 v[14:17], v[118:121], v[212:215], v[14:17]
	v_mfma_f32_16x16x32_bf16 v[10:13], v[134:137], v[212:215], v[10:13]
	s_setprio 0
	s_setprio 1
	v_mfma_f32_16x16x32_bf16 v[54:57], v[146:149], v[180:183], v[54:57]
	v_mfma_f32_16x16x32_bf16 v[50:53], v[166:169], v[180:183], v[50:53]
	v_mfma_f32_16x16x32_bf16 v[38:41], v[146:149], v[192:195], v[38:41]
	v_mfma_f32_16x16x32_bf16 v[34:37], v[166:169], v[192:195], v[34:37]
	v_mfma_f32_16x16x32_bf16 v[22:25], v[146:149], v[200:203], v[22:25]
	v_mfma_f32_16x16x32_bf16 v[18:21], v[166:169], v[200:203], v[18:21]
	v_mfma_f32_16x16x32_bf16 v[6:9], v[146:149], v[208:211], v[6:9]
	v_mfma_f32_16x16x32_bf16 v[2:5], v[166:169], v[208:211], v[2:5]
	v_mfma_f32_16x16x32_bf16 v[54:57], v[150:153], v[188:191], v[54:57]
	v_mfma_f32_16x16x32_bf16 v[50:53], v[170:173], v[188:191], v[50:53]
	v_mfma_f32_16x16x32_bf16 v[38:41], v[150:153], v[196:199], v[38:41]
	v_mfma_f32_16x16x32_bf16 v[34:37], v[170:173], v[196:199], v[34:37]
	v_mfma_f32_16x16x32_bf16 v[22:25], v[150:153], v[204:207], v[22:25]
	v_mfma_f32_16x16x32_bf16 v[18:21], v[170:173], v[204:207], v[18:21]
	v_mfma_f32_16x16x32_bf16 v[6:9], v[150:153], v[212:215], v[6:9]
	v_mfma_f32_16x16x32_bf16 v[2:5], v[170:173], v[212:215], v[2:5]
	s_setprio 0
	s_barrier
; #define PG8_STAGE(bufoff, gbase, voff) do { _Pragma("unroll") for (int _i = 0; _i < 2; ++_i) \
;         __builtin_amdgcn_global_load_lds((const unsigned*)((const char*)(gbase) + (voff)[_i]), (PG8_LAS unsigned*)(lds + (bufoff) + ldsw + _i * 8192), 16, 0, 0); } while (0)
; #define PG8_LDA(dst, b, h) do { _Pragma("unroll") for (int m = 0; m < 4; ++m) _Pragma("unroll") for (int k = 0; k < 2; ++k) dst[m][k] = *(const PG8_LAS bf16x8*)(lds + PG8_SA(b, h) + aoff + m * 2048 + k * 1024); } while (0)
; #define PG8_LDB(dst, b, h) do { _Pragma("unroll") for (int n = 0; n < 2; ++n) _Pragma("unroll") for (int k = 0; k < 2; ++k) dst[n][k] = *(const PG8_LAS bf16x8*)(lds + PG8_SB(b, h) + boff + n * 2048 + k * 1024); } while (0)
; #define PG8_MMA(ai, bj, At, Bt) do { __builtin_amdgcn_s_setprio(1); _Pragma("unroll") for (int m = 0; m < 4; ++m) _Pragma("unroll") for (int n = 0; n < 2; ++n) _Pragma("unroll") for (int k = 0; k < 2; ++k) \
;         acc[ai][bj][m][n] = __builtin_amdgcn_mfma_f32_16x16x32_bf16(Bt[n][k], At[m][k], acc[ai][bj][m][n], 0, 0, 0); __builtin_amdgcn_s_setprio(0); } while (0)
; #define PG8_WAIT_V(n) asm volatile("s_waitcnt vmcnt(" #n ")" ::: "memory")
; #define PG8_WAIT_L(n) asm volatile("s_waitcnt lgkmcnt(" #n ")" ::: "memory")
; #define PG8_BAR __builtin_amdgcn_s_barrier()
; #define PG8_SCHED __builtin_amdgcn_sched_barrier(0)
; template <class Epi, class Sched, bool ALIGN_EPI = false, bool SP2 = false>
; __device__ __forceinline__ void gemm_phase(PG8_LAS unsigned char* lds, const Gemm g, const Sched& S, const Epi& E) {
;     ...
;             PG8_LDB(B0, 1, 0); PG8_LDB(B1, 1, 1); PG8_SCHED; PG8_LDA(At, 1, 0); PG8_STAGE(PG8_SA(0, 1), a2 + hstep, voffA);
;             PG8_WAIT_V(8); PG8_WAIT_L(0); PG8_BAR; PG8_MMA(0, 0, At, B0); PG8_MMA(0, 1, At, B1); PG8_BAR; PG8_SCHED;
	s_add_i32 s51, 0, 0x18000
	s_add_i32 s52, 0, 0x1c000
	v_add_u32_e32 v134, s51, v185
	v_add_u32_e32 v170, s52, v185
	ds_read_b128 v[114:117], v134
	ds_read_b128 v[118:121], v134 offset:1024
	ds_read_b128 v[122:125], v134 offset:2048
	ds_read_b128 v[134:137], v134 offset:3072
	ds_read_b128 v[146:149], v170
	ds_read_b128 v[150:153], v170 offset:1024
	ds_read_b128 v[166:169], v170 offset:2048
	ds_read_b128 v[170:173], v170 offset:3072
	s_add_u32 s22, s26, 0xb0000
	s_addc_u32 s23, s27, 0
	s_mov_b32 m0, s37
	v_lshl_add_u64 v[228:229], s[22:23], 0, v[160:161]
	ds_read_b128 v[180:183], v186 offset:32768
	ds_read_b128 v[188:191], v186 offset:33792
	ds_read_b128 v[192:195], v186 offset:34816
	ds_read_b128 v[196:199], v186 offset:35840
	ds_read_b128 v[200:203], v186 offset:36864
	ds_read_b128 v[204:207], v186 offset:37888
	ds_read_b128 v[208:211], v186 offset:38912
	ds_read_b128 v[212:215], v186 offset:39936
	global_load_lds_dwordx4 v[228:229], off
	v_lshl_add_u64 v[228:229], s[22:23], 0, v[156:157]
	s_mov_b32 m0, s38
	s_nop 0
	global_load_lds_dwordx4 v[228:229], off
	s_waitcnt vmcnt(8)
	s_waitcnt lgkmcnt(0)
	s_barrier
	s_setprio 1
	s_waitcnt lgkmcnt(0)
	v_mfma_f32_16x16x32_bf16 v[142:145], v[114:117], v[180:183], v[142:145]
	v_mfma_f32_16x16x32_bf16 v[138:141], v[122:125], v[180:183], v[138:141]
	v_mfma_f32_16x16x32_bf16 v[110:113], v[114:117], v[192:195], v[110:113]
	v_mfma_f32_16x16x32_bf16 v[106:109], v[122:125], v[192:195], v[106:109]
	v_mfma_f32_16x16x32_bf16 v[94:97], v[114:117], v[200:203], v[94:97]
	v_mfma_f32_16x16x32_bf16 v[90:93], v[122:125], v[200:203], v[90:93]
	v_mfma_f32_16x16x32_bf16 v[78:81], v[114:117], v[208:211], v[78:81]
	v_mfma_f32_16x16x32_bf16 v[74:77], v[122:125], v[208:211], v[74:77]
	v_mfma_f32_16x16x32_bf16 v[142:145], v[118:121], v[188:191], v[142:145]
	v_mfma_f32_16x16x32_bf16 v[138:141], v[134:137], v[188:191], v[138:141]
	v_mfma_f32_16x16x32_bf16 v[110:113], v[118:121], v[196:199], v[110:113]
	v_mfma_f32_16x16x32_bf16 v[106:109], v[134:137], v[196:199], v[106:109]
	v_mfma_f32_16x16x32_bf16 v[94:97], v[118:121], v[204:207], v[94:97]
	v_mfma_f32_16x16x32_bf16 v[90:93], v[134:137], v[204:207], v[90:93]
	v_mfma_f32_16x16x32_bf16 v[78:81], v[118:121], v[212:215], v[78:81]
	v_mfma_f32_16x16x32_bf16 v[74:77], v[134:137], v[212:215], v[74:77]
	s_setprio 0
	s_setprio 1
	v_mfma_f32_16x16x32_bf16 v[130:133], v[146:149], v[180:183], v[130:133]
	v_mfma_f32_16x16x32_bf16 v[126:129], v[166:169], v[180:183], v[126:129]
	v_mfma_f32_16x16x32_bf16 v[102:105], v[146:149], v[192:195], v[102:105]
	v_mfma_f32_16x16x32_bf16 v[98:101], v[166:169], v[192:195], v[98:101]
	v_mfma_f32_16x16x32_bf16 v[86:89], v[146:149], v[200:203], v[86:89]
	v_mfma_f32_16x16x32_bf16 v[82:85], v[166:169], v[200:203], v[82:85]
	v_mfma_f32_16x16x32_bf16 v[70:73], v[146:149], v[208:211], v[70:73]
	v_mfma_f32_16x16x32_bf16 v[66:69], v[166:169], v[208:211], v[66:69]
	v_mfma_f32_16x16x32_bf16 v[130:133], v[150:153], v[188:191], v[130:133]
	v_mfma_f32_16x16x32_bf16 v[126:129], v[170:173], v[188:191], v[126:129]
	v_mfma_f32_16x16x32_bf16 v[102:105], v[150:153], v[196:199], v[102:105]
	v_mfma_f32_16x16x32_bf16 v[98:101], v[170:173], v[196:199], v[98:101]
	v_mfma_f32_16x16x32_bf16 v[86:89], v[150:153], v[204:207], v[86:89]
	v_mfma_f32_16x16x32_bf16 v[82:85], v[170:173], v[204:207], v[82:85]
	v_mfma_f32_16x16x32_bf16 v[70:73], v[150:153], v[212:215], v[70:73]
	v_mfma_f32_16x16x32_bf16 v[66:69], v[170:173], v[212:215], v[66:69]
	s_setprio 0
	s_barrier
; #define PG8_STAGE(bufoff, gbase, voff) do { _Pragma("unroll") for (int _i = 0; _i < 2; ++_i) \
;         __builtin_amdgcn_global_load_lds((const unsigned*)((const char*)(gbase) + (voff)[_i]), (PG8_LAS unsigned*)(lds + (bufoff) + ldsw + _i * 8192), 16, 0, 0); } while (0)
; #define PG8_LDA(dst, b, h) do { _Pragma("unroll") for (int m = 0; m < 4; ++m) _Pragma("unroll") for (int k = 0; k < 2; ++k) dst[m][k] = *(const PG8_LAS bf16x8*)(lds + PG8_SA(b, h) + aoff + m * 2048 + k * 1024); } while (0)
; #define PG8_MMA(ai, bj, At, Bt) do { __builtin_amdgcn_s_setprio(1); _Pragma("unroll") for (int m = 0; m < 4; ++m) _Pragma("unroll") for (int n = 0; n < 2; ++n) _Pragma("unroll") for (int k = 0; k < 2; ++k) \
;         acc[ai][bj][m][n] = __builtin_amdgcn_mfma_f32_16x16x32_bf16(Bt[n][k], At[m][k], acc[ai][bj][m][n], 0, 0, 0); __builtin_amdgcn_s_setprio(0); } while (0)
; #define PG8_WAIT_V(n) asm volatile("s_waitcnt vmcnt(" #n ")" ::: "memory")
; #define PG8_WAIT_L(n) asm volatile("s_waitcnt lgkmcnt(" #n ")" ::: "memory")
; #define PG8_BAR __builtin_amdgcn_s_barrier()
; #define PG8_SCHED __builtin_amdgcn_sched_barrier(0)
; template <class Epi, class Sched, bool ALIGN_EPI = false, bool SP2 = false>
; __device__ __forceinline__ void gemm_phase(PG8_LAS unsigned char* lds, const Gemm g, const Sched& S, const Epi& E) {
;     ...
;             PG8_LDA(At, 1, 1); PG8_STAGE(PG8_SB(1, 0), b3, voffB); PG8_STAGE(PG8_SB(1, 1), b3 + hstep, voffB); PG8_STAGE(PG8_SA(1, 0), a3, voffA);
;             PG8_WAIT_V(8); PG8_WAIT_L(0); PG8_BAR; PG8_MMA(1, 0, At, B0); PG8_MMA(1, 1, At, B1); PG8_BAR; PG8_SCHED;
;     ...
;         if constexpr (ALIGN_EPI) { if (wr == 0) PG8_BAR; }
	s_add_i32 s22, s51, s34
	v_lshl_add_u64 v[216:217], v[216:217], 0, s[96:97]
	s_mov_b32 m0, s22
	ds_read_b128 v[180:183], v186 offset:49152
	ds_read_b128 v[188:191], v186 offset:50176
	ds_read_b128 v[192:195], v186 offset:51200
	ds_read_b128 v[196:199], v186 offset:52224
	ds_read_b128 v[200:203], v186 offset:53248
	ds_read_b128 v[204:207], v186 offset:54272
	ds_read_b128 v[208:211], v186 offset:55296
	ds_read_b128 v[212:215], v186 offset:56320
	global_load_lds_dwordx4 v[216:217], off
	s_add_i32 m0, s22, 0x2000
	s_add_u32 s22, s24, 0xb0080
	v_lshl_add_u64 v[216:217], v[218:219], 0, s[96:97]
	s_addc_u32 s23, s25, 0
	s_add_i32 s24, s52, s34
	global_load_lds_dwordx4 v[216:217], off
	v_lshl_add_u64 v[216:217], s[22:23], 0, v[158:159]
	s_mov_b32 m0, s24
	s_nop 0
	global_load_lds_dwordx4 v[216:217], off
	v_lshl_add_u64 v[216:217], s[22:23], 0, v[154:155]
	s_add_i32 m0, s24, 0x2000
	s_nop 0
	global_load_lds_dwordx4 v[216:217], off
	v_lshl_add_u64 v[216:217], v[220:221], 0, s[96:97]
	s_mov_b32 m0, s41
	s_nop 0
	global_load_lds_dwordx4 v[216:217], off
	v_lshl_add_u64 v[216:217], v[222:223], 0, s[96:97]
	s_mov_b32 m0, s42
	s_nop 0
	global_load_lds_dwordx4 v[216:217], off
	s_waitcnt vmcnt(8)
	s_waitcnt lgkmcnt(0)
	s_barrier
	s_setprio 1
	s_waitcnt lgkmcnt(0)
	v_mfma_f32_16x16x32_bf16 v[62:65], v[114:117], v[180:183], v[62:65]
	v_mfma_f32_16x16x32_bf16 v[58:61], v[122:125], v[180:183], v[58:61]
	v_mfma_f32_16x16x32_bf16 v[46:49], v[114:117], v[192:195], v[46:49]
	v_mfma_f32_16x16x32_bf16 v[42:45], v[122:125], v[192:195], v[42:45]
	v_mfma_f32_16x16x32_bf16 v[30:33], v[114:117], v[200:203], v[30:33]
	v_mfma_f32_16x16x32_bf16 v[26:29], v[122:125], v[200:203], v[26:29]
	v_mfma_f32_16x16x32_bf16 v[14:17], v[114:117], v[208:211], v[14:17]
	v_mfma_f32_16x16x32_bf16 v[10:13], v[122:125], v[208:211], v[10:13]
	v_mfma_f32_16x16x32_bf16 v[62:65], v[118:121], v[188:191], v[62:65]
	v_mfma_f32_16x16x32_bf16 v[58:61], v[134:137], v[188:191], v[58:61]
	v_mfma_f32_16x16x32_bf16 v[46:49], v[118:121], v[196:199], v[46:49]
	v_mfma_f32_16x16x32_bf16 v[42:45], v[134:137], v[196:199], v[42:45]
	v_mfma_f32_16x16x32_bf16 v[30:33], v[118:121], v[204:207], v[30:33]
	v_mfma_f32_16x16x32_bf16 v[26:29], v[134:137], v[204:207], v[26:29]
	v_mfma_f32_16x16x32_bf16 v[14:17], v[118:121], v[212:215], v[14:17]
	v_mfma_f32_16x16x32_bf16 v[10:13], v[134:137], v[212:215], v[10:13]
	s_setprio 0
	s_setprio 1
	v_mfma_f32_16x16x32_bf16 v[54:57], v[146:149], v[180:183], v[54:57]
	v_mfma_f32_16x16x32_bf16 v[50:53], v[166:169], v[180:183], v[50:53]
	v_mfma_f32_16x16x32_bf16 v[38:41], v[146:149], v[192:195], v[38:41]
	v_mfma_f32_16x16x32_bf16 v[34:37], v[166:169], v[192:195], v[34:37]
	v_mfma_f32_16x16x32_bf16 v[22:25], v[146:149], v[200:203], v[22:25]
	v_mfma_f32_16x16x32_bf16 v[18:21], v[166:169], v[200:203], v[18:21]
	v_mfma_f32_16x16x32_bf16 v[6:9], v[146:149], v[208:211], v[6:9]
	v_mfma_f32_16x16x32_bf16 v[2:5], v[166:169], v[208:211], v[2:5]
	v_mfma_f32_16x16x32_bf16 v[54:57], v[150:153], v[188:191], v[54:57]
	v_mfma_f32_16x16x32_bf16 v[50:53], v[170:173], v[188:191], v[50:53]
	v_mfma_f32_16x16x32_bf16 v[38:41], v[150:153], v[196:199], v[38:41]
	v_mfma_f32_16x16x32_bf16 v[34:37], v[170:173], v[196:199], v[34:37]
	v_mfma_f32_16x16x32_bf16 v[22:25], v[150:153], v[204:207], v[22:25]
	v_mfma_f32_16x16x32_bf16 v[18:21], v[170:173], v[204:207], v[18:21]
	v_mfma_f32_16x16x32_bf16 v[6:9], v[150:153], v[212:215], v[6:9]
	v_mfma_f32_16x16x32_bf16 v[2:5], v[170:173], v[212:215], v[2:5]
	s_setprio 0
	s_barrier
	s_add_i32 s50, s50, 2
	s_add_u32 s33, s33, 0x100
	s_addc_u32 s49, s49, 0
	s_cmp_gt_u32 s50, 41
	s_mov_b64 s[22:23], s[8:9]
	s_cbranch_scc0 .LBB0_1360
	s_and_b64 vcc, exec, s[14:15]
	s_cbranch_vccz .LBB0_1363
	s_barrier
